# weight-conversion items issue all 32 loads before draining; DeltaNet scan W/QG/state LDS fragments read ahead of the MFMAs (k-loop unrolled)
# speedup vs baseline: 1.0352x; 1.0052x over previous
; #define LAS __attribute__((address_space(3)))
; DI void cvt_item(const float* W, int ldw, int nvalid, int srccol0, bf16_t* WT, int K, int dstrow0, int k0, LAS float* scr, int lane) {
;     const int n = srccol0 + (lane & 31);
; #pragma unroll 8
;     for (int i = 0; i < 32; ++i) { const int kk = 2 * i + (lane >> 5); scr[kk * 33 + (lane & 31)] = (n < nvalid) ? __builtin_nontemporal_load(W + (size_t)(k0 + kk) * ldw + n) : 0.f; }
;     asm volatile("s_waitcnt lgkmcnt(0)" ::: "memory");
.LBB0_234:
	v_mov_b32_e32 v104, 0
	v_mov_b32_e32 v105, 0
	v_mov_b32_e32 v106, 0
	v_mov_b32_e32 v107, 0
	v_mov_b32_e32 v108, 0
	v_mov_b32_e32 v109, 0
	v_mov_b32_e32 v110, 0
	v_mov_b32_e32 v111, 0
	v_mov_b32_e32 v112, 0
	v_mov_b32_e32 v113, 0
	v_mov_b32_e32 v114, 0
	v_mov_b32_e32 v115, 0
	v_mov_b32_e32 v116, 0
	v_mov_b32_e32 v117, 0
	v_mov_b32_e32 v118, 0
	v_mov_b32_e32 v119, 0
	v_mov_b32_e32 v120, 0
	v_mov_b32_e32 v121, 0
	v_mov_b32_e32 v122, 0
	v_mov_b32_e32 v123, 0
	v_mov_b32_e32 v124, 0
	v_mov_b32_e32 v125, 0
	v_mov_b32_e32 v126, 0
	v_mov_b32_e32 v127, 0
	v_mov_b32_e32 v128, 0
	v_mov_b32_e32 v129, 0
	v_mov_b32_e32 v130, 0
	v_mov_b32_e32 v131, 0
	v_mov_b32_e32 v132, 0
	v_mov_b32_e32 v133, 0
	v_mov_b32_e32 v134, 0
	v_mov_b32_e32 v135, 0
	s_and_saveexec_b64 s[6:7], vcc
	v_lshl_add_u64 v[40:41], v[16:17], 0, s[4:5]
	global_load_dword v104, v[40:41], off nt
	v_lshl_add_u64 v[40:41], v[14:15], 0, s[4:5]
	global_load_dword v105, v[40:41], off nt
	v_lshl_add_u64 v[40:41], v[12:13], 0, s[4:5]
	global_load_dword v106, v[40:41], off nt
	v_lshl_add_u64 v[40:41], v[10:11], 0, s[4:5]
	global_load_dword v107, v[40:41], off nt
	v_lshl_add_u64 v[40:41], v[8:9], 0, s[4:5]
	global_load_dword v108, v[40:41], off nt
	v_lshl_add_u64 v[40:41], v[6:7], 0, s[4:5]
	global_load_dword v109, v[40:41], off nt
	v_lshl_add_u64 v[40:41], v[4:5], 0, s[4:5]
	global_load_dword v110, v[40:41], off nt
	v_lshl_add_u64 v[40:41], v[2:3], 0, s[4:5]
	global_load_dword v111, v[40:41], off nt
	s_add_u32 s4, s4, 0x58000
	s_addc_u32 s5, s5, 0
	v_lshl_add_u64 v[40:41], v[16:17], 0, s[4:5]
	global_load_dword v112, v[40:41], off nt
	v_lshl_add_u64 v[40:41], v[14:15], 0, s[4:5]
	global_load_dword v113, v[40:41], off nt
	v_lshl_add_u64 v[40:41], v[12:13], 0, s[4:5]
	global_load_dword v114, v[40:41], off nt
	v_lshl_add_u64 v[40:41], v[10:11], 0, s[4:5]
	global_load_dword v115, v[40:41], off nt
	v_lshl_add_u64 v[40:41], v[8:9], 0, s[4:5]
	global_load_dword v116, v[40:41], off nt
	v_lshl_add_u64 v[40:41], v[6:7], 0, s[4:5]
	global_load_dword v117, v[40:41], off nt
	v_lshl_add_u64 v[40:41], v[4:5], 0, s[4:5]
	global_load_dword v118, v[40:41], off nt
	v_lshl_add_u64 v[40:41], v[2:3], 0, s[4:5]
	global_load_dword v119, v[40:41], off nt
	s_add_u32 s4, s4, 0x58000
	s_addc_u32 s5, s5, 0
	v_lshl_add_u64 v[40:41], v[16:17], 0, s[4:5]
	global_load_dword v120, v[40:41], off nt
	v_lshl_add_u64 v[40:41], v[14:15], 0, s[4:5]
	global_load_dword v121, v[40:41], off nt
	v_lshl_add_u64 v[40:41], v[12:13], 0, s[4:5]
	global_load_dword v122, v[40:41], off nt
	v_lshl_add_u64 v[40:41], v[10:11], 0, s[4:5]
	global_load_dword v123, v[40:41], off nt
	v_lshl_add_u64 v[40:41], v[8:9], 0, s[4:5]
	global_load_dword v124, v[40:41], off nt
	v_lshl_add_u64 v[40:41], v[6:7], 0, s[4:5]
	global_load_dword v125, v[40:41], off nt
	v_lshl_add_u64 v[40:41], v[4:5], 0, s[4:5]
	global_load_dword v126, v[40:41], off nt
	v_lshl_add_u64 v[40:41], v[2:3], 0, s[4:5]
	global_load_dword v127, v[40:41], off nt
	s_add_u32 s4, s4, 0x58000
	s_addc_u32 s5, s5, 0
	v_lshl_add_u64 v[40:41], v[16:17], 0, s[4:5]
	global_load_dword v128, v[40:41], off nt
	v_lshl_add_u64 v[40:41], v[14:15], 0, s[4:5]
	global_load_dword v129, v[40:41], off nt
	v_lshl_add_u64 v[40:41], v[12:13], 0, s[4:5]
	global_load_dword v130, v[40:41], off nt
	v_lshl_add_u64 v[40:41], v[10:11], 0, s[4:5]
	global_load_dword v131, v[40:41], off nt
	v_lshl_add_u64 v[40:41], v[8:9], 0, s[4:5]
	global_load_dword v132, v[40:41], off nt
	v_lshl_add_u64 v[40:41], v[6:7], 0, s[4:5]
	global_load_dword v133, v[40:41], off nt
	v_lshl_add_u64 v[40:41], v[4:5], 0, s[4:5]
	global_load_dword v134, v[40:41], off nt
	v_lshl_add_u64 v[40:41], v[2:3], 0, s[4:5]
	global_load_dword v135, v[40:41], off nt
	s_add_u32 s4, s4, 0x58000
	s_addc_u32 s5, s5, 0
	s_or_b64 exec, exec, s[6:7]
	s_waitcnt vmcnt(31)
	ds_write_b32 v38, v104
	s_waitcnt vmcnt(30)
	ds_write_b32 v38, v105 offset:264
	s_waitcnt vmcnt(29)
	ds_write_b32 v38, v106 offset:528
	s_waitcnt vmcnt(28)
	ds_write_b32 v38, v107 offset:792
	s_waitcnt vmcnt(27)
	ds_write_b32 v38, v108 offset:1056
	s_waitcnt vmcnt(26)
	ds_write_b32 v38, v109 offset:1320
	s_waitcnt vmcnt(25)
	ds_write_b32 v38, v110 offset:1584
	s_waitcnt vmcnt(24)
	ds_write_b32 v38, v111 offset:1848
	s_waitcnt vmcnt(23)
	ds_write_b32 v38, v112 offset:2112
	s_waitcnt vmcnt(22)
	ds_write_b32 v38, v113 offset:2376
	s_waitcnt vmcnt(21)
	ds_write_b32 v38, v114 offset:2640
	s_waitcnt vmcnt(20)
	ds_write_b32 v38, v115 offset:2904
	s_waitcnt vmcnt(19)
	ds_write_b32 v38, v116 offset:3168
	s_waitcnt vmcnt(18)
	ds_write_b32 v38, v117 offset:3432
	s_waitcnt vmcnt(17)
	ds_write_b32 v38, v118 offset:3696
	s_waitcnt vmcnt(16)
	ds_write_b32 v38, v119 offset:3960
	s_waitcnt vmcnt(15)
	ds_write_b32 v38, v120 offset:4224
	s_waitcnt vmcnt(14)
	ds_write_b32 v38, v121 offset:4488
	s_waitcnt vmcnt(13)
	ds_write_b32 v38, v122 offset:4752
	s_waitcnt vmcnt(12)
	ds_write_b32 v38, v123 offset:5016
	s_waitcnt vmcnt(11)
	ds_write_b32 v38, v124 offset:5280
	s_waitcnt vmcnt(10)
	ds_write_b32 v38, v125 offset:5544
	s_waitcnt vmcnt(9)
	ds_write_b32 v38, v126 offset:5808
	s_waitcnt vmcnt(8)
	ds_write_b32 v38, v127 offset:6072
	s_waitcnt vmcnt(7)
	ds_write_b32 v38, v128 offset:6336
	s_waitcnt vmcnt(6)
	ds_write_b32 v38, v129 offset:6600
	s_waitcnt vmcnt(5)
	ds_write_b32 v38, v130 offset:6864
	s_waitcnt vmcnt(4)
	ds_write_b32 v38, v131 offset:7128
	s_waitcnt vmcnt(3)
	ds_write_b32 v38, v132 offset:7392
	s_waitcnt vmcnt(2)
	ds_write_b32 v38, v133 offset:7656
	s_waitcnt vmcnt(1)
	ds_write_b32 v38, v134 offset:7920
	s_waitcnt vmcnt(0)
	ds_write_b32 v38, v135 offset:8184
	s_branch .LBB0_231

; #define LAS __attribute__((address_space(3)))
; DI void cvt_item(const float* W, int ldw, int nvalid, int srccol0, bf16_t* WT, int K, int dstrow0, int k0, LAS float* scr, int lane) {
;     const int n = srccol0 + (lane & 31);
; #pragma unroll 8
;     for (int i = 0; i < 32; ++i) { const int kk = 2 * i + (lane >> 5); scr[kk * 33 + (lane & 31)] = (n < nvalid) ? __builtin_nontemporal_load(W + (size_t)(k0 + kk) * ldw + n) : 0.f; }
.LBB0_255:
	v_mov_b32_e32 v104, 0
	v_mov_b32_e32 v105, 0
	v_mov_b32_e32 v106, 0
	v_mov_b32_e32 v107, 0
	v_mov_b32_e32 v108, 0
	v_mov_b32_e32 v109, 0
	v_mov_b32_e32 v110, 0
	v_mov_b32_e32 v111, 0
	v_mov_b32_e32 v112, 0
	v_mov_b32_e32 v113, 0
	v_mov_b32_e32 v114, 0
	v_mov_b32_e32 v115, 0
	v_mov_b32_e32 v116, 0
	v_mov_b32_e32 v117, 0
	v_mov_b32_e32 v118, 0
	v_mov_b32_e32 v119, 0
	v_mov_b32_e32 v120, 0
	v_mov_b32_e32 v121, 0
	v_mov_b32_e32 v122, 0
	v_mov_b32_e32 v123, 0
	v_mov_b32_e32 v124, 0
	v_mov_b32_e32 v125, 0
	v_mov_b32_e32 v126, 0
	v_mov_b32_e32 v127, 0
	v_mov_b32_e32 v128, 0
	v_mov_b32_e32 v129, 0
	v_mov_b32_e32 v130, 0
	v_mov_b32_e32 v131, 0
	v_mov_b32_e32 v132, 0
	v_mov_b32_e32 v133, 0
	v_mov_b32_e32 v134, 0
	v_mov_b32_e32 v135, 0
	s_and_saveexec_b64 s[4:5], vcc
	v_add_u32_e32 v10, s1, v6
	v_ashrrev_i32_e32 v11, 31, v10
	v_lshlrev_b64 v[10:11], 12, v[10:11]
	v_lshl_add_u64 v[10:11], v[2:3], 0, v[10:11]
	global_load_dword v104, v[10:11], off nt
	v_add3_u32 v8, v6, s1, 2
	v_ashrrev_i32_e32 v9, 31, v8
	v_lshlrev_b64 v[8:9], 12, v[8:9]
	v_lshl_add_u64 v[8:9], v[2:3], 0, v[8:9]
	global_load_dword v105, v[8:9], off nt
	v_add3_u32 v10, v6, s1, 4
	v_ashrrev_i32_e32 v11, 31, v10
	v_lshlrev_b64 v[10:11], 12, v[10:11]
	v_lshl_add_u64 v[10:11], v[2:3], 0, v[10:11]
	global_load_dword v106, v[10:11], off nt
	v_add3_u32 v8, v6, s1, 6
	v_ashrrev_i32_e32 v9, 31, v8
	v_lshlrev_b64 v[8:9], 12, v[8:9]
	v_lshl_add_u64 v[8:9], v[2:3], 0, v[8:9]
	global_load_dword v107, v[8:9], off nt
	v_add3_u32 v10, v6, s1, 8
	v_ashrrev_i32_e32 v11, 31, v10
	v_lshlrev_b64 v[10:11], 12, v[10:11]
	v_lshl_add_u64 v[10:11], v[2:3], 0, v[10:11]
	global_load_dword v108, v[10:11], off nt
	v_add3_u32 v8, v6, s1, 10
	v_ashrrev_i32_e32 v9, 31, v8
	v_lshlrev_b64 v[8:9], 12, v[8:9]
	v_lshl_add_u64 v[8:9], v[2:3], 0, v[8:9]
	global_load_dword v109, v[8:9], off nt
	v_add3_u32 v10, v6, s1, 12
	v_ashrrev_i32_e32 v11, 31, v10
	v_lshlrev_b64 v[10:11], 12, v[10:11]
	v_lshl_add_u64 v[10:11], v[2:3], 0, v[10:11]
	global_load_dword v110, v[10:11], off nt
	v_add3_u32 v8, v6, s1, 14
	v_ashrrev_i32_e32 v9, 31, v8
	v_lshlrev_b64 v[8:9], 12, v[8:9]
	v_lshl_add_u64 v[8:9], v[2:3], 0, v[8:9]
	global_load_dword v111, v[8:9], off nt
	s_add_i32 s1, s1, 16
	v_add_u32_e32 v10, s1, v6
	v_ashrrev_i32_e32 v11, 31, v10
	v_lshlrev_b64 v[10:11], 12, v[10:11]
	v_lshl_add_u64 v[10:11], v[2:3], 0, v[10:11]
	global_load_dword v112, v[10:11], off nt
	v_add3_u32 v8, v6, s1, 2
	v_ashrrev_i32_e32 v9, 31, v8
	v_lshlrev_b64 v[8:9], 12, v[8:9]
	v_lshl_add_u64 v[8:9], v[2:3], 0, v[8:9]
	global_load_dword v113, v[8:9], off nt
	v_add3_u32 v10, v6, s1, 4
	v_ashrrev_i32_e32 v11, 31, v10
	v_lshlrev_b64 v[10:11], 12, v[10:11]
	v_lshl_add_u64 v[10:11], v[2:3], 0, v[10:11]
	global_load_dword v114, v[10:11], off nt
	v_add3_u32 v8, v6, s1, 6
	v_ashrrev_i32_e32 v9, 31, v8
	v_lshlrev_b64 v[8:9], 12, v[8:9]
	v_lshl_add_u64 v[8:9], v[2:3], 0, v[8:9]
	global_load_dword v115, v[8:9], off nt
	v_add3_u32 v10, v6, s1, 8
	v_ashrrev_i32_e32 v11, 31, v10
	v_lshlrev_b64 v[10:11], 12, v[10:11]
	v_lshl_add_u64 v[10:11], v[2:3], 0, v[10:11]
	global_load_dword v116, v[10:11], off nt
	v_add3_u32 v8, v6, s1, 10
	v_ashrrev_i32_e32 v9, 31, v8
	v_lshlrev_b64 v[8:9], 12, v[8:9]
	v_lshl_add_u64 v[8:9], v[2:3], 0, v[8:9]
	global_load_dword v117, v[8:9], off nt
	v_add3_u32 v10, v6, s1, 12
	v_ashrrev_i32_e32 v11, 31, v10
	v_lshlrev_b64 v[10:11], 12, v[10:11]
	v_lshl_add_u64 v[10:11], v[2:3], 0, v[10:11]
	global_load_dword v118, v[10:11], off nt
	v_add3_u32 v8, v6, s1, 14
	v_ashrrev_i32_e32 v9, 31, v8
	v_lshlrev_b64 v[8:9], 12, v[8:9]
	v_lshl_add_u64 v[8:9], v[2:3], 0, v[8:9]
	global_load_dword v119, v[8:9], off nt
	s_add_i32 s1, s1, 16
	v_add_u32_e32 v10, s1, v6
	v_ashrrev_i32_e32 v11, 31, v10
	v_lshlrev_b64 v[10:11], 12, v[10:11]
	v_lshl_add_u64 v[10:11], v[2:3], 0, v[10:11]
	global_load_dword v120, v[10:11], off nt
	v_add3_u32 v8, v6, s1, 2
	v_ashrrev_i32_e32 v9, 31, v8
	v_lshlrev_b64 v[8:9], 12, v[8:9]
	v_lshl_add_u64 v[8:9], v[2:3], 0, v[8:9]
	global_load_dword v121, v[8:9], off nt
	v_add3_u32 v10, v6, s1, 4
	v_ashrrev_i32_e32 v11, 31, v10
	v_lshlrev_b64 v[10:11], 12, v[10:11]
	v_lshl_add_u64 v[10:11], v[2:3], 0, v[10:11]
	global_load_dword v122, v[10:11], off nt
	v_add3_u32 v8, v6, s1, 6
	v_ashrrev_i32_e32 v9, 31, v8
	v_lshlrev_b64 v[8:9], 12, v[8:9]
	v_lshl_add_u64 v[8:9], v[2:3], 0, v[8:9]
	global_load_dword v123, v[8:9], off nt
	v_add3_u32 v10, v6, s1, 8
	v_ashrrev_i32_e32 v11, 31, v10
	v_lshlrev_b64 v[10:11], 12, v[10:11]
	v_lshl_add_u64 v[10:11], v[2:3], 0, v[10:11]
	global_load_dword v124, v[10:11], off nt
	v_add3_u32 v8, v6, s1, 10
	v_ashrrev_i32_e32 v9, 31, v8
	v_lshlrev_b64 v[8:9], 12, v[8:9]
	v_lshl_add_u64 v[8:9], v[2:3], 0, v[8:9]
	global_load_dword v125, v[8:9], off nt
	v_add3_u32 v10, v6, s1, 12
	v_ashrrev_i32_e32 v11, 31, v10
	v_lshlrev_b64 v[10:11], 12, v[10:11]
	v_lshl_add_u64 v[10:11], v[2:3], 0, v[10:11]
	global_load_dword v126, v[10:11], off nt
	v_add3_u32 v8, v6, s1, 14
	v_ashrrev_i32_e32 v9, 31, v8
	v_lshlrev_b64 v[8:9], 12, v[8:9]
	v_lshl_add_u64 v[8:9], v[2:3], 0, v[8:9]
	global_load_dword v127, v[8:9], off nt
	s_add_i32 s1, s1, 16
	v_add_u32_e32 v10, s1, v6
	v_ashrrev_i32_e32 v11, 31, v10
	v_lshlrev_b64 v[10:11], 12, v[10:11]
	v_lshl_add_u64 v[10:11], v[2:3], 0, v[10:11]
	global_load_dword v128, v[10:11], off nt
	v_add3_u32 v8, v6, s1, 2
	v_ashrrev_i32_e32 v9, 31, v8
	v_lshlrev_b64 v[8:9], 12, v[8:9]
	v_lshl_add_u64 v[8:9], v[2:3], 0, v[8:9]
	global_load_dword v129, v[8:9], off nt
	v_add3_u32 v10, v6, s1, 4
	v_ashrrev_i32_e32 v11, 31, v10
	v_lshlrev_b64 v[10:11], 12, v[10:11]
	v_lshl_add_u64 v[10:11], v[2:3], 0, v[10:11]
	global_load_dword v130, v[10:11], off nt
	v_add3_u32 v8, v6, s1, 6
	v_ashrrev_i32_e32 v9, 31, v8
	v_lshlrev_b64 v[8:9], 12, v[8:9]
	v_lshl_add_u64 v[8:9], v[2:3], 0, v[8:9]
	global_load_dword v131, v[8:9], off nt
	v_add3_u32 v10, v6, s1, 8
	v_ashrrev_i32_e32 v11, 31, v10
	v_lshlrev_b64 v[10:11], 12, v[10:11]
	v_lshl_add_u64 v[10:11], v[2:3], 0, v[10:11]
	global_load_dword v132, v[10:11], off nt
	v_add3_u32 v8, v6, s1, 10
	v_ashrrev_i32_e32 v9, 31, v8
	v_lshlrev_b64 v[8:9], 12, v[8:9]
	v_lshl_add_u64 v[8:9], v[2:3], 0, v[8:9]
	global_load_dword v133, v[8:9], off nt
	v_add3_u32 v10, v6, s1, 12
	v_ashrrev_i32_e32 v11, 31, v10
	v_lshlrev_b64 v[10:11], 12, v[10:11]
	v_lshl_add_u64 v[10:11], v[2:3], 0, v[10:11]
	global_load_dword v134, v[10:11], off nt
	v_add3_u32 v8, v6, s1, 14
	v_ashrrev_i32_e32 v9, 31, v8
	v_lshlrev_b64 v[8:9], 12, v[8:9]
	v_lshl_add_u64 v[8:9], v[2:3], 0, v[8:9]
	global_load_dword v135, v[8:9], off nt
	s_add_i32 s1, s1, 16
	s_or_b64 exec, exec, s[4:5]
	s_waitcnt vmcnt(31)
; DI void cvt_item(const float* W, int ldw, int nvalid, int srccol0, bf16_t* WT, int K, int dstrow0, int k0, LAS float* scr, int lane) {
;     ...
;     for (int i = 0; i < 32; ++i) { const int kk = 2 * i + (lane >> 5); scr[kk * 33 + (lane & 31)] = (n < nvalid) ? __builtin_nontemporal_load(W + (size_t)(k0 + kk) * ldw + n) : 0.f; }
;     asm volatile("s_waitcnt lgkmcnt(0)" ::: "memory");
	ds_write_b32 v7, v104
	s_waitcnt vmcnt(30)
	ds_write_b32 v7, v105 offset:264
	s_waitcnt vmcnt(29)
	ds_write_b32 v7, v106 offset:528
	s_waitcnt vmcnt(28)
	ds_write_b32 v7, v107 offset:792
	s_waitcnt vmcnt(27)
	ds_write_b32 v7, v108 offset:1056
	s_waitcnt vmcnt(26)
	ds_write_b32 v7, v109 offset:1320
	s_waitcnt vmcnt(25)
	ds_write_b32 v7, v110 offset:1584
	s_waitcnt vmcnt(24)
	ds_write_b32 v7, v111 offset:1848
	s_waitcnt vmcnt(23)
	ds_write_b32 v7, v112 offset:2112
	s_waitcnt vmcnt(22)
	ds_write_b32 v7, v113 offset:2376
	s_waitcnt vmcnt(21)
	ds_write_b32 v7, v114 offset:2640
	s_waitcnt vmcnt(20)
	ds_write_b32 v7, v115 offset:2904
	s_waitcnt vmcnt(19)
	ds_write_b32 v7, v116 offset:3168
	s_waitcnt vmcnt(18)
	ds_write_b32 v7, v117 offset:3432
	s_waitcnt vmcnt(17)
	ds_write_b32 v7, v118 offset:3696
	s_waitcnt vmcnt(16)
	ds_write_b32 v7, v119 offset:3960
	s_waitcnt vmcnt(15)
	ds_write_b32 v7, v120 offset:4224
	s_waitcnt vmcnt(14)
	ds_write_b32 v7, v121 offset:4488
	s_waitcnt vmcnt(13)
	ds_write_b32 v7, v122 offset:4752
	s_waitcnt vmcnt(12)
	ds_write_b32 v7, v123 offset:5016
	s_waitcnt vmcnt(11)
	ds_write_b32 v7, v124 offset:5280
	s_waitcnt vmcnt(10)
	ds_write_b32 v7, v125 offset:5544
	s_waitcnt vmcnt(9)
	ds_write_b32 v7, v126 offset:5808
	s_waitcnt vmcnt(8)
	ds_write_b32 v7, v127 offset:6072
	s_waitcnt vmcnt(7)
	ds_write_b32 v7, v128 offset:6336
	s_waitcnt vmcnt(6)
	ds_write_b32 v7, v129 offset:6600
	s_waitcnt vmcnt(5)
	ds_write_b32 v7, v130 offset:6864
	s_waitcnt vmcnt(4)
	ds_write_b32 v7, v131 offset:7128
	s_waitcnt vmcnt(3)
	ds_write_b32 v7, v132 offset:7392
	s_waitcnt vmcnt(2)
	ds_write_b32 v7, v133 offset:7656
	s_waitcnt vmcnt(1)
	ds_write_b32 v7, v134 offset:7920
	s_waitcnt vmcnt(0)
	ds_write_b32 v7, v135 offset:8184
	s_branch .LBB0_252

; #define LAS __attribute__((address_space(3)))
; DI void cvt_item(const float* W, int ldw, int nvalid, int srccol0, bf16_t* WT, int K, int dstrow0, int k0, LAS float* scr, int lane) {
;     const int n = srccol0 + (lane & 31);
; #pragma unroll 8
;     for (int i = 0; i < 32; ++i) { const int kk = 2 * i + (lane >> 5); scr[kk * 33 + (lane & 31)] = (n < nvalid) ? __builtin_nontemporal_load(W + (size_t)(k0 + kk) * ldw + n) : 0.f; }
;     asm volatile("s_waitcnt lgkmcnt(0)" ::: "memory");
.LBB0_276:
	v_mov_b32_e32 v104, 0
	v_mov_b32_e32 v105, 0
	v_mov_b32_e32 v106, 0
	v_mov_b32_e32 v107, 0
	v_mov_b32_e32 v108, 0
	v_mov_b32_e32 v109, 0
	v_mov_b32_e32 v110, 0
	v_mov_b32_e32 v111, 0
	v_mov_b32_e32 v112, 0
	v_mov_b32_e32 v113, 0
	v_mov_b32_e32 v114, 0
	v_mov_b32_e32 v115, 0
	v_mov_b32_e32 v116, 0
	v_mov_b32_e32 v117, 0
	v_mov_b32_e32 v118, 0
	v_mov_b32_e32 v119, 0
	v_mov_b32_e32 v120, 0
	v_mov_b32_e32 v121, 0
	v_mov_b32_e32 v122, 0
	v_mov_b32_e32 v123, 0
	v_mov_b32_e32 v124, 0
	v_mov_b32_e32 v125, 0
	v_mov_b32_e32 v126, 0
	v_mov_b32_e32 v127, 0
	v_mov_b32_e32 v128, 0
	v_mov_b32_e32 v129, 0
	v_mov_b32_e32 v130, 0
	v_mov_b32_e32 v131, 0
	v_mov_b32_e32 v132, 0
	v_mov_b32_e32 v133, 0
	v_mov_b32_e32 v134, 0
	v_mov_b32_e32 v135, 0
	s_and_saveexec_b64 s[6:7], vcc
	v_lshl_add_u64 v[40:41], v[16:17], 0, s[4:5]
	global_load_dword v104, v[40:41], off nt
	v_lshl_add_u64 v[40:41], v[14:15], 0, s[4:5]
	global_load_dword v105, v[40:41], off nt
	v_lshl_add_u64 v[40:41], v[12:13], 0, s[4:5]
	global_load_dword v106, v[40:41], off nt
	v_lshl_add_u64 v[40:41], v[10:11], 0, s[4:5]
	global_load_dword v107, v[40:41], off nt
	v_lshl_add_u64 v[40:41], v[8:9], 0, s[4:5]
	global_load_dword v108, v[40:41], off nt
	v_lshl_add_u64 v[40:41], v[6:7], 0, s[4:5]
	global_load_dword v109, v[40:41], off nt
	v_lshl_add_u64 v[40:41], v[4:5], 0, s[4:5]
	global_load_dword v110, v[40:41], off nt
	v_lshl_add_u64 v[40:41], v[2:3], 0, s[4:5]
	global_load_dword v111, v[40:41], off nt
	s_add_u32 s4, s4, 0x40400
	s_addc_u32 s5, s5, 0
	v_lshl_add_u64 v[40:41], v[16:17], 0, s[4:5]
	global_load_dword v112, v[40:41], off nt
	v_lshl_add_u64 v[40:41], v[14:15], 0, s[4:5]
	global_load_dword v113, v[40:41], off nt
	v_lshl_add_u64 v[40:41], v[12:13], 0, s[4:5]
	global_load_dword v114, v[40:41], off nt
	v_lshl_add_u64 v[40:41], v[10:11], 0, s[4:5]
	global_load_dword v115, v[40:41], off nt
	v_lshl_add_u64 v[40:41], v[8:9], 0, s[4:5]
	global_load_dword v116, v[40:41], off nt
	v_lshl_add_u64 v[40:41], v[6:7], 0, s[4:5]
	global_load_dword v117, v[40:41], off nt
	v_lshl_add_u64 v[40:41], v[4:5], 0, s[4:5]
	global_load_dword v118, v[40:41], off nt
	v_lshl_add_u64 v[40:41], v[2:3], 0, s[4:5]
	global_load_dword v119, v[40:41], off nt
	s_add_u32 s4, s4, 0x40400
	s_addc_u32 s5, s5, 0
	v_lshl_add_u64 v[40:41], v[16:17], 0, s[4:5]
	global_load_dword v120, v[40:41], off nt
	v_lshl_add_u64 v[40:41], v[14:15], 0, s[4:5]
	global_load_dword v121, v[40:41], off nt
	v_lshl_add_u64 v[40:41], v[12:13], 0, s[4:5]
	global_load_dword v122, v[40:41], off nt
	v_lshl_add_u64 v[40:41], v[10:11], 0, s[4:5]
	global_load_dword v123, v[40:41], off nt
	v_lshl_add_u64 v[40:41], v[8:9], 0, s[4:5]
	global_load_dword v124, v[40:41], off nt
	v_lshl_add_u64 v[40:41], v[6:7], 0, s[4:5]
	global_load_dword v125, v[40:41], off nt
	v_lshl_add_u64 v[40:41], v[4:5], 0, s[4:5]
	global_load_dword v126, v[40:41], off nt
	v_lshl_add_u64 v[40:41], v[2:3], 0, s[4:5]
	global_load_dword v127, v[40:41], off nt
	s_add_u32 s4, s4, 0x40400
	s_addc_u32 s5, s5, 0
	v_lshl_add_u64 v[40:41], v[16:17], 0, s[4:5]
	global_load_dword v128, v[40:41], off nt
	v_lshl_add_u64 v[40:41], v[14:15], 0, s[4:5]
	global_load_dword v129, v[40:41], off nt
	v_lshl_add_u64 v[40:41], v[12:13], 0, s[4:5]
	global_load_dword v130, v[40:41], off nt
	v_lshl_add_u64 v[40:41], v[10:11], 0, s[4:5]
	global_load_dword v131, v[40:41], off nt
	v_lshl_add_u64 v[40:41], v[8:9], 0, s[4:5]
	global_load_dword v132, v[40:41], off nt
	v_lshl_add_u64 v[40:41], v[6:7], 0, s[4:5]
	global_load_dword v133, v[40:41], off nt
	v_lshl_add_u64 v[40:41], v[4:5], 0, s[4:5]
	global_load_dword v134, v[40:41], off nt
	v_lshl_add_u64 v[40:41], v[2:3], 0, s[4:5]
	global_load_dword v135, v[40:41], off nt
	s_add_u32 s4, s4, 0x40400
	s_addc_u32 s5, s5, 0
	s_or_b64 exec, exec, s[6:7]
	s_waitcnt vmcnt(31)
	ds_write_b32 v38, v104
	s_waitcnt vmcnt(30)
	ds_write_b32 v38, v105 offset:264
	s_waitcnt vmcnt(29)
	ds_write_b32 v38, v106 offset:528
	s_waitcnt vmcnt(28)
	ds_write_b32 v38, v107 offset:792
	s_waitcnt vmcnt(27)
	ds_write_b32 v38, v108 offset:1056
	s_waitcnt vmcnt(26)
	ds_write_b32 v38, v109 offset:1320
	s_waitcnt vmcnt(25)
	ds_write_b32 v38, v110 offset:1584
	s_waitcnt vmcnt(24)
	ds_write_b32 v38, v111 offset:1848
	s_waitcnt vmcnt(23)
	ds_write_b32 v38, v112 offset:2112
	s_waitcnt vmcnt(22)
	ds_write_b32 v38, v113 offset:2376
	s_waitcnt vmcnt(21)
	ds_write_b32 v38, v114 offset:2640
	s_waitcnt vmcnt(20)
	ds_write_b32 v38, v115 offset:2904
	s_waitcnt vmcnt(19)
	ds_write_b32 v38, v116 offset:3168
	s_waitcnt vmcnt(18)
	ds_write_b32 v38, v117 offset:3432
	s_waitcnt vmcnt(17)
	ds_write_b32 v38, v118 offset:3696
	s_waitcnt vmcnt(16)
	ds_write_b32 v38, v119 offset:3960
	s_waitcnt vmcnt(15)
	ds_write_b32 v38, v120 offset:4224
	s_waitcnt vmcnt(14)
	ds_write_b32 v38, v121 offset:4488
	s_waitcnt vmcnt(13)
	ds_write_b32 v38, v122 offset:4752
	s_waitcnt vmcnt(12)
	ds_write_b32 v38, v123 offset:5016
	s_waitcnt vmcnt(11)
	ds_write_b32 v38, v124 offset:5280
	s_waitcnt vmcnt(10)
	ds_write_b32 v38, v125 offset:5544
	s_waitcnt vmcnt(9)
	ds_write_b32 v38, v126 offset:5808
	s_waitcnt vmcnt(8)
	ds_write_b32 v38, v127 offset:6072
	s_waitcnt vmcnt(7)
	ds_write_b32 v38, v128 offset:6336
	s_waitcnt vmcnt(6)
	ds_write_b32 v38, v129 offset:6600
	s_waitcnt vmcnt(5)
	ds_write_b32 v38, v130 offset:6864
	s_waitcnt vmcnt(4)
	ds_write_b32 v38, v131 offset:7128
	s_waitcnt vmcnt(3)
	ds_write_b32 v38, v132 offset:7392
	s_waitcnt vmcnt(2)
	ds_write_b32 v38, v133 offset:7656
	s_waitcnt vmcnt(1)
	ds_write_b32 v38, v134 offset:7920
	s_waitcnt vmcnt(0)
	ds_write_b32 v38, v135 offset:8184
	s_branch .LBB0_273

; #define LAS __attribute__((address_space(3)))
; DI unsigned pk2(float lo, float hi) { f32x2 v = {lo, hi}; bf16x2_t b = __builtin_convertvector(v, bf16x2_t); return __builtin_bit_cast(unsigned, b); }
; DI float bf2f(bf16_t b) { return __uint_as_float(((unsigned)b) << 16); }
; DI int crow(int r, int hi) { return (r & 3) + 8 * (r >> 2) + 4 * hi; }
; #define MFMA32(a, b, c) __builtin_amdgcn_mfma_f32_32x32x16_bf16((a), (b), (c), 0, 0, 0)
; DI void dn_scan(const Params& p, LAS unsigned char* L, int tid, int wave, int lane, int bid, int G) {
;     ...
; #pragma unroll
;         for (int e = 0; e < 16; ++e) { vacc[e] = bf2f(*(const LAS bf16_t*)(L + SC_U + (ib * 32 + crow(e, hi)) * 272 + (db * 32 + n31) * 2)); oacc[e] = 0.f; }
; #pragma unroll 2
;         for (int ks = 0; ks < 8; ++ks) {
;             const bf16x8 bs = *(const LAS bf16x8*)(L + SC_ST + (db * 32 + n31) * 272 + ks * 32 + hi * 16);
;             const bf16x8 aw = *(const LAS bf16x8*)(L + SC_W + (ib * 32 + n31) * 272 + ks * 32 + hi * 16);
;             const bf16x8 aq = *(const LAS bf16x8*)(L + SC_QG + (ib * 32 + n31) * 272 + ks * 32 + hi * 16);
;             vacc = MFMA32(aw, bs, vacc); oacc = MFMA32(aq, bs, oacc);
;         }
; #pragma unroll
;         for (int g = 0; g < 4; ++g) { u32x2 w2; w2.x = pk2(vacc[4 * g], vacc[4 * g + 1]); w2.y = pk2(vacc[4 * g + 2], vacc[4 * g + 3]);
;             *(LAS u32x2*)(L + SC_VNT + (db * 32 + n31) * 144 + (ib * 32 + 8 * g + 4 * hi) * 2) = w2; }
.LBB0_645:
	v_add_u32_e32 v218, 0x13800, v133
	ds_read_b128 v[138:141], v218
	ds_read_b128 v[142:145], v132 offset:17408
	ds_read_b128 v[146:149], v132
	ds_read_b128 v[150:153], v218 offset:32
	ds_read_b128 v[154:157], v132 offset:17440
	ds_read_b128 v[158:161], v132 offset:32
	ds_read_b128 v[162:165], v218 offset:64
	ds_read_b128 v[166:169], v132 offset:17472
	ds_read_b128 v[170:173], v132 offset:64
	ds_read_b128 v[174:177], v218 offset:96
	ds_read_b128 v[178:181], v132 offset:17504
	ds_read_b128 v[182:185], v132 offset:96
	s_waitcnt lgkmcnt(9)
	v_mfma_f32_32x32x16_bf16 v[32:47], v[142:145], v[138:141], v[32:47]
	v_mfma_f32_32x32x16_bf16 v[48:63], v[146:149], v[138:141], v[48:63]
	ds_read_b128 v[138:141], v218 offset:128
	ds_read_b128 v[142:145], v132 offset:17536
	ds_read_b128 v[146:149], v132 offset:128
	s_waitcnt lgkmcnt(9)
	v_mfma_f32_32x32x16_bf16 v[32:47], v[154:157], v[150:153], v[32:47]
	v_mfma_f32_32x32x16_bf16 v[48:63], v[158:161], v[150:153], v[48:63]
	ds_read_b128 v[150:153], v218 offset:160
	ds_read_b128 v[154:157], v132 offset:17568
	ds_read_b128 v[158:161], v132 offset:160
	s_waitcnt lgkmcnt(9)
	v_mfma_f32_32x32x16_bf16 v[32:47], v[166:169], v[162:165], v[32:47]
	v_mfma_f32_32x32x16_bf16 v[48:63], v[170:173], v[162:165], v[48:63]
	ds_read_b128 v[162:165], v218 offset:192
	ds_read_b128 v[166:169], v132 offset:17600
	ds_read_b128 v[170:173], v132 offset:192
	s_waitcnt lgkmcnt(9)
	v_mfma_f32_32x32x16_bf16 v[32:47], v[178:181], v[174:177], v[32:47]
	v_mfma_f32_32x32x16_bf16 v[48:63], v[182:185], v[174:177], v[48:63]
	ds_read_b128 v[174:177], v218 offset:224
	ds_read_b128 v[178:181], v132 offset:17632
	ds_read_b128 v[182:185], v132 offset:224
	s_waitcnt lgkmcnt(9)
	v_mfma_f32_32x32x16_bf16 v[32:47], v[142:145], v[138:141], v[32:47]
	v_mfma_f32_32x32x16_bf16 v[48:63], v[146:149], v[138:141], v[48:63]
	s_waitcnt lgkmcnt(6)
	v_mfma_f32_32x32x16_bf16 v[32:47], v[154:157], v[150:153], v[32:47]
	v_mfma_f32_32x32x16_bf16 v[48:63], v[158:161], v[150:153], v[48:63]
	s_waitcnt lgkmcnt(3)
	v_mfma_f32_32x32x16_bf16 v[32:47], v[166:169], v[162:165], v[32:47]
	v_mfma_f32_32x32x16_bf16 v[48:63], v[170:173], v[162:165], v[48:63]
	s_waitcnt lgkmcnt(0)
	v_mfma_f32_32x32x16_bf16 v[32:47], v[178:181], v[174:177], v[32:47]
	v_mfma_f32_32x32x16_bf16 v[48:63], v[182:185], v[174:177], v[48:63]
	s_nop 1
	s_nop 10
	v_cvt_pk_bf16_f32 v48, v48, v49
	v_cvt_pk_bf16_f32 v49, v50, v51
	v_cvt_pk_bf16_f32 v50, v52, v53
	v_cvt_pk_bf16_f32 v51, v54, v55
	ds_write2_b64 v134, v[48:49], v[50:51] offset1:2
	v_cvt_pk_bf16_f32 v48, v56, v57
	v_cvt_pk_bf16_f32 v49, v58, v59
	v_cvt_pk_bf16_f32 v50, v60, v61
	v_cvt_pk_bf16_f32 v51, v62, v63
	ds_write2_b64 v134, v[48:49], v[50:51] offset0:4 offset1:6
	s_waitcnt lgkmcnt(0)
	s_barrier
; #define LAS __attribute__((address_space(3)))
; #define MFMA32(a, b, c) __builtin_amdgcn_mfma_f32_32x32x16_bf16((a), (b), (c), 0, 0, 0)
; DI void lds_barrier() { asm volatile("s_waitcnt lgkmcnt(0)" ::: "memory"); __builtin_amdgcn_s_barrier(); asm volatile("" ::: "memory"); }
; #define SC_WRITE_ST() do { _Pragma("unroll") for (int k2 = 0; k2 < 2; ++k2) { const int kb = ib * 2 + k2; _Pragma("unroll") for (int g = 0; g < 4; ++g) { u32x2 w2; w2.x = pk2(sacc[k2][4 * g], sacc[k2][4 * g + 1]); w2.y = pk2(sacc[k2][4 * g + 2], sacc[k2][4 * g + 3]); \
;         *(LAS u32x2*)(L + SC_ST + (db * 32 + n31) * 272 + (kb * 32 + 8 * g + 4 * hi) * 2) = w2; } } } while (0)
; DI void dn_scan(const Params& p, LAS unsigned char* L, int tid, int wave, int lane, int bid, int G) {
;     ...
; #pragma unroll
;         for (int ks = 0; ks < 4; ++ks) {
;             const bf16x8 bv = *(const LAS bf16x8*)(L + SC_VNT + (db * 32 + n31) * 144 + ks * 32 + hi * 16);
;             const bf16x8 aa = *(const LAS bf16x8*)(L + SC_AT + (ib * 32 + n31) * 144 + ks * 32 + hi * 16);
;             oacc = MFMA32(aa, bv, oacc);
;         }
; #pragma unroll
;         for (int k2 = 0; k2 < 2; ++k2) { const int kb = ib * 2 + k2;
; #pragma unroll
;             for (int e = 0; e < 16; ++e) sacc[k2][e] *= glast;
; #pragma unroll
;             for (int ks = 0; ks < 4; ++ks) {
;                 const bf16x8 bv = *(const LAS bf16x8*)(L + SC_VNT + (db * 32 + n31) * 144 + ks * 32 + hi * 16);
;                 const bf16x8 ak = *(const LAS bf16x8*)(L + SC_KGT + (kb * 32 + n31) * 144 + ks * 32 + hi * 16);
;                 sacc[k2] = MFMA32(ak, bv, sacc[k2]);
;             } }
;         lds_barrier();
;         SC_WRITE_ST();
;         if (c + 1 < nsteps) SC_STORE();
	v_add_u32_e32 v138, v130, v129
	ds_read_b128 v[48:51], v138
	ds_read_b128 v[52:55], v138 offset:32
	ds_read_b128 v[56:59], v136 offset:44032
	ds_read_b128 v[60:63], v136 offset:44064
	v_pk_mul_f32 v[0:1], v[118:119], v[0:1] op_sel_hi:[0,1]
	v_pk_mul_f32 v[2:3], v[118:119], v[2:3] op_sel_hi:[0,1]
	v_pk_mul_f32 v[4:5], v[118:119], v[4:5] op_sel_hi:[0,1]
	v_pk_mul_f32 v[6:7], v[118:119], v[6:7] op_sel_hi:[0,1]
	v_pk_mul_f32 v[8:9], v[118:119], v[8:9] op_sel_hi:[0,1]
	v_pk_mul_f32 v[10:11], v[118:119], v[10:11] op_sel_hi:[0,1]
	v_pk_mul_f32 v[12:13], v[118:119], v[12:13] op_sel_hi:[0,1]
	v_pk_mul_f32 v[14:15], v[118:119], v[14:15] op_sel_hi:[0,1]
	v_pk_mul_f32 v[16:17], v[118:119], v[16:17] op_sel_hi:[0,1]
	v_pk_mul_f32 v[18:19], v[118:119], v[18:19] op_sel_hi:[0,1]
	s_waitcnt lgkmcnt(0)
	v_mfma_f32_32x32x16_bf16 v[0:15], v[56:59], v[48:51], v[0:15]
	v_mul_f32_e64 v20, v118, v20
	v_mul_f32_e64 v21, v118, v21
	v_mul_f32_e64 v22, v118, v22
	v_mul_f32_e64 v23, v118, v23
	v_mul_f32_e64 v24, v118, v24
	v_mul_f32_e64 v25, v118, v25
	v_pk_mul_f32 v[26:27], v[118:119], v[26:27] op_sel_hi:[0,1]
	v_pk_mul_f32 v[28:29], v[118:119], v[28:29] op_sel_hi:[0,1]
	v_pk_mul_f32 v[30:31], v[118:119], v[30:31] op_sel_hi:[0,1]
	s_and_b64 vcc, exec, s[4:5]
	v_mfma_f32_32x32x16_bf16 v[0:15], v[60:63], v[52:55], v[0:15]
	ds_read_b128 v[56:59], v136 offset:44096
	ds_read_b128 v[60:63], v138 offset:64
	ds_read_b128 v[138:141], v138 offset:96
	ds_read_b128 v[142:145], v136 offset:44128
	s_waitcnt lgkmcnt(0)
	v_mfma_f32_32x32x16_bf16 v[0:15], v[56:59], v[60:63], v[0:15]
	ds_read_b128 v[56:59], v136 offset:48640
	v_mfma_f32_32x32x16_bf16 v[0:15], v[142:145], v[138:141], v[0:15]
	ds_read_b128 v[142:145], v136 offset:48672
	s_waitcnt lgkmcnt(0)
	v_mfma_f32_32x32x16_bf16 v[16:31], v[56:59], v[48:51], v[16:31]
	v_mfma_f32_32x32x16_bf16 v[16:31], v[142:145], v[52:55], v[16:31]
	ds_read_b128 v[56:59], v136 offset:48704
	ds_read_b128 v[142:145], v136 offset:48736
	s_waitcnt lgkmcnt(0)
	v_mfma_f32_32x32x16_bf16 v[16:31], v[56:59], v[60:63], v[16:31]
	v_mfma_f32_32x32x16_bf16 v[16:31], v[142:145], v[138:141], v[16:31]
	ds_read_b128 v[56:59], v135 offset:34816
	ds_read_b128 v[142:145], v135 offset:34848
	ds_read_b128 v[146:149], v135 offset:34880
	ds_read_b128 v[150:153], v135 offset:34912
	s_waitcnt lgkmcnt(0)
	s_barrier
	s_waitcnt lgkmcnt(0)
	v_mfma_f32_32x32x16_bf16 v[32:47], v[56:59], v[48:51], v[32:47]
	v_cvt_pk_bf16_f32 v48, v0, v1
	v_cvt_pk_bf16_f32 v49, v2, v3
	v_cvt_pk_bf16_f32 v50, v4, v5
	v_cvt_pk_bf16_f32 v51, v6, v7
	ds_write2_b64 v127, v[48:49], v[50:51] offset1:2
	v_cvt_pk_bf16_f32 v48, v8, v9
	v_cvt_pk_bf16_f32 v49, v10, v11
	v_mfma_f32_32x32x16_bf16 v[32:47], v[142:145], v[52:55], v[32:47]
	v_cvt_pk_bf16_f32 v50, v12, v13
	v_cvt_pk_bf16_f32 v51, v14, v15
	ds_write2_b64 v127, v[48:49], v[50:51] offset0:4 offset1:6
	v_cvt_pk_bf16_f32 v48, v16, v17
	v_cvt_pk_bf16_f32 v49, v18, v19
	v_cvt_pk_bf16_f32 v50, v20, v21
	v_cvt_pk_bf16_f32 v51, v22, v23
	v_mfma_f32_32x32x16_bf16 v[32:47], v[146:149], v[60:63], v[32:47]
	ds_write2_b64 v127, v[48:49], v[50:51] offset0:8 offset1:10
	v_cvt_pk_bf16_f32 v48, v24, v25
	v_cvt_pk_bf16_f32 v49, v26, v27
	v_cvt_pk_bf16_f32 v50, v28, v29
	v_cvt_pk_bf16_f32 v51, v30, v31
	ds_write2_b64 v127, v[48:49], v[50:51] offset0:12 offset1:14
	v_mfma_f32_32x32x16_bf16 v[32:47], v[150:153], v[138:141], v[32:47]
	s_cbranch_vccz .LBB0_641
	s_waitcnt vmcnt(0)
	ds_write_b128 v121, v[66:69]
	ds_write_b128 v121, v[70:73] offset:17408
	ds_write_b128 v121, v[74:77] offset:62464
	ds_write_b16 v122, v78 offset:44032
	ds_write_b16_d16_hi v122, v78 offset:44176
	ds_write_b16 v122, v79 offset:44320
	ds_write_b16_d16_hi v122, v79 offset:44464
	ds_write_b16 v122, v80 offset:44608
	ds_write_b16_d16_hi v122, v80 offset:44752
	ds_write_b16 v122, v81 offset:44896
	ds_write_b16_d16_hi v122, v81 offset:45040
	ds_write_b128 v123, v[82:85]
	ds_write_b128 v123, v[86:89] offset:17408
	ds_write_b128 v123, v[90:93] offset:62464
	ds_write_b16 v124, v94 offset:44032
	ds_write_b16_d16_hi v124, v94 offset:44176
	ds_write_b16 v124, v95 offset:44320
	ds_write_b16_d16_hi v124, v95 offset:44464
	ds_write_b16 v124, v96 offset:44608
	ds_write_b16_d16_hi v124, v96 offset:44752
	ds_write_b16 v124, v97 offset:44896
	ds_write_b16_d16_hi v124, v97 offset:45040
	ds_write_b128 v126, v[98:101] offset:34816
	s_branch .LBB0_641

; #define LAS __attribute__((address_space(3)))
; DI void cvt_item(const float* W, int ldw, int nvalid, int srccol0, bf16_t* WT, int K, int dstrow0, int k0, LAS float* scr, int lane) {
;     const int n = srccol0 + (lane & 31);
; #pragma unroll 8
;     for (int i = 0; i < 32; ++i) { const int kk = 2 * i + (lane >> 5); scr[kk * 33 + (lane & 31)] = (n < nvalid) ? __builtin_nontemporal_load(W + (size_t)(k0 + kk) * ldw + n) : 0.f; }
;     asm volatile("s_waitcnt lgkmcnt(0)" ::: "memory");
.LBB0_656:
	v_mov_b32_e32 v104, 0
	v_mov_b32_e32 v105, 0
	v_mov_b32_e32 v106, 0
	v_mov_b32_e32 v107, 0
	v_mov_b32_e32 v108, 0
	v_mov_b32_e32 v109, 0
	v_mov_b32_e32 v110, 0
	v_mov_b32_e32 v111, 0
	v_mov_b32_e32 v112, 0
	v_mov_b32_e32 v113, 0
	v_mov_b32_e32 v114, 0
	v_mov_b32_e32 v115, 0
	v_mov_b32_e32 v116, 0
	v_mov_b32_e32 v117, 0
	v_mov_b32_e32 v118, 0
	v_mov_b32_e32 v119, 0
	v_mov_b32_e32 v120, 0
	v_mov_b32_e32 v121, 0
	v_mov_b32_e32 v122, 0
	v_mov_b32_e32 v123, 0
	v_mov_b32_e32 v124, 0
	v_mov_b32_e32 v125, 0
	v_mov_b32_e32 v126, 0
	v_mov_b32_e32 v127, 0
	v_mov_b32_e32 v128, 0
	v_mov_b32_e32 v129, 0
	v_mov_b32_e32 v130, 0
	v_mov_b32_e32 v131, 0
	v_mov_b32_e32 v132, 0
	v_mov_b32_e32 v133, 0
	v_mov_b32_e32 v134, 0
	v_mov_b32_e32 v135, 0
	s_and_saveexec_b64 s[10:11], vcc
	v_lshl_add_u64 v[40:41], v[18:19], 0, s[6:7]
	global_load_dword v104, v[40:41], off nt
	v_lshl_add_u64 v[38:39], v[16:17], 0, s[6:7]
	global_load_dword v105, v[38:39], off nt
	v_lshl_add_u64 v[40:41], v[14:15], 0, s[6:7]
	global_load_dword v106, v[40:41], off nt
	v_lshl_add_u64 v[38:39], v[12:13], 0, s[6:7]
	global_load_dword v107, v[38:39], off nt
	v_lshl_add_u64 v[40:41], v[10:11], 0, s[6:7]
	global_load_dword v108, v[40:41], off nt
	v_lshl_add_u64 v[38:39], v[8:9], 0, s[6:7]
	global_load_dword v109, v[38:39], off nt
	v_lshl_add_u64 v[40:41], v[6:7], 0, s[6:7]
	global_load_dword v110, v[40:41], off nt
	v_lshl_add_u64 v[38:39], v[4:5], 0, s[6:7]
	global_load_dword v111, v[38:39], off nt
	s_add_u32 s6, s6, 0x58000
	s_addc_u32 s7, s7, 0
	v_lshl_add_u64 v[40:41], v[18:19], 0, s[6:7]
	global_load_dword v112, v[40:41], off nt
	v_lshl_add_u64 v[38:39], v[16:17], 0, s[6:7]
	global_load_dword v113, v[38:39], off nt
	v_lshl_add_u64 v[40:41], v[14:15], 0, s[6:7]
	global_load_dword v114, v[40:41], off nt
	v_lshl_add_u64 v[38:39], v[12:13], 0, s[6:7]
	global_load_dword v115, v[38:39], off nt
	v_lshl_add_u64 v[40:41], v[10:11], 0, s[6:7]
	global_load_dword v116, v[40:41], off nt
	v_lshl_add_u64 v[38:39], v[8:9], 0, s[6:7]
	global_load_dword v117, v[38:39], off nt
	v_lshl_add_u64 v[40:41], v[6:7], 0, s[6:7]
	global_load_dword v118, v[40:41], off nt
	v_lshl_add_u64 v[38:39], v[4:5], 0, s[6:7]
	global_load_dword v119, v[38:39], off nt
	s_add_u32 s6, s6, 0x58000
	s_addc_u32 s7, s7, 0
	v_lshl_add_u64 v[40:41], v[18:19], 0, s[6:7]
	global_load_dword v120, v[40:41], off nt
	v_lshl_add_u64 v[38:39], v[16:17], 0, s[6:7]
	global_load_dword v121, v[38:39], off nt
	v_lshl_add_u64 v[40:41], v[14:15], 0, s[6:7]
	global_load_dword v122, v[40:41], off nt
	v_lshl_add_u64 v[38:39], v[12:13], 0, s[6:7]
	global_load_dword v123, v[38:39], off nt
	v_lshl_add_u64 v[40:41], v[10:11], 0, s[6:7]
	global_load_dword v124, v[40:41], off nt
	v_lshl_add_u64 v[38:39], v[8:9], 0, s[6:7]
	global_load_dword v125, v[38:39], off nt
	v_lshl_add_u64 v[40:41], v[6:7], 0, s[6:7]
	global_load_dword v126, v[40:41], off nt
	v_lshl_add_u64 v[38:39], v[4:5], 0, s[6:7]
	global_load_dword v127, v[38:39], off nt
	s_add_u32 s6, s6, 0x58000
	s_addc_u32 s7, s7, 0
	v_lshl_add_u64 v[40:41], v[18:19], 0, s[6:7]
	global_load_dword v128, v[40:41], off nt
	v_lshl_add_u64 v[38:39], v[16:17], 0, s[6:7]
	global_load_dword v129, v[38:39], off nt
	v_lshl_add_u64 v[40:41], v[14:15], 0, s[6:7]
	global_load_dword v130, v[40:41], off nt
	v_lshl_add_u64 v[38:39], v[12:13], 0, s[6:7]
	global_load_dword v131, v[38:39], off nt
	v_lshl_add_u64 v[40:41], v[10:11], 0, s[6:7]
	global_load_dword v132, v[40:41], off nt
	v_lshl_add_u64 v[38:39], v[8:9], 0, s[6:7]
	global_load_dword v133, v[38:39], off nt
	v_lshl_add_u64 v[40:41], v[6:7], 0, s[6:7]
	global_load_dword v134, v[40:41], off nt
	v_lshl_add_u64 v[38:39], v[4:5], 0, s[6:7]
	global_load_dword v135, v[38:39], off nt
	s_add_u32 s6, s6, 0x58000
	s_addc_u32 s7, s7, 0
	s_or_b64 exec, exec, s[10:11]
	s_waitcnt vmcnt(31)
	ds_write_b32 v37, v104
	s_waitcnt vmcnt(30)
	ds_write_b32 v37, v105 offset:264
	s_waitcnt vmcnt(29)
	ds_write_b32 v37, v106 offset:528
	s_waitcnt vmcnt(28)
	ds_write_b32 v37, v107 offset:792
	s_waitcnt vmcnt(27)
	ds_write_b32 v37, v108 offset:1056
	s_waitcnt vmcnt(26)
	ds_write_b32 v37, v109 offset:1320
	s_waitcnt vmcnt(25)
	ds_write_b32 v37, v110 offset:1584
	s_waitcnt vmcnt(24)
	ds_write_b32 v37, v111 offset:1848
	s_waitcnt vmcnt(23)
	ds_write_b32 v37, v112 offset:2112
	s_waitcnt vmcnt(22)
	ds_write_b32 v37, v113 offset:2376
	s_waitcnt vmcnt(21)
	ds_write_b32 v37, v114 offset:2640
	s_waitcnt vmcnt(20)
	ds_write_b32 v37, v115 offset:2904
	s_waitcnt vmcnt(19)
	ds_write_b32 v37, v116 offset:3168
	s_waitcnt vmcnt(18)
	ds_write_b32 v37, v117 offset:3432
	s_waitcnt vmcnt(17)
	ds_write_b32 v37, v118 offset:3696
	s_waitcnt vmcnt(16)
	ds_write_b32 v37, v119 offset:3960
	s_waitcnt vmcnt(15)
	ds_write_b32 v37, v120 offset:4224
	s_waitcnt vmcnt(14)
	ds_write_b32 v37, v121 offset:4488
	s_waitcnt vmcnt(13)
	ds_write_b32 v37, v122 offset:4752
	s_waitcnt vmcnt(12)
	ds_write_b32 v37, v123 offset:5016
	s_waitcnt vmcnt(11)
	ds_write_b32 v37, v124 offset:5280
	s_waitcnt vmcnt(10)
	ds_write_b32 v37, v125 offset:5544
	s_waitcnt vmcnt(9)
	ds_write_b32 v37, v126 offset:5808
	s_waitcnt vmcnt(8)
	ds_write_b32 v37, v127 offset:6072
	s_waitcnt vmcnt(7)
	ds_write_b32 v37, v128 offset:6336
	s_waitcnt vmcnt(6)
	ds_write_b32 v37, v129 offset:6600
	s_waitcnt vmcnt(5)
	ds_write_b32 v37, v130 offset:6864
	s_waitcnt vmcnt(4)
	ds_write_b32 v37, v131 offset:7128
	s_waitcnt vmcnt(3)
	ds_write_b32 v37, v132 offset:7392
	s_waitcnt vmcnt(2)
	ds_write_b32 v37, v133 offset:7656
	s_waitcnt vmcnt(1)
	ds_write_b32 v37, v134 offset:7920
	s_waitcnt vmcnt(0)
	ds_write_b32 v37, v135 offset:8184
	s_branch .LBB0_653

; #define LAS __attribute__((address_space(3)))
; DI void cvt_item(const float* W, int ldw, int nvalid, int srccol0, bf16_t* WT, int K, int dstrow0, int k0, LAS float* scr, int lane) {
;     const int n = srccol0 + (lane & 31);
; #pragma unroll 8
;     for (int i = 0; i < 32; ++i) { const int kk = 2 * i + (lane >> 5); scr[kk * 33 + (lane & 31)] = (n < nvalid) ? __builtin_nontemporal_load(W + (size_t)(k0 + kk) * ldw + n) : 0.f; }
.LBB0_677:
	v_mov_b32_e32 v104, 0
	v_mov_b32_e32 v105, 0
	v_mov_b32_e32 v106, 0
	v_mov_b32_e32 v107, 0
	v_mov_b32_e32 v108, 0
	v_mov_b32_e32 v109, 0
	v_mov_b32_e32 v110, 0
	v_mov_b32_e32 v111, 0
	v_mov_b32_e32 v112, 0
	v_mov_b32_e32 v113, 0
	v_mov_b32_e32 v114, 0
	v_mov_b32_e32 v115, 0
	v_mov_b32_e32 v116, 0
	v_mov_b32_e32 v117, 0
	v_mov_b32_e32 v118, 0
	v_mov_b32_e32 v119, 0
	v_mov_b32_e32 v120, 0
	v_mov_b32_e32 v121, 0
	v_mov_b32_e32 v122, 0
	v_mov_b32_e32 v123, 0
	v_mov_b32_e32 v124, 0
	v_mov_b32_e32 v125, 0
	v_mov_b32_e32 v126, 0
	v_mov_b32_e32 v127, 0
	v_mov_b32_e32 v128, 0
	v_mov_b32_e32 v129, 0
	v_mov_b32_e32 v130, 0
	v_mov_b32_e32 v131, 0
	v_mov_b32_e32 v132, 0
	v_mov_b32_e32 v133, 0
	v_mov_b32_e32 v134, 0
	v_mov_b32_e32 v135, 0
	s_and_saveexec_b64 s[6:7], vcc
	v_add_u32_e32 v16, s5, v13
	v_ashrrev_i32_e32 v17, 31, v16
	v_lshlrev_b64 v[16:17], 12, v[16:17]
	v_lshl_add_u64 v[16:17], v[4:5], 0, v[16:17]
	global_load_dword v104, v[16:17], off nt
	v_add3_u32 v16, v13, s5, 2
	v_ashrrev_i32_e32 v17, 31, v16
	v_lshlrev_b64 v[16:17], 12, v[16:17]
	v_lshl_add_u64 v[16:17], v[4:5], 0, v[16:17]
	global_load_dword v105, v[16:17], off nt
	v_add3_u32 v16, v13, s5, 4
	v_ashrrev_i32_e32 v17, 31, v16
	v_lshlrev_b64 v[16:17], 12, v[16:17]
	v_lshl_add_u64 v[16:17], v[4:5], 0, v[16:17]
	global_load_dword v106, v[16:17], off nt
	v_add3_u32 v16, v13, s5, 6
	v_ashrrev_i32_e32 v17, 31, v16
	v_lshlrev_b64 v[16:17], 12, v[16:17]
	v_lshl_add_u64 v[16:17], v[4:5], 0, v[16:17]
	global_load_dword v107, v[16:17], off nt
	v_add3_u32 v16, v13, s5, 8
	v_ashrrev_i32_e32 v17, 31, v16
	v_lshlrev_b64 v[16:17], 12, v[16:17]
	v_lshl_add_u64 v[16:17], v[4:5], 0, v[16:17]
	global_load_dword v108, v[16:17], off nt
	v_add3_u32 v16, v13, s5, 10
	v_ashrrev_i32_e32 v17, 31, v16
	v_lshlrev_b64 v[16:17], 12, v[16:17]
	v_lshl_add_u64 v[16:17], v[4:5], 0, v[16:17]
	global_load_dword v109, v[16:17], off nt
	v_add3_u32 v16, v13, s5, 12
	v_ashrrev_i32_e32 v17, 31, v16
	v_lshlrev_b64 v[16:17], 12, v[16:17]
	v_lshl_add_u64 v[16:17], v[4:5], 0, v[16:17]
	global_load_dword v110, v[16:17], off nt
	v_add3_u32 v16, v13, s5, 14
	v_ashrrev_i32_e32 v17, 31, v16
	v_lshlrev_b64 v[16:17], 12, v[16:17]
	v_lshl_add_u64 v[16:17], v[4:5], 0, v[16:17]
	global_load_dword v111, v[16:17], off nt
	s_add_i32 s5, s5, 16
	v_add_u32_e32 v16, s5, v13
	v_ashrrev_i32_e32 v17, 31, v16
	v_lshlrev_b64 v[16:17], 12, v[16:17]
	v_lshl_add_u64 v[16:17], v[4:5], 0, v[16:17]
	global_load_dword v112, v[16:17], off nt
	v_add3_u32 v16, v13, s5, 2
	v_ashrrev_i32_e32 v17, 31, v16
	v_lshlrev_b64 v[16:17], 12, v[16:17]
	v_lshl_add_u64 v[16:17], v[4:5], 0, v[16:17]
	global_load_dword v113, v[16:17], off nt
	v_add3_u32 v16, v13, s5, 4
	v_ashrrev_i32_e32 v17, 31, v16
	v_lshlrev_b64 v[16:17], 12, v[16:17]
	v_lshl_add_u64 v[16:17], v[4:5], 0, v[16:17]
	global_load_dword v114, v[16:17], off nt
	v_add3_u32 v16, v13, s5, 6
	v_ashrrev_i32_e32 v17, 31, v16
	v_lshlrev_b64 v[16:17], 12, v[16:17]
	v_lshl_add_u64 v[16:17], v[4:5], 0, v[16:17]
	global_load_dword v115, v[16:17], off nt
	v_add3_u32 v16, v13, s5, 8
	v_ashrrev_i32_e32 v17, 31, v16
	v_lshlrev_b64 v[16:17], 12, v[16:17]
	v_lshl_add_u64 v[16:17], v[4:5], 0, v[16:17]
	global_load_dword v116, v[16:17], off nt
	v_add3_u32 v16, v13, s5, 10
	v_ashrrev_i32_e32 v17, 31, v16
	v_lshlrev_b64 v[16:17], 12, v[16:17]
	v_lshl_add_u64 v[16:17], v[4:5], 0, v[16:17]
	global_load_dword v117, v[16:17], off nt
	v_add3_u32 v16, v13, s5, 12
	v_ashrrev_i32_e32 v17, 31, v16
	v_lshlrev_b64 v[16:17], 12, v[16:17]
	v_lshl_add_u64 v[16:17], v[4:5], 0, v[16:17]
	global_load_dword v118, v[16:17], off nt
	v_add3_u32 v16, v13, s5, 14
	v_ashrrev_i32_e32 v17, 31, v16
	v_lshlrev_b64 v[16:17], 12, v[16:17]
	v_lshl_add_u64 v[16:17], v[4:5], 0, v[16:17]
	global_load_dword v119, v[16:17], off nt
	s_add_i32 s5, s5, 16
	v_add_u32_e32 v16, s5, v13
	v_ashrrev_i32_e32 v17, 31, v16
	v_lshlrev_b64 v[16:17], 12, v[16:17]
	v_lshl_add_u64 v[16:17], v[4:5], 0, v[16:17]
	global_load_dword v120, v[16:17], off nt
	v_add3_u32 v16, v13, s5, 2
	v_ashrrev_i32_e32 v17, 31, v16
	v_lshlrev_b64 v[16:17], 12, v[16:17]
	v_lshl_add_u64 v[16:17], v[4:5], 0, v[16:17]
	global_load_dword v121, v[16:17], off nt
	v_add3_u32 v16, v13, s5, 4
	v_ashrrev_i32_e32 v17, 31, v16
	v_lshlrev_b64 v[16:17], 12, v[16:17]
	v_lshl_add_u64 v[16:17], v[4:5], 0, v[16:17]
	global_load_dword v122, v[16:17], off nt
	v_add3_u32 v16, v13, s5, 6
	v_ashrrev_i32_e32 v17, 31, v16
	v_lshlrev_b64 v[16:17], 12, v[16:17]
	v_lshl_add_u64 v[16:17], v[4:5], 0, v[16:17]
	global_load_dword v123, v[16:17], off nt
	v_add3_u32 v16, v13, s5, 8
	v_ashrrev_i32_e32 v17, 31, v16
	v_lshlrev_b64 v[16:17], 12, v[16:17]
	v_lshl_add_u64 v[16:17], v[4:5], 0, v[16:17]
	global_load_dword v124, v[16:17], off nt
	v_add3_u32 v16, v13, s5, 10
	v_ashrrev_i32_e32 v17, 31, v16
	v_lshlrev_b64 v[16:17], 12, v[16:17]
	v_lshl_add_u64 v[16:17], v[4:5], 0, v[16:17]
	global_load_dword v125, v[16:17], off nt
	v_add3_u32 v16, v13, s5, 12
	v_ashrrev_i32_e32 v17, 31, v16
	v_lshlrev_b64 v[16:17], 12, v[16:17]
	v_lshl_add_u64 v[16:17], v[4:5], 0, v[16:17]
	global_load_dword v126, v[16:17], off nt
	v_add3_u32 v16, v13, s5, 14
	v_ashrrev_i32_e32 v17, 31, v16
	v_lshlrev_b64 v[16:17], 12, v[16:17]
	v_lshl_add_u64 v[16:17], v[4:5], 0, v[16:17]
	global_load_dword v127, v[16:17], off nt
	s_add_i32 s5, s5, 16
	v_add_u32_e32 v16, s5, v13
	v_ashrrev_i32_e32 v17, 31, v16
	v_lshlrev_b64 v[16:17], 12, v[16:17]
	v_lshl_add_u64 v[16:17], v[4:5], 0, v[16:17]
	global_load_dword v128, v[16:17], off nt
	v_add3_u32 v16, v13, s5, 2
	v_ashrrev_i32_e32 v17, 31, v16
	v_lshlrev_b64 v[16:17], 12, v[16:17]
	v_lshl_add_u64 v[16:17], v[4:5], 0, v[16:17]
	global_load_dword v129, v[16:17], off nt
	v_add3_u32 v16, v13, s5, 4
	v_ashrrev_i32_e32 v17, 31, v16
	v_lshlrev_b64 v[16:17], 12, v[16:17]
	v_lshl_add_u64 v[16:17], v[4:5], 0, v[16:17]
	global_load_dword v130, v[16:17], off nt
	v_add3_u32 v16, v13, s5, 6
	v_ashrrev_i32_e32 v17, 31, v16
	v_lshlrev_b64 v[16:17], 12, v[16:17]
	v_lshl_add_u64 v[16:17], v[4:5], 0, v[16:17]
	global_load_dword v131, v[16:17], off nt
	v_add3_u32 v16, v13, s5, 8
	v_ashrrev_i32_e32 v17, 31, v16
	v_lshlrev_b64 v[16:17], 12, v[16:17]
	v_lshl_add_u64 v[16:17], v[4:5], 0, v[16:17]
	global_load_dword v132, v[16:17], off nt
	v_add3_u32 v16, v13, s5, 10
	v_ashrrev_i32_e32 v17, 31, v16
	v_lshlrev_b64 v[16:17], 12, v[16:17]
	v_lshl_add_u64 v[16:17], v[4:5], 0, v[16:17]
	global_load_dword v133, v[16:17], off nt
	v_add3_u32 v16, v13, s5, 12
	v_ashrrev_i32_e32 v17, 31, v16
	v_lshlrev_b64 v[16:17], 12, v[16:17]
	v_lshl_add_u64 v[16:17], v[4:5], 0, v[16:17]
	global_load_dword v134, v[16:17], off nt
	v_add3_u32 v16, v13, s5, 14
	v_ashrrev_i32_e32 v17, 31, v16
	v_lshlrev_b64 v[16:17], 12, v[16:17]
	v_lshl_add_u64 v[16:17], v[4:5], 0, v[16:17]
	global_load_dword v135, v[16:17], off nt
	s_add_i32 s5, s5, 16
	s_or_b64 exec, exec, s[6:7]
	s_waitcnt vmcnt(31)
; DI void cvt_item(const float* W, int ldw, int nvalid, int srccol0, bf16_t* WT, int K, int dstrow0, int k0, LAS float* scr, int lane) {
;     ...
;     for (int i = 0; i < 32; ++i) { const int kk = 2 * i + (lane >> 5); scr[kk * 33 + (lane & 31)] = (n < nvalid) ? __builtin_nontemporal_load(W + (size_t)(k0 + kk) * ldw + n) : 0.f; }
;     asm volatile("s_waitcnt lgkmcnt(0)" ::: "memory");
	ds_write_b32 v14, v104
	s_waitcnt vmcnt(30)
	ds_write_b32 v14, v105 offset:264
	s_waitcnt vmcnt(29)
	ds_write_b32 v14, v106 offset:528
	s_waitcnt vmcnt(28)
	ds_write_b32 v14, v107 offset:792
	s_waitcnt vmcnt(27)
	ds_write_b32 v14, v108 offset:1056
	s_waitcnt vmcnt(26)
	ds_write_b32 v14, v109 offset:1320
	s_waitcnt vmcnt(25)
	ds_write_b32 v14, v110 offset:1584
	s_waitcnt vmcnt(24)
	ds_write_b32 v14, v111 offset:1848
	s_waitcnt vmcnt(23)
	ds_write_b32 v14, v112 offset:2112
	s_waitcnt vmcnt(22)
	ds_write_b32 v14, v113 offset:2376
	s_waitcnt vmcnt(21)
	ds_write_b32 v14, v114 offset:2640
	s_waitcnt vmcnt(20)
	ds_write_b32 v14, v115 offset:2904
	s_waitcnt vmcnt(19)
	ds_write_b32 v14, v116 offset:3168
	s_waitcnt vmcnt(18)
	ds_write_b32 v14, v117 offset:3432
	s_waitcnt vmcnt(17)
	ds_write_b32 v14, v118 offset:3696
	s_waitcnt vmcnt(16)
	ds_write_b32 v14, v119 offset:3960
	s_waitcnt vmcnt(15)
	ds_write_b32 v14, v120 offset:4224
	s_waitcnt vmcnt(14)
	ds_write_b32 v14, v121 offset:4488
	s_waitcnt vmcnt(13)
	ds_write_b32 v14, v122 offset:4752
	s_waitcnt vmcnt(12)
	ds_write_b32 v14, v123 offset:5016
	s_waitcnt vmcnt(11)
	ds_write_b32 v14, v124 offset:5280
	s_waitcnt vmcnt(10)
	ds_write_b32 v14, v125 offset:5544
	s_waitcnt vmcnt(9)
	ds_write_b32 v14, v126 offset:5808
	s_waitcnt vmcnt(8)
	ds_write_b32 v14, v127 offset:6072
	s_waitcnt vmcnt(7)
	ds_write_b32 v14, v128 offset:6336
	s_waitcnt vmcnt(6)
	ds_write_b32 v14, v129 offset:6600
	s_waitcnt vmcnt(5)
	ds_write_b32 v14, v130 offset:6864
	s_waitcnt vmcnt(4)
	ds_write_b32 v14, v131 offset:7128
	s_waitcnt vmcnt(3)
	ds_write_b32 v14, v132 offset:7392
	s_waitcnt vmcnt(2)
	ds_write_b32 v14, v133 offset:7656
	s_waitcnt vmcnt(1)
	ds_write_b32 v14, v134 offset:7920
	s_waitcnt vmcnt(0)
	ds_write_b32 v14, v135 offset:8184
	s_branch .LBB0_674

; #define LAS __attribute__((address_space(3)))
; DI void cvt_item(const float* W, int ldw, int nvalid, int srccol0, bf16_t* WT, int K, int dstrow0, int k0, LAS float* scr, int lane) {
;     const int n = srccol0 + (lane & 31);
; #pragma unroll 8
;     for (int i = 0; i < 32; ++i) { const int kk = 2 * i + (lane >> 5); scr[kk * 33 + (lane & 31)] = (n < nvalid) ? __builtin_nontemporal_load(W + (size_t)(k0 + kk) * ldw + n) : 0.f; }
;     asm volatile("s_waitcnt lgkmcnt(0)" ::: "memory");
.LBB0_698:
	v_mov_b32_e32 v104, 0
	v_mov_b32_e32 v105, 0
	v_mov_b32_e32 v106, 0
	v_mov_b32_e32 v107, 0
	v_mov_b32_e32 v108, 0
	v_mov_b32_e32 v109, 0
	v_mov_b32_e32 v110, 0
	v_mov_b32_e32 v111, 0
	v_mov_b32_e32 v112, 0
	v_mov_b32_e32 v113, 0
	v_mov_b32_e32 v114, 0
	v_mov_b32_e32 v115, 0
	v_mov_b32_e32 v116, 0
	v_mov_b32_e32 v117, 0
	v_mov_b32_e32 v118, 0
	v_mov_b32_e32 v119, 0
	v_mov_b32_e32 v120, 0
	v_mov_b32_e32 v121, 0
	v_mov_b32_e32 v122, 0
	v_mov_b32_e32 v123, 0
	v_mov_b32_e32 v124, 0
	v_mov_b32_e32 v125, 0
	v_mov_b32_e32 v126, 0
	v_mov_b32_e32 v127, 0
	v_mov_b32_e32 v128, 0
	v_mov_b32_e32 v129, 0
	v_mov_b32_e32 v130, 0
	v_mov_b32_e32 v131, 0
	v_mov_b32_e32 v132, 0
	v_mov_b32_e32 v133, 0
	v_mov_b32_e32 v134, 0
	v_mov_b32_e32 v135, 0
	s_and_saveexec_b64 s[6:7], vcc
	v_add_u32_e32 v16, s5, v13
	v_mad_i64_i32 v[16:17], s[16:17], v16, s83, v[4:5]
	global_load_dword v104, v[16:17], off nt
	v_add3_u32 v15, v13, s5, 2
	v_mad_i64_i32 v[16:17], s[16:17], v15, s83, v[4:5]
	global_load_dword v105, v[16:17], off nt
	v_add3_u32 v16, v13, s5, 4
	v_mad_i64_i32 v[16:17], s[16:17], v16, s83, v[4:5]
	global_load_dword v106, v[16:17], off nt
	v_add3_u32 v15, v13, s5, 6
	v_mad_i64_i32 v[16:17], s[16:17], v15, s83, v[4:5]
	global_load_dword v107, v[16:17], off nt
	v_add3_u32 v16, v13, s5, 8
	v_mad_i64_i32 v[16:17], s[16:17], v16, s83, v[4:5]
	global_load_dword v108, v[16:17], off nt
	v_add3_u32 v15, v13, s5, 10
	v_mad_i64_i32 v[16:17], s[16:17], v15, s83, v[4:5]
	global_load_dword v109, v[16:17], off nt
	v_add3_u32 v16, v13, s5, 12
	v_mad_i64_i32 v[16:17], s[16:17], v16, s83, v[4:5]
	global_load_dword v110, v[16:17], off nt
	v_add3_u32 v15, v13, s5, 14
	v_mad_i64_i32 v[16:17], s[16:17], v15, s83, v[4:5]
	global_load_dword v111, v[16:17], off nt
	s_add_i32 s5, s5, 16
	v_add_u32_e32 v16, s5, v13
	v_mad_i64_i32 v[16:17], s[16:17], v16, s83, v[4:5]
	global_load_dword v112, v[16:17], off nt
	v_add3_u32 v15, v13, s5, 2
	v_mad_i64_i32 v[16:17], s[16:17], v15, s83, v[4:5]
	global_load_dword v113, v[16:17], off nt
	v_add3_u32 v16, v13, s5, 4
	v_mad_i64_i32 v[16:17], s[16:17], v16, s83, v[4:5]
	global_load_dword v114, v[16:17], off nt
	v_add3_u32 v15, v13, s5, 6
	v_mad_i64_i32 v[16:17], s[16:17], v15, s83, v[4:5]
	global_load_dword v115, v[16:17], off nt
	v_add3_u32 v16, v13, s5, 8
	v_mad_i64_i32 v[16:17], s[16:17], v16, s83, v[4:5]
	global_load_dword v116, v[16:17], off nt
	v_add3_u32 v15, v13, s5, 10
	v_mad_i64_i32 v[16:17], s[16:17], v15, s83, v[4:5]
	global_load_dword v117, v[16:17], off nt
	v_add3_u32 v16, v13, s5, 12
	v_mad_i64_i32 v[16:17], s[16:17], v16, s83, v[4:5]
	global_load_dword v118, v[16:17], off nt
	v_add3_u32 v15, v13, s5, 14
	v_mad_i64_i32 v[16:17], s[16:17], v15, s83, v[4:5]
	global_load_dword v119, v[16:17], off nt
	s_add_i32 s5, s5, 16
	v_add_u32_e32 v16, s5, v13
	v_mad_i64_i32 v[16:17], s[16:17], v16, s83, v[4:5]
	global_load_dword v120, v[16:17], off nt
	v_add3_u32 v15, v13, s5, 2
	v_mad_i64_i32 v[16:17], s[16:17], v15, s83, v[4:5]
	global_load_dword v121, v[16:17], off nt
	v_add3_u32 v16, v13, s5, 4
	v_mad_i64_i32 v[16:17], s[16:17], v16, s83, v[4:5]
	global_load_dword v122, v[16:17], off nt
	v_add3_u32 v15, v13, s5, 6
	v_mad_i64_i32 v[16:17], s[16:17], v15, s83, v[4:5]
	global_load_dword v123, v[16:17], off nt
	v_add3_u32 v16, v13, s5, 8
	v_mad_i64_i32 v[16:17], s[16:17], v16, s83, v[4:5]
	global_load_dword v124, v[16:17], off nt
	v_add3_u32 v15, v13, s5, 10
	v_mad_i64_i32 v[16:17], s[16:17], v15, s83, v[4:5]
	global_load_dword v125, v[16:17], off nt
	v_add3_u32 v16, v13, s5, 12
	v_mad_i64_i32 v[16:17], s[16:17], v16, s83, v[4:5]
	global_load_dword v126, v[16:17], off nt
	v_add3_u32 v15, v13, s5, 14
	v_mad_i64_i32 v[16:17], s[16:17], v15, s83, v[4:5]
	global_load_dword v127, v[16:17], off nt
	s_add_i32 s5, s5, 16
	v_add_u32_e32 v16, s5, v13
	v_mad_i64_i32 v[16:17], s[16:17], v16, s83, v[4:5]
	global_load_dword v128, v[16:17], off nt
	v_add3_u32 v15, v13, s5, 2
	v_mad_i64_i32 v[16:17], s[16:17], v15, s83, v[4:5]
	global_load_dword v129, v[16:17], off nt
	v_add3_u32 v16, v13, s5, 4
	v_mad_i64_i32 v[16:17], s[16:17], v16, s83, v[4:5]
	global_load_dword v130, v[16:17], off nt
	v_add3_u32 v15, v13, s5, 6
	v_mad_i64_i32 v[16:17], s[16:17], v15, s83, v[4:5]
	global_load_dword v131, v[16:17], off nt
	v_add3_u32 v16, v13, s5, 8
	v_mad_i64_i32 v[16:17], s[16:17], v16, s83, v[4:5]
	global_load_dword v132, v[16:17], off nt
	v_add3_u32 v15, v13, s5, 10
	v_mad_i64_i32 v[16:17], s[16:17], v15, s83, v[4:5]
	global_load_dword v133, v[16:17], off nt
	v_add3_u32 v16, v13, s5, 12
	v_mad_i64_i32 v[16:17], s[16:17], v16, s83, v[4:5]
	global_load_dword v134, v[16:17], off nt
	v_add3_u32 v15, v13, s5, 14
	v_mad_i64_i32 v[16:17], s[16:17], v15, s83, v[4:5]
	global_load_dword v135, v[16:17], off nt
	s_add_i32 s5, s5, 16
	s_or_b64 exec, exec, s[6:7]
	s_waitcnt vmcnt(31)
	ds_write_b32 v14, v104
	s_waitcnt vmcnt(30)
	ds_write_b32 v14, v105 offset:264
	s_waitcnt vmcnt(29)
	ds_write_b32 v14, v106 offset:528
	s_waitcnt vmcnt(28)
	ds_write_b32 v14, v107 offset:792
	s_waitcnt vmcnt(27)
	ds_write_b32 v14, v108 offset:1056
	s_waitcnt vmcnt(26)
	ds_write_b32 v14, v109 offset:1320
	s_waitcnt vmcnt(25)
	ds_write_b32 v14, v110 offset:1584
	s_waitcnt vmcnt(24)
	ds_write_b32 v14, v111 offset:1848
	s_waitcnt vmcnt(23)
	ds_write_b32 v14, v112 offset:2112
	s_waitcnt vmcnt(22)
	ds_write_b32 v14, v113 offset:2376
	s_waitcnt vmcnt(21)
	ds_write_b32 v14, v114 offset:2640
	s_waitcnt vmcnt(20)
	ds_write_b32 v14, v115 offset:2904
	s_waitcnt vmcnt(19)
	ds_write_b32 v14, v116 offset:3168
	s_waitcnt vmcnt(18)
	ds_write_b32 v14, v117 offset:3432
	s_waitcnt vmcnt(17)
	ds_write_b32 v14, v118 offset:3696
	s_waitcnt vmcnt(16)
	ds_write_b32 v14, v119 offset:3960
	s_waitcnt vmcnt(15)
	ds_write_b32 v14, v120 offset:4224
	s_waitcnt vmcnt(14)
	ds_write_b32 v14, v121 offset:4488
	s_waitcnt vmcnt(13)
	ds_write_b32 v14, v122 offset:4752
	s_waitcnt vmcnt(12)
	ds_write_b32 v14, v123 offset:5016
	s_waitcnt vmcnt(11)
	ds_write_b32 v14, v124 offset:5280
	s_waitcnt vmcnt(10)
	ds_write_b32 v14, v125 offset:5544
	s_waitcnt vmcnt(9)
	ds_write_b32 v14, v126 offset:5808
	s_waitcnt vmcnt(8)
	ds_write_b32 v14, v127 offset:6072
	s_waitcnt vmcnt(7)
	ds_write_b32 v14, v128 offset:6336
	s_waitcnt vmcnt(6)
	ds_write_b32 v14, v129 offset:6600
	s_waitcnt vmcnt(5)
	ds_write_b32 v14, v130 offset:6864
	s_waitcnt vmcnt(4)
	ds_write_b32 v14, v131 offset:7128
	s_waitcnt vmcnt(3)
	ds_write_b32 v14, v132 offset:7392
	s_waitcnt vmcnt(2)
	ds_write_b32 v14, v133 offset:7656
	s_waitcnt vmcnt(1)
	ds_write_b32 v14, v134 offset:7920
	s_waitcnt vmcnt(0)
	ds_write_b32 v14, v135 offset:8184
	s_branch .LBB0_695

; #define LAS __attribute__((address_space(3)))
; DI void cvt_item(const float* W, int ldw, int nvalid, int srccol0, bf16_t* WT, int K, int dstrow0, int k0, LAS float* scr, int lane) {
;     const int n = srccol0 + (lane & 31);
; #pragma unroll 8
;     for (int i = 0; i < 32; ++i) { const int kk = 2 * i + (lane >> 5); scr[kk * 33 + (lane & 31)] = (n < nvalid) ? __builtin_nontemporal_load(W + (size_t)(k0 + kk) * ldw + n) : 0.f; }
;     asm volatile("s_waitcnt lgkmcnt(0)" ::: "memory");
.LBB0_742:
	v_mov_b32_e32 v104, 0
	v_mov_b32_e32 v105, 0
	v_mov_b32_e32 v106, 0
	v_mov_b32_e32 v107, 0
	v_mov_b32_e32 v108, 0
	v_mov_b32_e32 v109, 0
	v_mov_b32_e32 v110, 0
	v_mov_b32_e32 v111, 0
	v_mov_b32_e32 v112, 0
	v_mov_b32_e32 v113, 0
	v_mov_b32_e32 v114, 0
	v_mov_b32_e32 v115, 0
	v_mov_b32_e32 v116, 0
	v_mov_b32_e32 v117, 0
	v_mov_b32_e32 v118, 0
	v_mov_b32_e32 v119, 0
	v_mov_b32_e32 v120, 0
	v_mov_b32_e32 v121, 0
	v_mov_b32_e32 v122, 0
	v_mov_b32_e32 v123, 0
	v_mov_b32_e32 v124, 0
	v_mov_b32_e32 v125, 0
	v_mov_b32_e32 v126, 0
	v_mov_b32_e32 v127, 0
	v_mov_b32_e32 v128, 0
	v_mov_b32_e32 v129, 0
	v_mov_b32_e32 v130, 0
	v_mov_b32_e32 v131, 0
	v_mov_b32_e32 v132, 0
	v_mov_b32_e32 v133, 0
	v_mov_b32_e32 v134, 0
	v_mov_b32_e32 v135, 0
	s_and_saveexec_b64 s[6:7], vcc
	v_lshl_add_u64 v[40:41], v[18:19], 0, s[4:5]
	global_load_dword v104, v[40:41], off nt
	v_lshl_add_u64 v[38:39], v[16:17], 0, s[4:5]
	global_load_dword v105, v[38:39], off nt
	v_lshl_add_u64 v[40:41], v[14:15], 0, s[4:5]
	global_load_dword v106, v[40:41], off nt
	v_lshl_add_u64 v[38:39], v[12:13], 0, s[4:5]
	global_load_dword v107, v[38:39], off nt
	v_lshl_add_u64 v[40:41], v[10:11], 0, s[4:5]
	global_load_dword v108, v[40:41], off nt
	v_lshl_add_u64 v[38:39], v[8:9], 0, s[4:5]
	global_load_dword v109, v[38:39], off nt
	v_lshl_add_u64 v[40:41], v[6:7], 0, s[4:5]
	global_load_dword v110, v[40:41], off nt
	v_lshl_add_u64 v[38:39], v[4:5], 0, s[4:5]
	global_load_dword v111, v[38:39], off nt
	s_add_u32 s4, s4, 0x58000
	s_addc_u32 s5, s5, 0
	v_lshl_add_u64 v[40:41], v[18:19], 0, s[4:5]
	global_load_dword v112, v[40:41], off nt
	v_lshl_add_u64 v[38:39], v[16:17], 0, s[4:5]
	global_load_dword v113, v[38:39], off nt
	v_lshl_add_u64 v[40:41], v[14:15], 0, s[4:5]
	global_load_dword v114, v[40:41], off nt
	v_lshl_add_u64 v[38:39], v[12:13], 0, s[4:5]
	global_load_dword v115, v[38:39], off nt
	v_lshl_add_u64 v[40:41], v[10:11], 0, s[4:5]
	global_load_dword v116, v[40:41], off nt
	v_lshl_add_u64 v[38:39], v[8:9], 0, s[4:5]
	global_load_dword v117, v[38:39], off nt
	v_lshl_add_u64 v[40:41], v[6:7], 0, s[4:5]
	global_load_dword v118, v[40:41], off nt
	v_lshl_add_u64 v[38:39], v[4:5], 0, s[4:5]
	global_load_dword v119, v[38:39], off nt
	s_add_u32 s4, s4, 0x58000
	s_addc_u32 s5, s5, 0
	v_lshl_add_u64 v[40:41], v[18:19], 0, s[4:5]
	global_load_dword v120, v[40:41], off nt
	v_lshl_add_u64 v[38:39], v[16:17], 0, s[4:5]
	global_load_dword v121, v[38:39], off nt
	v_lshl_add_u64 v[40:41], v[14:15], 0, s[4:5]
	global_load_dword v122, v[40:41], off nt
	v_lshl_add_u64 v[38:39], v[12:13], 0, s[4:5]
	global_load_dword v123, v[38:39], off nt
	v_lshl_add_u64 v[40:41], v[10:11], 0, s[4:5]
	global_load_dword v124, v[40:41], off nt
	v_lshl_add_u64 v[38:39], v[8:9], 0, s[4:5]
	global_load_dword v125, v[38:39], off nt
	v_lshl_add_u64 v[40:41], v[6:7], 0, s[4:5]
	global_load_dword v126, v[40:41], off nt
	v_lshl_add_u64 v[38:39], v[4:5], 0, s[4:5]
	global_load_dword v127, v[38:39], off nt
	s_add_u32 s4, s4, 0x58000
	s_addc_u32 s5, s5, 0
	v_lshl_add_u64 v[40:41], v[18:19], 0, s[4:5]
	global_load_dword v128, v[40:41], off nt
	v_lshl_add_u64 v[38:39], v[16:17], 0, s[4:5]
	global_load_dword v129, v[38:39], off nt
	v_lshl_add_u64 v[40:41], v[14:15], 0, s[4:5]
	global_load_dword v130, v[40:41], off nt
	v_lshl_add_u64 v[38:39], v[12:13], 0, s[4:5]
	global_load_dword v131, v[38:39], off nt
	v_lshl_add_u64 v[40:41], v[10:11], 0, s[4:5]
	global_load_dword v132, v[40:41], off nt
	v_lshl_add_u64 v[38:39], v[8:9], 0, s[4:5]
	global_load_dword v133, v[38:39], off nt
	v_lshl_add_u64 v[40:41], v[6:7], 0, s[4:5]
	global_load_dword v134, v[40:41], off nt
	v_lshl_add_u64 v[38:39], v[4:5], 0, s[4:5]
	global_load_dword v135, v[38:39], off nt
	s_add_u32 s4, s4, 0x58000
	s_addc_u32 s5, s5, 0
	s_or_b64 exec, exec, s[6:7]
	s_waitcnt vmcnt(31)
	ds_write_b32 v37, v104
	s_waitcnt vmcnt(30)
	ds_write_b32 v37, v105 offset:264
	s_waitcnt vmcnt(29)
	ds_write_b32 v37, v106 offset:528
	s_waitcnt vmcnt(28)
	ds_write_b32 v37, v107 offset:792
	s_waitcnt vmcnt(27)
	ds_write_b32 v37, v108 offset:1056
	s_waitcnt vmcnt(26)
	ds_write_b32 v37, v109 offset:1320
	s_waitcnt vmcnt(25)
	ds_write_b32 v37, v110 offset:1584
	s_waitcnt vmcnt(24)
	ds_write_b32 v37, v111 offset:1848
	s_waitcnt vmcnt(23)
	ds_write_b32 v37, v112 offset:2112
	s_waitcnt vmcnt(22)
	ds_write_b32 v37, v113 offset:2376
	s_waitcnt vmcnt(21)
	ds_write_b32 v37, v114 offset:2640
	s_waitcnt vmcnt(20)
	ds_write_b32 v37, v115 offset:2904
	s_waitcnt vmcnt(19)
	ds_write_b32 v37, v116 offset:3168
	s_waitcnt vmcnt(18)
	ds_write_b32 v37, v117 offset:3432
	s_waitcnt vmcnt(17)
	ds_write_b32 v37, v118 offset:3696
	s_waitcnt vmcnt(16)
	ds_write_b32 v37, v119 offset:3960
	s_waitcnt vmcnt(15)
	ds_write_b32 v37, v120 offset:4224
	s_waitcnt vmcnt(14)
	ds_write_b32 v37, v121 offset:4488
	s_waitcnt vmcnt(13)
	ds_write_b32 v37, v122 offset:4752
	s_waitcnt vmcnt(12)
	ds_write_b32 v37, v123 offset:5016
	s_waitcnt vmcnt(11)
	ds_write_b32 v37, v124 offset:5280
	s_waitcnt vmcnt(10)
	ds_write_b32 v37, v125 offset:5544
	s_waitcnt vmcnt(9)
	ds_write_b32 v37, v126 offset:5808
	s_waitcnt vmcnt(8)
	ds_write_b32 v37, v127 offset:6072
	s_waitcnt vmcnt(7)
	ds_write_b32 v37, v128 offset:6336
	s_waitcnt vmcnt(6)
	ds_write_b32 v37, v129 offset:6600
	s_waitcnt vmcnt(5)
	ds_write_b32 v37, v130 offset:6864
	s_waitcnt vmcnt(4)
	ds_write_b32 v37, v131 offset:7128
	s_waitcnt vmcnt(3)
	ds_write_b32 v37, v132 offset:7392
	s_waitcnt vmcnt(2)
	ds_write_b32 v37, v133 offset:7656
	s_waitcnt vmcnt(1)
	ds_write_b32 v37, v134 offset:7920
	s_waitcnt vmcnt(0)
	ds_write_b32 v37, v135 offset:8184
	s_branch .LBB0_739

; #define LAS __attribute__((address_space(3)))
; DI void cvt_item(const float* W, int ldw, int nvalid, int srccol0, bf16_t* WT, int K, int dstrow0, int k0, LAS float* scr, int lane) {
;     const int n = srccol0 + (lane & 31);
; #pragma unroll 8
;     for (int i = 0; i < 32; ++i) { const int kk = 2 * i + (lane >> 5); scr[kk * 33 + (lane & 31)] = (n < nvalid) ? __builtin_nontemporal_load(W + (size_t)(k0 + kk) * ldw + n) : 0.f; }
.LBB0_765:
	v_mov_b32_e32 v104, 0
	v_mov_b32_e32 v105, 0
	v_mov_b32_e32 v106, 0
	v_mov_b32_e32 v107, 0
	v_mov_b32_e32 v108, 0
	v_mov_b32_e32 v109, 0
	v_mov_b32_e32 v110, 0
	v_mov_b32_e32 v111, 0
	v_mov_b32_e32 v112, 0
	v_mov_b32_e32 v113, 0
	v_mov_b32_e32 v114, 0
	v_mov_b32_e32 v115, 0
	v_mov_b32_e32 v116, 0
	v_mov_b32_e32 v117, 0
	v_mov_b32_e32 v118, 0
	v_mov_b32_e32 v119, 0
	v_mov_b32_e32 v120, 0
	v_mov_b32_e32 v121, 0
	v_mov_b32_e32 v122, 0
	v_mov_b32_e32 v123, 0
	v_mov_b32_e32 v124, 0
	v_mov_b32_e32 v125, 0
	v_mov_b32_e32 v126, 0
	v_mov_b32_e32 v127, 0
	v_mov_b32_e32 v128, 0
	v_mov_b32_e32 v129, 0
	v_mov_b32_e32 v130, 0
	v_mov_b32_e32 v131, 0
	v_mov_b32_e32 v132, 0
	v_mov_b32_e32 v133, 0
	v_mov_b32_e32 v134, 0
	v_mov_b32_e32 v135, 0
	s_and_saveexec_b64 s[4:5], vcc
	v_add_u32_e32 v16, s1, v11
	v_ashrrev_i32_e32 v17, 31, v16
	v_lshlrev_b64 v[16:17], 12, v[16:17]
	v_lshl_add_u64 v[16:17], v[4:5], 0, v[16:17]
	global_load_dword v104, v[16:17], off nt
	v_add3_u32 v16, v11, s1, 2
	v_ashrrev_i32_e32 v17, 31, v16
	v_lshlrev_b64 v[16:17], 12, v[16:17]
	v_lshl_add_u64 v[16:17], v[4:5], 0, v[16:17]
	global_load_dword v105, v[16:17], off nt
	v_add3_u32 v16, v11, s1, 4
	v_ashrrev_i32_e32 v17, 31, v16
	v_lshlrev_b64 v[16:17], 12, v[16:17]
	v_lshl_add_u64 v[16:17], v[4:5], 0, v[16:17]
	global_load_dword v106, v[16:17], off nt
	v_add3_u32 v16, v11, s1, 6
	v_ashrrev_i32_e32 v17, 31, v16
	v_lshlrev_b64 v[16:17], 12, v[16:17]
	v_lshl_add_u64 v[16:17], v[4:5], 0, v[16:17]
	global_load_dword v107, v[16:17], off nt
	v_add3_u32 v16, v11, s1, 8
	v_ashrrev_i32_e32 v17, 31, v16
	v_lshlrev_b64 v[16:17], 12, v[16:17]
	v_lshl_add_u64 v[16:17], v[4:5], 0, v[16:17]
	global_load_dword v108, v[16:17], off nt
	v_add3_u32 v16, v11, s1, 10
	v_ashrrev_i32_e32 v17, 31, v16
	v_lshlrev_b64 v[16:17], 12, v[16:17]
	v_lshl_add_u64 v[16:17], v[4:5], 0, v[16:17]
	global_load_dword v109, v[16:17], off nt
	v_add3_u32 v16, v11, s1, 12
	v_ashrrev_i32_e32 v17, 31, v16
	v_lshlrev_b64 v[16:17], 12, v[16:17]
	v_lshl_add_u64 v[16:17], v[4:5], 0, v[16:17]
	global_load_dword v110, v[16:17], off nt
	v_add3_u32 v16, v11, s1, 14
	v_ashrrev_i32_e32 v17, 31, v16
	v_lshlrev_b64 v[16:17], 12, v[16:17]
	v_lshl_add_u64 v[16:17], v[4:5], 0, v[16:17]
	global_load_dword v111, v[16:17], off nt
	s_add_i32 s1, s1, 16
	v_add_u32_e32 v16, s1, v11
	v_ashrrev_i32_e32 v17, 31, v16
	v_lshlrev_b64 v[16:17], 12, v[16:17]
	v_lshl_add_u64 v[16:17], v[4:5], 0, v[16:17]
	global_load_dword v112, v[16:17], off nt
	v_add3_u32 v16, v11, s1, 2
	v_ashrrev_i32_e32 v17, 31, v16
	v_lshlrev_b64 v[16:17], 12, v[16:17]
	v_lshl_add_u64 v[16:17], v[4:5], 0, v[16:17]
	global_load_dword v113, v[16:17], off nt
	v_add3_u32 v16, v11, s1, 4
	v_ashrrev_i32_e32 v17, 31, v16
	v_lshlrev_b64 v[16:17], 12, v[16:17]
	v_lshl_add_u64 v[16:17], v[4:5], 0, v[16:17]
	global_load_dword v114, v[16:17], off nt
	v_add3_u32 v16, v11, s1, 6
	v_ashrrev_i32_e32 v17, 31, v16
	v_lshlrev_b64 v[16:17], 12, v[16:17]
	v_lshl_add_u64 v[16:17], v[4:5], 0, v[16:17]
	global_load_dword v115, v[16:17], off nt
	v_add3_u32 v16, v11, s1, 8
	v_ashrrev_i32_e32 v17, 31, v16
	v_lshlrev_b64 v[16:17], 12, v[16:17]
	v_lshl_add_u64 v[16:17], v[4:5], 0, v[16:17]
	global_load_dword v116, v[16:17], off nt
	v_add3_u32 v16, v11, s1, 10
	v_ashrrev_i32_e32 v17, 31, v16
	v_lshlrev_b64 v[16:17], 12, v[16:17]
	v_lshl_add_u64 v[16:17], v[4:5], 0, v[16:17]
	global_load_dword v117, v[16:17], off nt
	v_add3_u32 v16, v11, s1, 12
	v_ashrrev_i32_e32 v17, 31, v16
	v_lshlrev_b64 v[16:17], 12, v[16:17]
	v_lshl_add_u64 v[16:17], v[4:5], 0, v[16:17]
	global_load_dword v118, v[16:17], off nt
	v_add3_u32 v16, v11, s1, 14
	v_ashrrev_i32_e32 v17, 31, v16
	v_lshlrev_b64 v[16:17], 12, v[16:17]
	v_lshl_add_u64 v[16:17], v[4:5], 0, v[16:17]
	global_load_dword v119, v[16:17], off nt
	s_add_i32 s1, s1, 16
	v_add_u32_e32 v16, s1, v11
	v_ashrrev_i32_e32 v17, 31, v16
	v_lshlrev_b64 v[16:17], 12, v[16:17]
	v_lshl_add_u64 v[16:17], v[4:5], 0, v[16:17]
	global_load_dword v120, v[16:17], off nt
	v_add3_u32 v16, v11, s1, 2
	v_ashrrev_i32_e32 v17, 31, v16
	v_lshlrev_b64 v[16:17], 12, v[16:17]
	v_lshl_add_u64 v[16:17], v[4:5], 0, v[16:17]
	global_load_dword v121, v[16:17], off nt
	v_add3_u32 v16, v11, s1, 4
	v_ashrrev_i32_e32 v17, 31, v16
	v_lshlrev_b64 v[16:17], 12, v[16:17]
	v_lshl_add_u64 v[16:17], v[4:5], 0, v[16:17]
	global_load_dword v122, v[16:17], off nt
	v_add3_u32 v16, v11, s1, 6
	v_ashrrev_i32_e32 v17, 31, v16
	v_lshlrev_b64 v[16:17], 12, v[16:17]
	v_lshl_add_u64 v[16:17], v[4:5], 0, v[16:17]
	global_load_dword v123, v[16:17], off nt
	v_add3_u32 v16, v11, s1, 8
	v_ashrrev_i32_e32 v17, 31, v16
	v_lshlrev_b64 v[16:17], 12, v[16:17]
	v_lshl_add_u64 v[16:17], v[4:5], 0, v[16:17]
	global_load_dword v124, v[16:17], off nt
	v_add3_u32 v16, v11, s1, 10
	v_ashrrev_i32_e32 v17, 31, v16
	v_lshlrev_b64 v[16:17], 12, v[16:17]
	v_lshl_add_u64 v[16:17], v[4:5], 0, v[16:17]
	global_load_dword v125, v[16:17], off nt
	v_add3_u32 v16, v11, s1, 12
	v_ashrrev_i32_e32 v17, 31, v16
	v_lshlrev_b64 v[16:17], 12, v[16:17]
	v_lshl_add_u64 v[16:17], v[4:5], 0, v[16:17]
	global_load_dword v126, v[16:17], off nt
	v_add3_u32 v16, v11, s1, 14
	v_ashrrev_i32_e32 v17, 31, v16
	v_lshlrev_b64 v[16:17], 12, v[16:17]
	v_lshl_add_u64 v[16:17], v[4:5], 0, v[16:17]
	global_load_dword v127, v[16:17], off nt
	s_add_i32 s1, s1, 16
	v_add_u32_e32 v16, s1, v11
	v_ashrrev_i32_e32 v17, 31, v16
	v_lshlrev_b64 v[16:17], 12, v[16:17]
	v_lshl_add_u64 v[16:17], v[4:5], 0, v[16:17]
	global_load_dword v128, v[16:17], off nt
	v_add3_u32 v16, v11, s1, 2
	v_ashrrev_i32_e32 v17, 31, v16
	v_lshlrev_b64 v[16:17], 12, v[16:17]
	v_lshl_add_u64 v[16:17], v[4:5], 0, v[16:17]
	global_load_dword v129, v[16:17], off nt
	v_add3_u32 v16, v11, s1, 4
	v_ashrrev_i32_e32 v17, 31, v16
	v_lshlrev_b64 v[16:17], 12, v[16:17]
	v_lshl_add_u64 v[16:17], v[4:5], 0, v[16:17]
	global_load_dword v130, v[16:17], off nt
	v_add3_u32 v16, v11, s1, 6
	v_ashrrev_i32_e32 v17, 31, v16
	v_lshlrev_b64 v[16:17], 12, v[16:17]
	v_lshl_add_u64 v[16:17], v[4:5], 0, v[16:17]
	global_load_dword v131, v[16:17], off nt
	v_add3_u32 v16, v11, s1, 8
	v_ashrrev_i32_e32 v17, 31, v16
	v_lshlrev_b64 v[16:17], 12, v[16:17]
	v_lshl_add_u64 v[16:17], v[4:5], 0, v[16:17]
	global_load_dword v132, v[16:17], off nt
	v_add3_u32 v16, v11, s1, 10
	v_ashrrev_i32_e32 v17, 31, v16
	v_lshlrev_b64 v[16:17], 12, v[16:17]
	v_lshl_add_u64 v[16:17], v[4:5], 0, v[16:17]
	global_load_dword v133, v[16:17], off nt
	v_add3_u32 v16, v11, s1, 12
	v_ashrrev_i32_e32 v17, 31, v16
	v_lshlrev_b64 v[16:17], 12, v[16:17]
	v_lshl_add_u64 v[16:17], v[4:5], 0, v[16:17]
	global_load_dword v134, v[16:17], off nt
	v_add3_u32 v16, v11, s1, 14
	v_ashrrev_i32_e32 v17, 31, v16
	v_lshlrev_b64 v[16:17], 12, v[16:17]
	v_lshl_add_u64 v[16:17], v[4:5], 0, v[16:17]
	global_load_dword v135, v[16:17], off nt
	s_add_i32 s1, s1, 16
	s_or_b64 exec, exec, s[4:5]
	s_waitcnt vmcnt(31)
; DI void cvt_item(const float* W, int ldw, int nvalid, int srccol0, bf16_t* WT, int K, int dstrow0, int k0, LAS float* scr, int lane) {
;     ...
;     for (int i = 0; i < 32; ++i) { const int kk = 2 * i + (lane >> 5); scr[kk * 33 + (lane & 31)] = (n < nvalid) ? __builtin_nontemporal_load(W + (size_t)(k0 + kk) * ldw + n) : 0.f; }
;     asm volatile("s_waitcnt lgkmcnt(0)" ::: "memory");
	ds_write_b32 v14, v104
	s_waitcnt vmcnt(30)
	ds_write_b32 v14, v105 offset:264
	s_waitcnt vmcnt(29)
	ds_write_b32 v14, v106 offset:528
	s_waitcnt vmcnt(28)
	ds_write_b32 v14, v107 offset:792
	s_waitcnt vmcnt(27)
	ds_write_b32 v14, v108 offset:1056
	s_waitcnt vmcnt(26)
	ds_write_b32 v14, v109 offset:1320
	s_waitcnt vmcnt(25)
	ds_write_b32 v14, v110 offset:1584
	s_waitcnt vmcnt(24)
	ds_write_b32 v14, v111 offset:1848
	s_waitcnt vmcnt(23)
	ds_write_b32 v14, v112 offset:2112
	s_waitcnt vmcnt(22)
	ds_write_b32 v14, v113 offset:2376
	s_waitcnt vmcnt(21)
	ds_write_b32 v14, v114 offset:2640
	s_waitcnt vmcnt(20)
	ds_write_b32 v14, v115 offset:2904
	s_waitcnt vmcnt(19)
	ds_write_b32 v14, v116 offset:3168
	s_waitcnt vmcnt(18)
	ds_write_b32 v14, v117 offset:3432
	s_waitcnt vmcnt(17)
	ds_write_b32 v14, v118 offset:3696
	s_waitcnt vmcnt(16)
	ds_write_b32 v14, v119 offset:3960
	s_waitcnt vmcnt(15)
	ds_write_b32 v14, v120 offset:4224
	s_waitcnt vmcnt(14)
	ds_write_b32 v14, v121 offset:4488
	s_waitcnt vmcnt(13)
	ds_write_b32 v14, v122 offset:4752
	s_waitcnt vmcnt(12)
	ds_write_b32 v14, v123 offset:5016
	s_waitcnt vmcnt(11)
	ds_write_b32 v14, v124 offset:5280
	s_waitcnt vmcnt(10)
	ds_write_b32 v14, v125 offset:5544
	s_waitcnt vmcnt(9)
	ds_write_b32 v14, v126 offset:5808
	s_waitcnt vmcnt(8)
	ds_write_b32 v14, v127 offset:6072
	s_waitcnt vmcnt(7)
	ds_write_b32 v14, v128 offset:6336
	s_waitcnt vmcnt(6)
	ds_write_b32 v14, v129 offset:6600
	s_waitcnt vmcnt(5)
	ds_write_b32 v14, v130 offset:6864
	s_waitcnt vmcnt(4)
	ds_write_b32 v14, v131 offset:7128
	s_waitcnt vmcnt(3)
	ds_write_b32 v14, v132 offset:7392
	s_waitcnt vmcnt(2)
	ds_write_b32 v14, v133 offset:7656
	s_waitcnt vmcnt(1)
	ds_write_b32 v14, v134 offset:7920
	s_waitcnt vmcnt(0)
	ds_write_b32 v14, v135 offset:8184
	s_branch .LBB0_762

; #define LAS __attribute__((address_space(3)))
; DI void cvt_item(const float* W, int ldw, int nvalid, int srccol0, bf16_t* WT, int K, int dstrow0, int k0, LAS float* scr, int lane) {
;     const int n = srccol0 + (lane & 31);
; #pragma unroll 8
;     for (int i = 0; i < 32; ++i) { const int kk = 2 * i + (lane >> 5); scr[kk * 33 + (lane & 31)] = (n < nvalid) ? __builtin_nontemporal_load(W + (size_t)(k0 + kk) * ldw + n) : 0.f; }
.LBB0_789:
	v_mov_b32_e32 v104, 0
	v_mov_b32_e32 v105, 0
	v_mov_b32_e32 v106, 0
	v_mov_b32_e32 v107, 0
	v_mov_b32_e32 v108, 0
	v_mov_b32_e32 v109, 0
	v_mov_b32_e32 v110, 0
	v_mov_b32_e32 v111, 0
	v_mov_b32_e32 v112, 0
	v_mov_b32_e32 v113, 0
	v_mov_b32_e32 v114, 0
	v_mov_b32_e32 v115, 0
	v_mov_b32_e32 v116, 0
	v_mov_b32_e32 v117, 0
	v_mov_b32_e32 v118, 0
	v_mov_b32_e32 v119, 0
	v_mov_b32_e32 v120, 0
	v_mov_b32_e32 v121, 0
	v_mov_b32_e32 v122, 0
	v_mov_b32_e32 v123, 0
	v_mov_b32_e32 v124, 0
	v_mov_b32_e32 v125, 0
	v_mov_b32_e32 v126, 0
	v_mov_b32_e32 v127, 0
	v_mov_b32_e32 v128, 0
	v_mov_b32_e32 v129, 0
	v_mov_b32_e32 v130, 0
	v_mov_b32_e32 v131, 0
	v_mov_b32_e32 v132, 0
	v_mov_b32_e32 v133, 0
	v_mov_b32_e32 v134, 0
	v_mov_b32_e32 v135, 0
	s_and_saveexec_b64 s[10:11], vcc
	v_add_u32_e32 v20, s7, v17
	v_ashrrev_i32_e32 v21, 31, v20
	v_lshlrev_b64 v[20:21], 10, v[20:21]
	v_lshl_add_u64 v[20:21], v[4:5], 0, v[20:21]
	global_load_dword v104, v[20:21], off nt
	v_add3_u32 v20, v17, s7, 2
	v_ashrrev_i32_e32 v21, 31, v20
	v_lshlrev_b64 v[20:21], 10, v[20:21]
	v_lshl_add_u64 v[20:21], v[4:5], 0, v[20:21]
	global_load_dword v105, v[20:21], off nt
	v_add3_u32 v20, v17, s7, 4
	v_ashrrev_i32_e32 v21, 31, v20
	v_lshlrev_b64 v[20:21], 10, v[20:21]
	v_lshl_add_u64 v[20:21], v[4:5], 0, v[20:21]
	global_load_dword v106, v[20:21], off nt
	v_add3_u32 v20, v17, s7, 6
	v_ashrrev_i32_e32 v21, 31, v20
	v_lshlrev_b64 v[20:21], 10, v[20:21]
	v_lshl_add_u64 v[20:21], v[4:5], 0, v[20:21]
	global_load_dword v107, v[20:21], off nt
	v_add3_u32 v20, v17, s7, 8
	v_ashrrev_i32_e32 v21, 31, v20
	v_lshlrev_b64 v[20:21], 10, v[20:21]
	v_lshl_add_u64 v[20:21], v[4:5], 0, v[20:21]
	global_load_dword v108, v[20:21], off nt
	v_add3_u32 v20, v17, s7, 10
	v_ashrrev_i32_e32 v21, 31, v20
	v_lshlrev_b64 v[20:21], 10, v[20:21]
	v_lshl_add_u64 v[20:21], v[4:5], 0, v[20:21]
	global_load_dword v109, v[20:21], off nt
	v_add3_u32 v20, v17, s7, 12
	v_ashrrev_i32_e32 v21, 31, v20
	v_lshlrev_b64 v[20:21], 10, v[20:21]
	v_lshl_add_u64 v[20:21], v[4:5], 0, v[20:21]
	global_load_dword v110, v[20:21], off nt
	v_add3_u32 v20, v17, s7, 14
	v_ashrrev_i32_e32 v21, 31, v20
	v_lshlrev_b64 v[20:21], 10, v[20:21]
	v_lshl_add_u64 v[20:21], v[4:5], 0, v[20:21]
	global_load_dword v111, v[20:21], off nt
	s_add_i32 s7, s7, 16
	v_add_u32_e32 v20, s7, v17
	v_ashrrev_i32_e32 v21, 31, v20
	v_lshlrev_b64 v[20:21], 10, v[20:21]
	v_lshl_add_u64 v[20:21], v[4:5], 0, v[20:21]
	global_load_dword v112, v[20:21], off nt
	v_add3_u32 v20, v17, s7, 2
	v_ashrrev_i32_e32 v21, 31, v20
	v_lshlrev_b64 v[20:21], 10, v[20:21]
	v_lshl_add_u64 v[20:21], v[4:5], 0, v[20:21]
	global_load_dword v113, v[20:21], off nt
	v_add3_u32 v20, v17, s7, 4
	v_ashrrev_i32_e32 v21, 31, v20
	v_lshlrev_b64 v[20:21], 10, v[20:21]
	v_lshl_add_u64 v[20:21], v[4:5], 0, v[20:21]
	global_load_dword v114, v[20:21], off nt
	v_add3_u32 v20, v17, s7, 6
	v_ashrrev_i32_e32 v21, 31, v20
	v_lshlrev_b64 v[20:21], 10, v[20:21]
	v_lshl_add_u64 v[20:21], v[4:5], 0, v[20:21]
	global_load_dword v115, v[20:21], off nt
	v_add3_u32 v20, v17, s7, 8
	v_ashrrev_i32_e32 v21, 31, v20
	v_lshlrev_b64 v[20:21], 10, v[20:21]
	v_lshl_add_u64 v[20:21], v[4:5], 0, v[20:21]
	global_load_dword v116, v[20:21], off nt
	v_add3_u32 v20, v17, s7, 10
	v_ashrrev_i32_e32 v21, 31, v20
	v_lshlrev_b64 v[20:21], 10, v[20:21]
	v_lshl_add_u64 v[20:21], v[4:5], 0, v[20:21]
	global_load_dword v117, v[20:21], off nt
	v_add3_u32 v20, v17, s7, 12
	v_ashrrev_i32_e32 v21, 31, v20
	v_lshlrev_b64 v[20:21], 10, v[20:21]
	v_lshl_add_u64 v[20:21], v[4:5], 0, v[20:21]
	global_load_dword v118, v[20:21], off nt
	v_add3_u32 v20, v17, s7, 14
	v_ashrrev_i32_e32 v21, 31, v20
	v_lshlrev_b64 v[20:21], 10, v[20:21]
	v_lshl_add_u64 v[20:21], v[4:5], 0, v[20:21]
	global_load_dword v119, v[20:21], off nt
	s_add_i32 s7, s7, 16
	v_add_u32_e32 v20, s7, v17
	v_ashrrev_i32_e32 v21, 31, v20
	v_lshlrev_b64 v[20:21], 10, v[20:21]
	v_lshl_add_u64 v[20:21], v[4:5], 0, v[20:21]
	global_load_dword v120, v[20:21], off nt
	v_add3_u32 v20, v17, s7, 2
	v_ashrrev_i32_e32 v21, 31, v20
	v_lshlrev_b64 v[20:21], 10, v[20:21]
	v_lshl_add_u64 v[20:21], v[4:5], 0, v[20:21]
	global_load_dword v121, v[20:21], off nt
	v_add3_u32 v20, v17, s7, 4
	v_ashrrev_i32_e32 v21, 31, v20
	v_lshlrev_b64 v[20:21], 10, v[20:21]
	v_lshl_add_u64 v[20:21], v[4:5], 0, v[20:21]
	global_load_dword v122, v[20:21], off nt
	v_add3_u32 v20, v17, s7, 6
	v_ashrrev_i32_e32 v21, 31, v20
	v_lshlrev_b64 v[20:21], 10, v[20:21]
	v_lshl_add_u64 v[20:21], v[4:5], 0, v[20:21]
	global_load_dword v123, v[20:21], off nt
	v_add3_u32 v20, v17, s7, 8
	v_ashrrev_i32_e32 v21, 31, v20
	v_lshlrev_b64 v[20:21], 10, v[20:21]
	v_lshl_add_u64 v[20:21], v[4:5], 0, v[20:21]
	global_load_dword v124, v[20:21], off nt
	v_add3_u32 v20, v17, s7, 10
	v_ashrrev_i32_e32 v21, 31, v20
	v_lshlrev_b64 v[20:21], 10, v[20:21]
	v_lshl_add_u64 v[20:21], v[4:5], 0, v[20:21]
	global_load_dword v125, v[20:21], off nt
	v_add3_u32 v20, v17, s7, 12
	v_ashrrev_i32_e32 v21, 31, v20
	v_lshlrev_b64 v[20:21], 10, v[20:21]
	v_lshl_add_u64 v[20:21], v[4:5], 0, v[20:21]
	global_load_dword v126, v[20:21], off nt
	v_add3_u32 v20, v17, s7, 14
	v_ashrrev_i32_e32 v21, 31, v20
	v_lshlrev_b64 v[20:21], 10, v[20:21]
	v_lshl_add_u64 v[20:21], v[4:5], 0, v[20:21]
	global_load_dword v127, v[20:21], off nt
	s_add_i32 s7, s7, 16
	v_add_u32_e32 v20, s7, v17
	v_ashrrev_i32_e32 v21, 31, v20
	v_lshlrev_b64 v[20:21], 10, v[20:21]
	v_lshl_add_u64 v[20:21], v[4:5], 0, v[20:21]
	global_load_dword v128, v[20:21], off nt
	v_add3_u32 v20, v17, s7, 2
	v_ashrrev_i32_e32 v21, 31, v20
	v_lshlrev_b64 v[20:21], 10, v[20:21]
	v_lshl_add_u64 v[20:21], v[4:5], 0, v[20:21]
	global_load_dword v129, v[20:21], off nt
	v_add3_u32 v20, v17, s7, 4
	v_ashrrev_i32_e32 v21, 31, v20
	v_lshlrev_b64 v[20:21], 10, v[20:21]
	v_lshl_add_u64 v[20:21], v[4:5], 0, v[20:21]
	global_load_dword v130, v[20:21], off nt
	v_add3_u32 v20, v17, s7, 6
	v_ashrrev_i32_e32 v21, 31, v20
	v_lshlrev_b64 v[20:21], 10, v[20:21]
	v_lshl_add_u64 v[20:21], v[4:5], 0, v[20:21]
	global_load_dword v131, v[20:21], off nt
	v_add3_u32 v20, v17, s7, 8
	v_ashrrev_i32_e32 v21, 31, v20
	v_lshlrev_b64 v[20:21], 10, v[20:21]
	v_lshl_add_u64 v[20:21], v[4:5], 0, v[20:21]
	global_load_dword v132, v[20:21], off nt
	v_add3_u32 v20, v17, s7, 10
	v_ashrrev_i32_e32 v21, 31, v20
	v_lshlrev_b64 v[20:21], 10, v[20:21]
	v_lshl_add_u64 v[20:21], v[4:5], 0, v[20:21]
	global_load_dword v133, v[20:21], off nt
	v_add3_u32 v20, v17, s7, 12
	v_ashrrev_i32_e32 v21, 31, v20
	v_lshlrev_b64 v[20:21], 10, v[20:21]
	v_lshl_add_u64 v[20:21], v[4:5], 0, v[20:21]
	global_load_dword v134, v[20:21], off nt
	v_add3_u32 v20, v17, s7, 14
	v_ashrrev_i32_e32 v21, 31, v20
	v_lshlrev_b64 v[20:21], 10, v[20:21]
	v_lshl_add_u64 v[20:21], v[4:5], 0, v[20:21]
	global_load_dword v135, v[20:21], off nt
	s_add_i32 s7, s7, 16
	s_or_b64 exec, exec, s[10:11]
	s_waitcnt vmcnt(31)
; DI void cvt_item(const float* W, int ldw, int nvalid, int srccol0, bf16_t* WT, int K, int dstrow0, int k0, LAS float* scr, int lane) {
;     ...
;     for (int i = 0; i < 32; ++i) { const int kk = 2 * i + (lane >> 5); scr[kk * 33 + (lane & 31)] = (n < nvalid) ? __builtin_nontemporal_load(W + (size_t)(k0 + kk) * ldw + n) : 0.f; }
;     asm volatile("s_waitcnt lgkmcnt(0)" ::: "memory");
	ds_write_b32 v18, v104
	s_waitcnt vmcnt(30)
	ds_write_b32 v18, v105 offset:264
	s_waitcnt vmcnt(29)
	ds_write_b32 v18, v106 offset:528
	s_waitcnt vmcnt(28)
	ds_write_b32 v18, v107 offset:792
	s_waitcnt vmcnt(27)
	ds_write_b32 v18, v108 offset:1056
	s_waitcnt vmcnt(26)
	ds_write_b32 v18, v109 offset:1320
	s_waitcnt vmcnt(25)
	ds_write_b32 v18, v110 offset:1584
	s_waitcnt vmcnt(24)
	ds_write_b32 v18, v111 offset:1848
	s_waitcnt vmcnt(23)
	ds_write_b32 v18, v112 offset:2112
	s_waitcnt vmcnt(22)
	ds_write_b32 v18, v113 offset:2376
	s_waitcnt vmcnt(21)
	ds_write_b32 v18, v114 offset:2640
	s_waitcnt vmcnt(20)
	ds_write_b32 v18, v115 offset:2904
	s_waitcnt vmcnt(19)
	ds_write_b32 v18, v116 offset:3168
	s_waitcnt vmcnt(18)
	ds_write_b32 v18, v117 offset:3432
	s_waitcnt vmcnt(17)
	ds_write_b32 v18, v118 offset:3696
	s_waitcnt vmcnt(16)
	ds_write_b32 v18, v119 offset:3960
	s_waitcnt vmcnt(15)
	ds_write_b32 v18, v120 offset:4224
	s_waitcnt vmcnt(14)
	ds_write_b32 v18, v121 offset:4488
	s_waitcnt vmcnt(13)
	ds_write_b32 v18, v122 offset:4752
	s_waitcnt vmcnt(12)
	ds_write_b32 v18, v123 offset:5016
	s_waitcnt vmcnt(11)
	ds_write_b32 v18, v124 offset:5280
	s_waitcnt vmcnt(10)
	ds_write_b32 v18, v125 offset:5544
	s_waitcnt vmcnt(9)
	ds_write_b32 v18, v126 offset:5808
	s_waitcnt vmcnt(8)
	ds_write_b32 v18, v127 offset:6072
	s_waitcnt vmcnt(7)
	ds_write_b32 v18, v128 offset:6336
	s_waitcnt vmcnt(6)
	ds_write_b32 v18, v129 offset:6600
	s_waitcnt vmcnt(5)
	ds_write_b32 v18, v130 offset:6864
	s_waitcnt vmcnt(4)
	ds_write_b32 v18, v131 offset:7128
	s_waitcnt vmcnt(3)
	ds_write_b32 v18, v132 offset:7392
	s_waitcnt vmcnt(2)
	ds_write_b32 v18, v133 offset:7656
	s_waitcnt vmcnt(1)
	ds_write_b32 v18, v134 offset:7920
	s_waitcnt vmcnt(0)
	ds_write_b32 v18, v135 offset:8184
	s_branch .LBB0_786

; #define LAS __attribute__((address_space(3)))
; DI void cvt_item(const float* W, int ldw, int nvalid, int srccol0, bf16_t* WT, int K, int dstrow0, int k0, LAS float* scr, int lane) {
;     const int n = srccol0 + (lane & 31);
; #pragma unroll 8
;     for (int i = 0; i < 32; ++i) { const int kk = 2 * i + (lane >> 5); scr[kk * 33 + (lane & 31)] = (n < nvalid) ? __builtin_nontemporal_load(W + (size_t)(k0 + kk) * ldw + n) : 0.f; }
;     asm volatile("s_waitcnt lgkmcnt(0)" ::: "memory");
.LBB0_1425:
	v_mov_b32_e32 v104, 0
	v_mov_b32_e32 v105, 0
	v_mov_b32_e32 v106, 0
	v_mov_b32_e32 v107, 0
	v_mov_b32_e32 v108, 0
	v_mov_b32_e32 v109, 0
	v_mov_b32_e32 v110, 0
	v_mov_b32_e32 v111, 0
	v_mov_b32_e32 v112, 0
	v_mov_b32_e32 v113, 0
	v_mov_b32_e32 v114, 0
	v_mov_b32_e32 v115, 0
	v_mov_b32_e32 v116, 0
	v_mov_b32_e32 v117, 0
	v_mov_b32_e32 v118, 0
	v_mov_b32_e32 v119, 0
	v_mov_b32_e32 v120, 0
	v_mov_b32_e32 v121, 0
	v_mov_b32_e32 v122, 0
	v_mov_b32_e32 v123, 0
	v_mov_b32_e32 v124, 0
	v_mov_b32_e32 v125, 0
	v_mov_b32_e32 v126, 0
	v_mov_b32_e32 v127, 0
	v_mov_b32_e32 v128, 0
	v_mov_b32_e32 v129, 0
	v_mov_b32_e32 v130, 0
	v_mov_b32_e32 v131, 0
	v_mov_b32_e32 v132, 0
	v_mov_b32_e32 v133, 0
	v_mov_b32_e32 v134, 0
	v_mov_b32_e32 v135, 0
	s_and_saveexec_b64 s[12:13], vcc
	v_lshl_add_u64 v[42:43], v[20:21], 0, s[10:11]
	global_load_dword v104, v[42:43], off nt
	v_lshl_add_u64 v[40:41], v[14:15], 0, s[10:11]
	global_load_dword v105, v[40:41], off nt
	v_lshl_add_u64 v[42:43], v[12:13], 0, s[10:11]
	global_load_dword v106, v[42:43], off nt
	v_lshl_add_u64 v[40:41], v[10:11], 0, s[10:11]
	global_load_dword v107, v[40:41], off nt
	v_lshl_add_u64 v[42:43], v[8:9], 0, s[10:11]
	global_load_dword v108, v[42:43], off nt
	v_lshl_add_u64 v[40:41], v[6:7], 0, s[10:11]
	global_load_dword v109, v[40:41], off nt
	v_lshl_add_u64 v[42:43], v[4:5], 0, s[10:11]
	global_load_dword v110, v[42:43], off nt
	v_lshl_add_u64 v[40:41], v[2:3], 0, s[10:11]
	global_load_dword v111, v[40:41], off nt
	s_add_u32 s10, s10, 0x58000
	s_addc_u32 s11, s11, 0
	v_lshl_add_u64 v[42:43], v[20:21], 0, s[10:11]
	global_load_dword v112, v[42:43], off nt
	v_lshl_add_u64 v[40:41], v[14:15], 0, s[10:11]
	global_load_dword v113, v[40:41], off nt
	v_lshl_add_u64 v[42:43], v[12:13], 0, s[10:11]
	global_load_dword v114, v[42:43], off nt
	v_lshl_add_u64 v[40:41], v[10:11], 0, s[10:11]
	global_load_dword v115, v[40:41], off nt
	v_lshl_add_u64 v[42:43], v[8:9], 0, s[10:11]
	global_load_dword v116, v[42:43], off nt
	v_lshl_add_u64 v[40:41], v[6:7], 0, s[10:11]
	global_load_dword v117, v[40:41], off nt
	v_lshl_add_u64 v[42:43], v[4:5], 0, s[10:11]
	global_load_dword v118, v[42:43], off nt
	v_lshl_add_u64 v[40:41], v[2:3], 0, s[10:11]
	global_load_dword v119, v[40:41], off nt
	s_add_u32 s10, s10, 0x58000
	s_addc_u32 s11, s11, 0
	v_lshl_add_u64 v[42:43], v[20:21], 0, s[10:11]
	global_load_dword v120, v[42:43], off nt
	v_lshl_add_u64 v[40:41], v[14:15], 0, s[10:11]
	global_load_dword v121, v[40:41], off nt
	v_lshl_add_u64 v[42:43], v[12:13], 0, s[10:11]
	global_load_dword v122, v[42:43], off nt
	v_lshl_add_u64 v[40:41], v[10:11], 0, s[10:11]
	global_load_dword v123, v[40:41], off nt
	v_lshl_add_u64 v[42:43], v[8:9], 0, s[10:11]
	global_load_dword v124, v[42:43], off nt
	v_lshl_add_u64 v[40:41], v[6:7], 0, s[10:11]
	global_load_dword v125, v[40:41], off nt
	v_lshl_add_u64 v[42:43], v[4:5], 0, s[10:11]
	global_load_dword v126, v[42:43], off nt
	v_lshl_add_u64 v[40:41], v[2:3], 0, s[10:11]
	global_load_dword v127, v[40:41], off nt
	s_add_u32 s10, s10, 0x58000
	s_addc_u32 s11, s11, 0
	v_lshl_add_u64 v[42:43], v[20:21], 0, s[10:11]
	global_load_dword v128, v[42:43], off nt
	v_lshl_add_u64 v[40:41], v[14:15], 0, s[10:11]
	global_load_dword v129, v[40:41], off nt
	v_lshl_add_u64 v[42:43], v[12:13], 0, s[10:11]
	global_load_dword v130, v[42:43], off nt
	v_lshl_add_u64 v[40:41], v[10:11], 0, s[10:11]
	global_load_dword v131, v[40:41], off nt
	v_lshl_add_u64 v[42:43], v[8:9], 0, s[10:11]
	global_load_dword v132, v[42:43], off nt
	v_lshl_add_u64 v[40:41], v[6:7], 0, s[10:11]
	global_load_dword v133, v[40:41], off nt
	v_lshl_add_u64 v[42:43], v[4:5], 0, s[10:11]
	global_load_dword v134, v[42:43], off nt
	v_lshl_add_u64 v[40:41], v[2:3], 0, s[10:11]
	global_load_dword v135, v[40:41], off nt
	s_add_u32 s10, s10, 0x58000
	s_addc_u32 s11, s11, 0
	s_or_b64 exec, exec, s[12:13]
	s_waitcnt vmcnt(31)
	ds_write_b32 v39, v104
	s_waitcnt vmcnt(30)
	ds_write_b32 v39, v105 offset:264
	s_waitcnt vmcnt(29)
	ds_write_b32 v39, v106 offset:528
	s_waitcnt vmcnt(28)
	ds_write_b32 v39, v107 offset:792
	s_waitcnt vmcnt(27)
	ds_write_b32 v39, v108 offset:1056
	s_waitcnt vmcnt(26)
	ds_write_b32 v39, v109 offset:1320
	s_waitcnt vmcnt(25)
	ds_write_b32 v39, v110 offset:1584
	s_waitcnt vmcnt(24)
	ds_write_b32 v39, v111 offset:1848
	s_waitcnt vmcnt(23)
	ds_write_b32 v39, v112 offset:2112
	s_waitcnt vmcnt(22)
	ds_write_b32 v39, v113 offset:2376
	s_waitcnt vmcnt(21)
	ds_write_b32 v39, v114 offset:2640
	s_waitcnt vmcnt(20)
	ds_write_b32 v39, v115 offset:2904
	s_waitcnt vmcnt(19)
	ds_write_b32 v39, v116 offset:3168
	s_waitcnt vmcnt(18)
	ds_write_b32 v39, v117 offset:3432
	s_waitcnt vmcnt(17)
	ds_write_b32 v39, v118 offset:3696
	s_waitcnt vmcnt(16)
	ds_write_b32 v39, v119 offset:3960
	s_waitcnt vmcnt(15)
	ds_write_b32 v39, v120 offset:4224
	s_waitcnt vmcnt(14)
	ds_write_b32 v39, v121 offset:4488
	s_waitcnt vmcnt(13)
	ds_write_b32 v39, v122 offset:4752
	s_waitcnt vmcnt(12)
	ds_write_b32 v39, v123 offset:5016
	s_waitcnt vmcnt(11)
	ds_write_b32 v39, v124 offset:5280
	s_waitcnt vmcnt(10)
	ds_write_b32 v39, v125 offset:5544
	s_waitcnt vmcnt(9)
	ds_write_b32 v39, v126 offset:5808
	s_waitcnt vmcnt(8)
	ds_write_b32 v39, v127 offset:6072
	s_waitcnt vmcnt(7)
	ds_write_b32 v39, v128 offset:6336
	s_waitcnt vmcnt(6)
	ds_write_b32 v39, v129 offset:6600
	s_waitcnt vmcnt(5)
	ds_write_b32 v39, v130 offset:6864
	s_waitcnt vmcnt(4)
	ds_write_b32 v39, v131 offset:7128
	s_waitcnt vmcnt(3)
	ds_write_b32 v39, v132 offset:7392
	s_waitcnt vmcnt(2)
	ds_write_b32 v39, v133 offset:7656
	s_waitcnt vmcnt(1)
	ds_write_b32 v39, v134 offset:7920
	s_waitcnt vmcnt(0)
	ds_write_b32 v39, v135 offset:8184
	s_branch .LBB0_1422

; DI void cvt_item(const float* W, int ldw, int nvalid, int srccol0, bf16_t* WT, int K, int dstrow0, int k0, LAS float* scr, int lane) {
;     const int n = srccol0 + (lane & 31);
; #pragma unroll 8
;     for (int i = 0; i < 32; ++i) { const int kk = 2 * i + (lane >> 5); scr[kk * 33 + (lane & 31)] = (n < nvalid) ? __builtin_nontemporal_load(W + (size_t)(k0 + kk) * ldw + n) : 0.f; }
;     asm volatile("s_waitcnt lgkmcnt(0)" ::: "memory");
.LBB0_1446:
	v_mov_b32_e32 v104, 0
	v_mov_b32_e32 v105, 0
	v_mov_b32_e32 v106, 0
	v_mov_b32_e32 v107, 0
	v_mov_b32_e32 v108, 0
	v_mov_b32_e32 v109, 0
	v_mov_b32_e32 v110, 0
	v_mov_b32_e32 v111, 0
	v_mov_b32_e32 v112, 0
	v_mov_b32_e32 v113, 0
	v_mov_b32_e32 v114, 0
	v_mov_b32_e32 v115, 0
	v_mov_b32_e32 v116, 0
	v_mov_b32_e32 v117, 0
	v_mov_b32_e32 v118, 0
	v_mov_b32_e32 v119, 0
	v_mov_b32_e32 v120, 0
	v_mov_b32_e32 v121, 0
	v_mov_b32_e32 v122, 0
	v_mov_b32_e32 v123, 0
	v_mov_b32_e32 v124, 0
	v_mov_b32_e32 v125, 0
	v_mov_b32_e32 v126, 0
	v_mov_b32_e32 v127, 0
	v_mov_b32_e32 v128, 0
	v_mov_b32_e32 v129, 0
	v_mov_b32_e32 v130, 0
	v_mov_b32_e32 v131, 0
	v_mov_b32_e32 v132, 0
	v_mov_b32_e32 v133, 0
	v_mov_b32_e32 v134, 0
	v_mov_b32_e32 v135, 0
	s_and_saveexec_b64 s[10:11], vcc
	v_add_u32_e32 v10, s7, v6
	v_ashrrev_i32_e32 v11, 31, v10
	v_lshlrev_b64 v[10:11], 12, v[10:11]
	v_lshl_add_u64 v[10:11], v[2:3], 0, v[10:11]
	global_load_dword v104, v[10:11], off nt
	v_add3_u32 v8, v6, s7, 2
	v_ashrrev_i32_e32 v9, 31, v8
	v_lshlrev_b64 v[8:9], 12, v[8:9]
	v_lshl_add_u64 v[8:9], v[2:3], 0, v[8:9]
	global_load_dword v105, v[8:9], off nt
	v_add3_u32 v10, v6, s7, 4
	v_ashrrev_i32_e32 v11, 31, v10
	v_lshlrev_b64 v[10:11], 12, v[10:11]
	v_lshl_add_u64 v[10:11], v[2:3], 0, v[10:11]
	global_load_dword v106, v[10:11], off nt
	v_add3_u32 v8, v6, s7, 6
	v_ashrrev_i32_e32 v9, 31, v8
	v_lshlrev_b64 v[8:9], 12, v[8:9]
	v_lshl_add_u64 v[8:9], v[2:3], 0, v[8:9]
	global_load_dword v107, v[8:9], off nt
	v_add3_u32 v10, v6, s7, 8
	v_ashrrev_i32_e32 v11, 31, v10
	v_lshlrev_b64 v[10:11], 12, v[10:11]
	v_lshl_add_u64 v[10:11], v[2:3], 0, v[10:11]
	global_load_dword v108, v[10:11], off nt
	v_add3_u32 v8, v6, s7, 10
	v_ashrrev_i32_e32 v9, 31, v8
	v_lshlrev_b64 v[8:9], 12, v[8:9]
	v_lshl_add_u64 v[8:9], v[2:3], 0, v[8:9]
	global_load_dword v109, v[8:9], off nt
	v_add3_u32 v10, v6, s7, 12
	v_ashrrev_i32_e32 v11, 31, v10
	v_lshlrev_b64 v[10:11], 12, v[10:11]
	v_lshl_add_u64 v[10:11], v[2:3], 0, v[10:11]
	global_load_dword v110, v[10:11], off nt
	v_add3_u32 v8, v6, s7, 14
	v_ashrrev_i32_e32 v9, 31, v8
	v_lshlrev_b64 v[8:9], 12, v[8:9]
	v_lshl_add_u64 v[8:9], v[2:3], 0, v[8:9]
	global_load_dword v111, v[8:9], off nt
	s_add_i32 s7, s7, 16
	v_add_u32_e32 v10, s7, v6
	v_ashrrev_i32_e32 v11, 31, v10
	v_lshlrev_b64 v[10:11], 12, v[10:11]
	v_lshl_add_u64 v[10:11], v[2:3], 0, v[10:11]
	global_load_dword v112, v[10:11], off nt
	v_add3_u32 v8, v6, s7, 2
	v_ashrrev_i32_e32 v9, 31, v8
	v_lshlrev_b64 v[8:9], 12, v[8:9]
	v_lshl_add_u64 v[8:9], v[2:3], 0, v[8:9]
	global_load_dword v113, v[8:9], off nt
	v_add3_u32 v10, v6, s7, 4
	v_ashrrev_i32_e32 v11, 31, v10
	v_lshlrev_b64 v[10:11], 12, v[10:11]
	v_lshl_add_u64 v[10:11], v[2:3], 0, v[10:11]
	global_load_dword v114, v[10:11], off nt
	v_add3_u32 v8, v6, s7, 6
	v_ashrrev_i32_e32 v9, 31, v8
	v_lshlrev_b64 v[8:9], 12, v[8:9]
	v_lshl_add_u64 v[8:9], v[2:3], 0, v[8:9]
	global_load_dword v115, v[8:9], off nt
	v_add3_u32 v10, v6, s7, 8
	v_ashrrev_i32_e32 v11, 31, v10
	v_lshlrev_b64 v[10:11], 12, v[10:11]
	v_lshl_add_u64 v[10:11], v[2:3], 0, v[10:11]
	global_load_dword v116, v[10:11], off nt
	v_add3_u32 v8, v6, s7, 10
	v_ashrrev_i32_e32 v9, 31, v8
	v_lshlrev_b64 v[8:9], 12, v[8:9]
	v_lshl_add_u64 v[8:9], v[2:3], 0, v[8:9]
	global_load_dword v117, v[8:9], off nt
	v_add3_u32 v10, v6, s7, 12
	v_ashrrev_i32_e32 v11, 31, v10
	v_lshlrev_b64 v[10:11], 12, v[10:11]
	v_lshl_add_u64 v[10:11], v[2:3], 0, v[10:11]
	global_load_dword v118, v[10:11], off nt
	v_add3_u32 v8, v6, s7, 14
	v_ashrrev_i32_e32 v9, 31, v8
	v_lshlrev_b64 v[8:9], 12, v[8:9]
	v_lshl_add_u64 v[8:9], v[2:3], 0, v[8:9]
	global_load_dword v119, v[8:9], off nt
	s_add_i32 s7, s7, 16
	v_add_u32_e32 v10, s7, v6
	v_ashrrev_i32_e32 v11, 31, v10
	v_lshlrev_b64 v[10:11], 12, v[10:11]
	v_lshl_add_u64 v[10:11], v[2:3], 0, v[10:11]
	global_load_dword v120, v[10:11], off nt
	v_add3_u32 v8, v6, s7, 2
	v_ashrrev_i32_e32 v9, 31, v8
	v_lshlrev_b64 v[8:9], 12, v[8:9]
	v_lshl_add_u64 v[8:9], v[2:3], 0, v[8:9]
	global_load_dword v121, v[8:9], off nt
	v_add3_u32 v10, v6, s7, 4
	v_ashrrev_i32_e32 v11, 31, v10
	v_lshlrev_b64 v[10:11], 12, v[10:11]
	v_lshl_add_u64 v[10:11], v[2:3], 0, v[10:11]
	global_load_dword v122, v[10:11], off nt
	v_add3_u32 v8, v6, s7, 6
	v_ashrrev_i32_e32 v9, 31, v8
	v_lshlrev_b64 v[8:9], 12, v[8:9]
	v_lshl_add_u64 v[8:9], v[2:3], 0, v[8:9]
	global_load_dword v123, v[8:9], off nt
	v_add3_u32 v10, v6, s7, 8
	v_ashrrev_i32_e32 v11, 31, v10
	v_lshlrev_b64 v[10:11], 12, v[10:11]
	v_lshl_add_u64 v[10:11], v[2:3], 0, v[10:11]
	global_load_dword v124, v[10:11], off nt
	v_add3_u32 v8, v6, s7, 10
	v_ashrrev_i32_e32 v9, 31, v8
	v_lshlrev_b64 v[8:9], 12, v[8:9]
	v_lshl_add_u64 v[8:9], v[2:3], 0, v[8:9]
	global_load_dword v125, v[8:9], off nt
	v_add3_u32 v10, v6, s7, 12
	v_ashrrev_i32_e32 v11, 31, v10
	v_lshlrev_b64 v[10:11], 12, v[10:11]
	v_lshl_add_u64 v[10:11], v[2:3], 0, v[10:11]
	global_load_dword v126, v[10:11], off nt
	v_add3_u32 v8, v6, s7, 14
	v_ashrrev_i32_e32 v9, 31, v8
	v_lshlrev_b64 v[8:9], 12, v[8:9]
	v_lshl_add_u64 v[8:9], v[2:3], 0, v[8:9]
	global_load_dword v127, v[8:9], off nt
	s_add_i32 s7, s7, 16
	v_add_u32_e32 v10, s7, v6
	v_ashrrev_i32_e32 v11, 31, v10
	v_lshlrev_b64 v[10:11], 12, v[10:11]
	v_lshl_add_u64 v[10:11], v[2:3], 0, v[10:11]
	global_load_dword v128, v[10:11], off nt
	v_add3_u32 v8, v6, s7, 2
	v_ashrrev_i32_e32 v9, 31, v8
	v_lshlrev_b64 v[8:9], 12, v[8:9]
	v_lshl_add_u64 v[8:9], v[2:3], 0, v[8:9]
	global_load_dword v129, v[8:9], off nt
	v_add3_u32 v10, v6, s7, 4
	v_ashrrev_i32_e32 v11, 31, v10
	v_lshlrev_b64 v[10:11], 12, v[10:11]
	v_lshl_add_u64 v[10:11], v[2:3], 0, v[10:11]
	global_load_dword v130, v[10:11], off nt
	v_add3_u32 v8, v6, s7, 6
	v_ashrrev_i32_e32 v9, 31, v8
	v_lshlrev_b64 v[8:9], 12, v[8:9]
	v_lshl_add_u64 v[8:9], v[2:3], 0, v[8:9]
	global_load_dword v131, v[8:9], off nt
	v_add3_u32 v10, v6, s7, 8
	v_ashrrev_i32_e32 v11, 31, v10
	v_lshlrev_b64 v[10:11], 12, v[10:11]
	v_lshl_add_u64 v[10:11], v[2:3], 0, v[10:11]
	global_load_dword v132, v[10:11], off nt
	v_add3_u32 v8, v6, s7, 10
	v_ashrrev_i32_e32 v9, 31, v8
	v_lshlrev_b64 v[8:9], 12, v[8:9]
	v_lshl_add_u64 v[8:9], v[2:3], 0, v[8:9]
	global_load_dword v133, v[8:9], off nt
	v_add3_u32 v10, v6, s7, 12
	v_ashrrev_i32_e32 v11, 31, v10
	v_lshlrev_b64 v[10:11], 12, v[10:11]
	v_lshl_add_u64 v[10:11], v[2:3], 0, v[10:11]
	global_load_dword v134, v[10:11], off nt
	v_add3_u32 v8, v6, s7, 14
	v_ashrrev_i32_e32 v9, 31, v8
	v_lshlrev_b64 v[8:9], 12, v[8:9]
	v_lshl_add_u64 v[8:9], v[2:3], 0, v[8:9]
	global_load_dword v135, v[8:9], off nt
	s_add_i32 s7, s7, 16
	s_or_b64 exec, exec, s[10:11]
	s_waitcnt vmcnt(31)
; DI void cvt_item(const float* W, int ldw, int nvalid, int srccol0, bf16_t* WT, int K, int dstrow0, int k0, LAS float* scr, int lane) {
;     const int n = srccol0 + (lane & 31);
; #pragma unroll 8
;     for (int i = 0; i < 32; ++i) { const int kk = 2 * i + (lane >> 5); scr[kk * 33 + (lane & 31)] = (n < nvalid) ? __builtin_nontemporal_load(W + (size_t)(k0 + kk) * ldw + n) : 0.f; }
;     asm volatile("s_waitcnt lgkmcnt(0)" ::: "memory");
	ds_write_b32 v7, v104
	s_waitcnt vmcnt(30)
	ds_write_b32 v7, v105 offset:264
	s_waitcnt vmcnt(29)
	ds_write_b32 v7, v106 offset:528
	s_waitcnt vmcnt(28)
	ds_write_b32 v7, v107 offset:792
	s_waitcnt vmcnt(27)
	ds_write_b32 v7, v108 offset:1056
	s_waitcnt vmcnt(26)
	ds_write_b32 v7, v109 offset:1320
	s_waitcnt vmcnt(25)
	ds_write_b32 v7, v110 offset:1584
	s_waitcnt vmcnt(24)
	ds_write_b32 v7, v111 offset:1848
	s_waitcnt vmcnt(23)
	ds_write_b32 v7, v112 offset:2112
	s_waitcnt vmcnt(22)
	ds_write_b32 v7, v113 offset:2376
	s_waitcnt vmcnt(21)
	ds_write_b32 v7, v114 offset:2640
	s_waitcnt vmcnt(20)
	ds_write_b32 v7, v115 offset:2904
	s_waitcnt vmcnt(19)
	ds_write_b32 v7, v116 offset:3168
	s_waitcnt vmcnt(18)
	ds_write_b32 v7, v117 offset:3432
	s_waitcnt vmcnt(17)
	ds_write_b32 v7, v118 offset:3696
	s_waitcnt vmcnt(16)
	ds_write_b32 v7, v119 offset:3960
	s_waitcnt vmcnt(15)
	ds_write_b32 v7, v120 offset:4224
	s_waitcnt vmcnt(14)
	ds_write_b32 v7, v121 offset:4488
	s_waitcnt vmcnt(13)
	ds_write_b32 v7, v122 offset:4752
	s_waitcnt vmcnt(12)
	ds_write_b32 v7, v123 offset:5016
	s_waitcnt vmcnt(11)
	ds_write_b32 v7, v124 offset:5280
	s_waitcnt vmcnt(10)
	ds_write_b32 v7, v125 offset:5544
	s_waitcnt vmcnt(9)
	ds_write_b32 v7, v126 offset:5808
	s_waitcnt vmcnt(8)
	ds_write_b32 v7, v127 offset:6072
	s_waitcnt vmcnt(7)
	ds_write_b32 v7, v128 offset:6336
	s_waitcnt vmcnt(6)
	ds_write_b32 v7, v129 offset:6600
	s_waitcnt vmcnt(5)
	ds_write_b32 v7, v130 offset:6864
	s_waitcnt vmcnt(4)
	ds_write_b32 v7, v131 offset:7128
	s_waitcnt vmcnt(3)
	ds_write_b32 v7, v132 offset:7392
	s_waitcnt vmcnt(2)
	ds_write_b32 v7, v133 offset:7656
	s_waitcnt vmcnt(1)
	ds_write_b32 v7, v134 offset:7920
	s_waitcnt vmcnt(0)
	ds_write_b32 v7, v135 offset:8184
	s_branch .LBB0_1443

; DI void cvt_item(const float* W, int ldw, int nvalid, int srccol0, bf16_t* WT, int K, int dstrow0, int k0, LAS float* scr, int lane) {
;     const int n = srccol0 + (lane & 31);
; #pragma unroll 8
;     for (int i = 0; i < 32; ++i) { const int kk = 2 * i + (lane >> 5); scr[kk * 33 + (lane & 31)] = (n < nvalid) ? __builtin_nontemporal_load(W + (size_t)(k0 + kk) * ldw + n) : 0.f; }
;     asm volatile("s_waitcnt lgkmcnt(0)" ::: "memory");
.LBB0_1473:
	v_mov_b32_e32 v104, 0
	v_mov_b32_e32 v105, 0
	v_mov_b32_e32 v106, 0
	v_mov_b32_e32 v107, 0
	v_mov_b32_e32 v108, 0
	v_mov_b32_e32 v109, 0
	v_mov_b32_e32 v110, 0
	v_mov_b32_e32 v111, 0
	v_mov_b32_e32 v112, 0
	v_mov_b32_e32 v113, 0
	v_mov_b32_e32 v114, 0
	v_mov_b32_e32 v115, 0
	v_mov_b32_e32 v116, 0
	v_mov_b32_e32 v117, 0
	v_mov_b32_e32 v118, 0
	v_mov_b32_e32 v119, 0
	v_mov_b32_e32 v120, 0
	v_mov_b32_e32 v121, 0
	v_mov_b32_e32 v122, 0
	v_mov_b32_e32 v123, 0
	v_mov_b32_e32 v124, 0
	v_mov_b32_e32 v125, 0
	v_mov_b32_e32 v126, 0
	v_mov_b32_e32 v127, 0
	v_mov_b32_e32 v128, 0
	v_mov_b32_e32 v129, 0
	v_mov_b32_e32 v130, 0
	v_mov_b32_e32 v131, 0
	v_mov_b32_e32 v132, 0
	v_mov_b32_e32 v133, 0
	v_mov_b32_e32 v134, 0
	v_mov_b32_e32 v135, 0
	s_and_saveexec_b64 s[12:13], vcc
	v_lshl_add_u64 v[42:43], v[20:21], 0, s[10:11]
	global_load_dword v104, v[42:43], off nt
	v_lshl_add_u64 v[40:41], v[14:15], 0, s[10:11]
	global_load_dword v105, v[40:41], off nt
	v_lshl_add_u64 v[42:43], v[12:13], 0, s[10:11]
	global_load_dword v106, v[42:43], off nt
	v_lshl_add_u64 v[40:41], v[10:11], 0, s[10:11]
	global_load_dword v107, v[40:41], off nt
	v_lshl_add_u64 v[42:43], v[8:9], 0, s[10:11]
	global_load_dword v108, v[42:43], off nt
	v_lshl_add_u64 v[40:41], v[6:7], 0, s[10:11]
	global_load_dword v109, v[40:41], off nt
	v_lshl_add_u64 v[42:43], v[4:5], 0, s[10:11]
	global_load_dword v110, v[42:43], off nt
	v_lshl_add_u64 v[40:41], v[2:3], 0, s[10:11]
	global_load_dword v111, v[40:41], off nt
	s_add_u32 s10, s10, 0x40400
	s_addc_u32 s11, s11, 0
	v_lshl_add_u64 v[42:43], v[20:21], 0, s[10:11]
	global_load_dword v112, v[42:43], off nt
	v_lshl_add_u64 v[40:41], v[14:15], 0, s[10:11]
	global_load_dword v113, v[40:41], off nt
	v_lshl_add_u64 v[42:43], v[12:13], 0, s[10:11]
	global_load_dword v114, v[42:43], off nt
	v_lshl_add_u64 v[40:41], v[10:11], 0, s[10:11]
	global_load_dword v115, v[40:41], off nt
	v_lshl_add_u64 v[42:43], v[8:9], 0, s[10:11]
	global_load_dword v116, v[42:43], off nt
	v_lshl_add_u64 v[40:41], v[6:7], 0, s[10:11]
	global_load_dword v117, v[40:41], off nt
	v_lshl_add_u64 v[42:43], v[4:5], 0, s[10:11]
	global_load_dword v118, v[42:43], off nt
	v_lshl_add_u64 v[40:41], v[2:3], 0, s[10:11]
	global_load_dword v119, v[40:41], off nt
	s_add_u32 s10, s10, 0x40400
	s_addc_u32 s11, s11, 0
	v_lshl_add_u64 v[42:43], v[20:21], 0, s[10:11]
	global_load_dword v120, v[42:43], off nt
	v_lshl_add_u64 v[40:41], v[14:15], 0, s[10:11]
	global_load_dword v121, v[40:41], off nt
	v_lshl_add_u64 v[42:43], v[12:13], 0, s[10:11]
	global_load_dword v122, v[42:43], off nt
	v_lshl_add_u64 v[40:41], v[10:11], 0, s[10:11]
	global_load_dword v123, v[40:41], off nt
	v_lshl_add_u64 v[42:43], v[8:9], 0, s[10:11]
	global_load_dword v124, v[42:43], off nt
	v_lshl_add_u64 v[40:41], v[6:7], 0, s[10:11]
	global_load_dword v125, v[40:41], off nt
	v_lshl_add_u64 v[42:43], v[4:5], 0, s[10:11]
	global_load_dword v126, v[42:43], off nt
	v_lshl_add_u64 v[40:41], v[2:3], 0, s[10:11]
	global_load_dword v127, v[40:41], off nt
	s_add_u32 s10, s10, 0x40400
	s_addc_u32 s11, s11, 0
	v_lshl_add_u64 v[42:43], v[20:21], 0, s[10:11]
	global_load_dword v128, v[42:43], off nt
	v_lshl_add_u64 v[40:41], v[14:15], 0, s[10:11]
	global_load_dword v129, v[40:41], off nt
	v_lshl_add_u64 v[42:43], v[12:13], 0, s[10:11]
	global_load_dword v130, v[42:43], off nt
	v_lshl_add_u64 v[40:41], v[10:11], 0, s[10:11]
	global_load_dword v131, v[40:41], off nt
	v_lshl_add_u64 v[42:43], v[8:9], 0, s[10:11]
	global_load_dword v132, v[42:43], off nt
	v_lshl_add_u64 v[40:41], v[6:7], 0, s[10:11]
	global_load_dword v133, v[40:41], off nt
	v_lshl_add_u64 v[42:43], v[4:5], 0, s[10:11]
	global_load_dword v134, v[42:43], off nt
	v_lshl_add_u64 v[40:41], v[2:3], 0, s[10:11]
	global_load_dword v135, v[40:41], off nt
	s_add_u32 s10, s10, 0x40400
	s_addc_u32 s11, s11, 0
	s_or_b64 exec, exec, s[12:13]
	s_waitcnt vmcnt(31)
	ds_write_b32 v39, v104
	s_waitcnt vmcnt(30)
	ds_write_b32 v39, v105 offset:264
	s_waitcnt vmcnt(29)
	ds_write_b32 v39, v106 offset:528
	s_waitcnt vmcnt(28)
	ds_write_b32 v39, v107 offset:792
	s_waitcnt vmcnt(27)
	ds_write_b32 v39, v108 offset:1056
	s_waitcnt vmcnt(26)
	ds_write_b32 v39, v109 offset:1320
	s_waitcnt vmcnt(25)
	ds_write_b32 v39, v110 offset:1584
	s_waitcnt vmcnt(24)
	ds_write_b32 v39, v111 offset:1848
	s_waitcnt vmcnt(23)
	ds_write_b32 v39, v112 offset:2112
	s_waitcnt vmcnt(22)
	ds_write_b32 v39, v113 offset:2376
	s_waitcnt vmcnt(21)
	ds_write_b32 v39, v114 offset:2640
	s_waitcnt vmcnt(20)
	ds_write_b32 v39, v115 offset:2904
	s_waitcnt vmcnt(19)
	ds_write_b32 v39, v116 offset:3168
	s_waitcnt vmcnt(18)
	ds_write_b32 v39, v117 offset:3432
	s_waitcnt vmcnt(17)
	ds_write_b32 v39, v118 offset:3696
	s_waitcnt vmcnt(16)
	ds_write_b32 v39, v119 offset:3960
	s_waitcnt vmcnt(15)
	ds_write_b32 v39, v120 offset:4224
	s_waitcnt vmcnt(14)
	ds_write_b32 v39, v121 offset:4488
	s_waitcnt vmcnt(13)
	ds_write_b32 v39, v122 offset:4752
	s_waitcnt vmcnt(12)
	ds_write_b32 v39, v123 offset:5016
	s_waitcnt vmcnt(11)
	ds_write_b32 v39, v124 offset:5280
	s_waitcnt vmcnt(10)
	ds_write_b32 v39, v125 offset:5544
	s_waitcnt vmcnt(9)
	ds_write_b32 v39, v126 offset:5808
	s_waitcnt vmcnt(8)
	ds_write_b32 v39, v127 offset:6072
	s_waitcnt vmcnt(7)
	ds_write_b32 v39, v128 offset:6336
	s_waitcnt vmcnt(6)
	ds_write_b32 v39, v129 offset:6600
	s_waitcnt vmcnt(5)
	ds_write_b32 v39, v130 offset:6864
	s_waitcnt vmcnt(4)
	ds_write_b32 v39, v131 offset:7128
	s_waitcnt vmcnt(3)
	ds_write_b32 v39, v132 offset:7392
	s_waitcnt vmcnt(2)
	ds_write_b32 v39, v133 offset:7656
	s_waitcnt vmcnt(1)
	ds_write_b32 v39, v134 offset:7920
	s_waitcnt vmcnt(0)
	ds_write_b32 v39, v135 offset:8184
	s_branch .LBB0_1470

; DI void cvt_item(const float* W, int ldw, int nvalid, int srccol0, bf16_t* WT, int K, int dstrow0, int k0, LAS float* scr, int lane) {
;     const int n = srccol0 + (lane & 31);
; #pragma unroll 8
;     for (int i = 0; i < 32; ++i) { const int kk = 2 * i + (lane >> 5); scr[kk * 33 + (lane & 31)] = (n < nvalid) ? __builtin_nontemporal_load(W + (size_t)(k0 + kk) * ldw + n) : 0.f; }
;     asm volatile("s_waitcnt lgkmcnt(0)" ::: "memory");
.LBB0_1520:
	v_mov_b32_e32 v104, 0
	v_mov_b32_e32 v105, 0
	v_mov_b32_e32 v106, 0
	v_mov_b32_e32 v107, 0
	v_mov_b32_e32 v108, 0
	v_mov_b32_e32 v109, 0
	v_mov_b32_e32 v110, 0
	v_mov_b32_e32 v111, 0
	v_mov_b32_e32 v112, 0
	v_mov_b32_e32 v113, 0
	v_mov_b32_e32 v114, 0
	v_mov_b32_e32 v115, 0
	v_mov_b32_e32 v116, 0
	v_mov_b32_e32 v117, 0
	v_mov_b32_e32 v118, 0
	v_mov_b32_e32 v119, 0
	v_mov_b32_e32 v120, 0
	v_mov_b32_e32 v121, 0
	v_mov_b32_e32 v122, 0
	v_mov_b32_e32 v123, 0
	v_mov_b32_e32 v124, 0
	v_mov_b32_e32 v125, 0
	v_mov_b32_e32 v126, 0
	v_mov_b32_e32 v127, 0
	v_mov_b32_e32 v128, 0
	v_mov_b32_e32 v129, 0
	v_mov_b32_e32 v130, 0
	v_mov_b32_e32 v131, 0
	v_mov_b32_e32 v132, 0
	v_mov_b32_e32 v133, 0
	v_mov_b32_e32 v134, 0
	v_mov_b32_e32 v135, 0
	s_and_saveexec_b64 s[6:7], vcc
	v_add_u32_e32 v9, s5, v6
	v_mad_i64_i32 v[10:11], s[12:13], v9, s83, v[2:3]
	global_load_dword v104, v[10:11], off nt
	v_add3_u32 v8, v6, s5, 2
	v_mad_i64_i32 v[8:9], s[12:13], v8, s83, v[2:3]
	global_load_dword v105, v[8:9], off nt
	v_add3_u32 v9, v6, s5, 4
	v_mad_i64_i32 v[10:11], s[12:13], v9, s83, v[2:3]
	global_load_dword v106, v[10:11], off nt
	v_add3_u32 v8, v6, s5, 6
	v_mad_i64_i32 v[8:9], s[12:13], v8, s83, v[2:3]
	global_load_dword v107, v[8:9], off nt
	v_add3_u32 v9, v6, s5, 8
	v_mad_i64_i32 v[10:11], s[12:13], v9, s83, v[2:3]
	global_load_dword v108, v[10:11], off nt
	v_add3_u32 v8, v6, s5, 10
	v_mad_i64_i32 v[8:9], s[12:13], v8, s83, v[2:3]
	global_load_dword v109, v[8:9], off nt
	v_add3_u32 v9, v6, s5, 12
	v_mad_i64_i32 v[10:11], s[12:13], v9, s83, v[2:3]
	global_load_dword v110, v[10:11], off nt
	v_add3_u32 v8, v6, s5, 14
	v_mad_i64_i32 v[8:9], s[12:13], v8, s83, v[2:3]
	global_load_dword v111, v[8:9], off nt
	s_add_i32 s5, s5, 16
	v_add_u32_e32 v9, s5, v6
	v_mad_i64_i32 v[10:11], s[12:13], v9, s83, v[2:3]
	global_load_dword v112, v[10:11], off nt
	v_add3_u32 v8, v6, s5, 2
	v_mad_i64_i32 v[8:9], s[12:13], v8, s83, v[2:3]
	global_load_dword v113, v[8:9], off nt
	v_add3_u32 v9, v6, s5, 4
	v_mad_i64_i32 v[10:11], s[12:13], v9, s83, v[2:3]
	global_load_dword v114, v[10:11], off nt
	v_add3_u32 v8, v6, s5, 6
	v_mad_i64_i32 v[8:9], s[12:13], v8, s83, v[2:3]
	global_load_dword v115, v[8:9], off nt
	v_add3_u32 v9, v6, s5, 8
	v_mad_i64_i32 v[10:11], s[12:13], v9, s83, v[2:3]
	global_load_dword v116, v[10:11], off nt
	v_add3_u32 v8, v6, s5, 10
	v_mad_i64_i32 v[8:9], s[12:13], v8, s83, v[2:3]
	global_load_dword v117, v[8:9], off nt
	v_add3_u32 v9, v6, s5, 12
	v_mad_i64_i32 v[10:11], s[12:13], v9, s83, v[2:3]
	global_load_dword v118, v[10:11], off nt
	v_add3_u32 v8, v6, s5, 14
	v_mad_i64_i32 v[8:9], s[12:13], v8, s83, v[2:3]
	global_load_dword v119, v[8:9], off nt
	s_add_i32 s5, s5, 16
	v_add_u32_e32 v9, s5, v6
	v_mad_i64_i32 v[10:11], s[12:13], v9, s83, v[2:3]
	global_load_dword v120, v[10:11], off nt
	v_add3_u32 v8, v6, s5, 2
	v_mad_i64_i32 v[8:9], s[12:13], v8, s83, v[2:3]
	global_load_dword v121, v[8:9], off nt
	v_add3_u32 v9, v6, s5, 4
	v_mad_i64_i32 v[10:11], s[12:13], v9, s83, v[2:3]
	global_load_dword v122, v[10:11], off nt
	v_add3_u32 v8, v6, s5, 6
	v_mad_i64_i32 v[8:9], s[12:13], v8, s83, v[2:3]
	global_load_dword v123, v[8:9], off nt
	v_add3_u32 v9, v6, s5, 8
	v_mad_i64_i32 v[10:11], s[12:13], v9, s83, v[2:3]
	global_load_dword v124, v[10:11], off nt
	v_add3_u32 v8, v6, s5, 10
	v_mad_i64_i32 v[8:9], s[12:13], v8, s83, v[2:3]
	global_load_dword v125, v[8:9], off nt
	v_add3_u32 v9, v6, s5, 12
	v_mad_i64_i32 v[10:11], s[12:13], v9, s83, v[2:3]
	global_load_dword v126, v[10:11], off nt
	v_add3_u32 v8, v6, s5, 14
	v_mad_i64_i32 v[8:9], s[12:13], v8, s83, v[2:3]
	global_load_dword v127, v[8:9], off nt
	s_add_i32 s5, s5, 16
	v_add_u32_e32 v9, s5, v6
	v_mad_i64_i32 v[10:11], s[12:13], v9, s83, v[2:3]
	global_load_dword v128, v[10:11], off nt
	v_add3_u32 v8, v6, s5, 2
	v_mad_i64_i32 v[8:9], s[12:13], v8, s83, v[2:3]
	global_load_dword v129, v[8:9], off nt
	v_add3_u32 v9, v6, s5, 4
	v_mad_i64_i32 v[10:11], s[12:13], v9, s83, v[2:3]
	global_load_dword v130, v[10:11], off nt
	v_add3_u32 v8, v6, s5, 6
	v_mad_i64_i32 v[8:9], s[12:13], v8, s83, v[2:3]
	global_load_dword v131, v[8:9], off nt
	v_add3_u32 v9, v6, s5, 8
	v_mad_i64_i32 v[10:11], s[12:13], v9, s83, v[2:3]
	global_load_dword v132, v[10:11], off nt
	v_add3_u32 v8, v6, s5, 10
	v_mad_i64_i32 v[8:9], s[12:13], v8, s83, v[2:3]
	global_load_dword v133, v[8:9], off nt
	v_add3_u32 v9, v6, s5, 12
	v_mad_i64_i32 v[10:11], s[12:13], v9, s83, v[2:3]
	global_load_dword v134, v[10:11], off nt
	v_add3_u32 v8, v6, s5, 14
	v_mad_i64_i32 v[8:9], s[12:13], v8, s83, v[2:3]
	global_load_dword v135, v[8:9], off nt
	s_add_i32 s5, s5, 16
	s_or_b64 exec, exec, s[6:7]
	s_waitcnt vmcnt(31)
	ds_write_b32 v7, v104
	s_waitcnt vmcnt(30)
	ds_write_b32 v7, v105 offset:264
	s_waitcnt vmcnt(29)
	ds_write_b32 v7, v106 offset:528
	s_waitcnt vmcnt(28)
	ds_write_b32 v7, v107 offset:792
	s_waitcnt vmcnt(27)
	ds_write_b32 v7, v108 offset:1056
	s_waitcnt vmcnt(26)
	ds_write_b32 v7, v109 offset:1320
	s_waitcnt vmcnt(25)
	ds_write_b32 v7, v110 offset:1584
	s_waitcnt vmcnt(24)
	ds_write_b32 v7, v111 offset:1848
	s_waitcnt vmcnt(23)
	ds_write_b32 v7, v112 offset:2112
	s_waitcnt vmcnt(22)
	ds_write_b32 v7, v113 offset:2376
	s_waitcnt vmcnt(21)
	ds_write_b32 v7, v114 offset:2640
	s_waitcnt vmcnt(20)
	ds_write_b32 v7, v115 offset:2904
	s_waitcnt vmcnt(19)
	ds_write_b32 v7, v116 offset:3168
	s_waitcnt vmcnt(18)
	ds_write_b32 v7, v117 offset:3432
	s_waitcnt vmcnt(17)
	ds_write_b32 v7, v118 offset:3696
	s_waitcnt vmcnt(16)
	ds_write_b32 v7, v119 offset:3960
	s_waitcnt vmcnt(15)
	ds_write_b32 v7, v120 offset:4224
	s_waitcnt vmcnt(14)
	ds_write_b32 v7, v121 offset:4488
	s_waitcnt vmcnt(13)
	ds_write_b32 v7, v122 offset:4752
	s_waitcnt vmcnt(12)
	ds_write_b32 v7, v123 offset:5016
	s_waitcnt vmcnt(11)
	ds_write_b32 v7, v124 offset:5280
	s_waitcnt vmcnt(10)
	ds_write_b32 v7, v125 offset:5544
	s_waitcnt vmcnt(9)
	ds_write_b32 v7, v126 offset:5808
	s_waitcnt vmcnt(8)
	ds_write_b32 v7, v127 offset:6072
	s_waitcnt vmcnt(7)
	ds_write_b32 v7, v128 offset:6336
	s_waitcnt vmcnt(6)
	ds_write_b32 v7, v129 offset:6600
	s_waitcnt vmcnt(5)
	ds_write_b32 v7, v130 offset:6864
	s_waitcnt vmcnt(4)
	ds_write_b32 v7, v131 offset:7128
	s_waitcnt vmcnt(3)
	ds_write_b32 v7, v132 offset:7392
	s_waitcnt vmcnt(2)
	ds_write_b32 v7, v133 offset:7656
	s_waitcnt vmcnt(1)
	ds_write_b32 v7, v134 offset:7920
	s_waitcnt vmcnt(0)
	ds_write_b32 v7, v135 offset:8184
	s_branch .LBB0_1517

; DI void cvt_item(const float* W, int ldw, int nvalid, int srccol0, bf16_t* WT, int K, int dstrow0, int k0, LAS float* scr, int lane) {
;     const int n = srccol0 + (lane & 31);
; #pragma unroll 8
;     for (int i = 0; i < 32; ++i) { const int kk = 2 * i + (lane >> 5); scr[kk * 33 + (lane & 31)] = (n < nvalid) ? __builtin_nontemporal_load(W + (size_t)(k0 + kk) * ldw + n) : 0.f; }
;     asm volatile("s_waitcnt lgkmcnt(0)" ::: "memory");
.LBB0_1542:
	v_mov_b32_e32 v104, 0
	v_mov_b32_e32 v105, 0
	v_mov_b32_e32 v106, 0
	v_mov_b32_e32 v107, 0
	v_mov_b32_e32 v108, 0
	v_mov_b32_e32 v109, 0
	v_mov_b32_e32 v110, 0
	v_mov_b32_e32 v111, 0
	v_mov_b32_e32 v112, 0
	v_mov_b32_e32 v113, 0
	v_mov_b32_e32 v114, 0
	v_mov_b32_e32 v115, 0
	v_mov_b32_e32 v116, 0
	v_mov_b32_e32 v117, 0
	v_mov_b32_e32 v118, 0
	v_mov_b32_e32 v119, 0
	v_mov_b32_e32 v120, 0
	v_mov_b32_e32 v121, 0
	v_mov_b32_e32 v122, 0
	v_mov_b32_e32 v123, 0
	v_mov_b32_e32 v124, 0
	v_mov_b32_e32 v125, 0
	v_mov_b32_e32 v126, 0
	v_mov_b32_e32 v127, 0
	v_mov_b32_e32 v128, 0
	v_mov_b32_e32 v129, 0
	v_mov_b32_e32 v130, 0
	v_mov_b32_e32 v131, 0
	v_mov_b32_e32 v132, 0
	v_mov_b32_e32 v133, 0
	v_mov_b32_e32 v134, 0
	v_mov_b32_e32 v135, 0
	s_and_saveexec_b64 s[6:7], vcc
	v_add_u32_e32 v10, s5, v6
	v_ashrrev_i32_e32 v11, 31, v10
	v_lshlrev_b64 v[10:11], 12, v[10:11]
	v_lshl_add_u64 v[10:11], v[2:3], 0, v[10:11]
	global_load_dword v104, v[10:11], off nt
	v_add3_u32 v8, v6, s5, 2
	v_ashrrev_i32_e32 v9, 31, v8
	v_lshlrev_b64 v[8:9], 12, v[8:9]
	v_lshl_add_u64 v[8:9], v[2:3], 0, v[8:9]
	global_load_dword v105, v[8:9], off nt
	v_add3_u32 v10, v6, s5, 4
	v_ashrrev_i32_e32 v11, 31, v10
	v_lshlrev_b64 v[10:11], 12, v[10:11]
	v_lshl_add_u64 v[10:11], v[2:3], 0, v[10:11]
	global_load_dword v106, v[10:11], off nt
	v_add3_u32 v8, v6, s5, 6
	v_ashrrev_i32_e32 v9, 31, v8
	v_lshlrev_b64 v[8:9], 12, v[8:9]
	v_lshl_add_u64 v[8:9], v[2:3], 0, v[8:9]
	global_load_dword v107, v[8:9], off nt
	v_add3_u32 v10, v6, s5, 8
	v_ashrrev_i32_e32 v11, 31, v10
	v_lshlrev_b64 v[10:11], 12, v[10:11]
	v_lshl_add_u64 v[10:11], v[2:3], 0, v[10:11]
	global_load_dword v108, v[10:11], off nt
	v_add3_u32 v8, v6, s5, 10
	v_ashrrev_i32_e32 v9, 31, v8
	v_lshlrev_b64 v[8:9], 12, v[8:9]
	v_lshl_add_u64 v[8:9], v[2:3], 0, v[8:9]
	global_load_dword v109, v[8:9], off nt
	v_add3_u32 v10, v6, s5, 12
	v_ashrrev_i32_e32 v11, 31, v10
	v_lshlrev_b64 v[10:11], 12, v[10:11]
	v_lshl_add_u64 v[10:11], v[2:3], 0, v[10:11]
	global_load_dword v110, v[10:11], off nt
	v_add3_u32 v8, v6, s5, 14
	v_ashrrev_i32_e32 v9, 31, v8
	v_lshlrev_b64 v[8:9], 12, v[8:9]
	v_lshl_add_u64 v[8:9], v[2:3], 0, v[8:9]
	global_load_dword v111, v[8:9], off nt
	s_add_i32 s5, s5, 16
	v_add_u32_e32 v10, s5, v6
	v_ashrrev_i32_e32 v11, 31, v10
	v_lshlrev_b64 v[10:11], 12, v[10:11]
	v_lshl_add_u64 v[10:11], v[2:3], 0, v[10:11]
	global_load_dword v112, v[10:11], off nt
	v_add3_u32 v8, v6, s5, 2
	v_ashrrev_i32_e32 v9, 31, v8
	v_lshlrev_b64 v[8:9], 12, v[8:9]
	v_lshl_add_u64 v[8:9], v[2:3], 0, v[8:9]
	global_load_dword v113, v[8:9], off nt
	v_add3_u32 v10, v6, s5, 4
	v_ashrrev_i32_e32 v11, 31, v10
	v_lshlrev_b64 v[10:11], 12, v[10:11]
	v_lshl_add_u64 v[10:11], v[2:3], 0, v[10:11]
	global_load_dword v114, v[10:11], off nt
	v_add3_u32 v8, v6, s5, 6
	v_ashrrev_i32_e32 v9, 31, v8
	v_lshlrev_b64 v[8:9], 12, v[8:9]
	v_lshl_add_u64 v[8:9], v[2:3], 0, v[8:9]
	global_load_dword v115, v[8:9], off nt
	v_add3_u32 v10, v6, s5, 8
	v_ashrrev_i32_e32 v11, 31, v10
	v_lshlrev_b64 v[10:11], 12, v[10:11]
	v_lshl_add_u64 v[10:11], v[2:3], 0, v[10:11]
	global_load_dword v116, v[10:11], off nt
	v_add3_u32 v8, v6, s5, 10
	v_ashrrev_i32_e32 v9, 31, v8
	v_lshlrev_b64 v[8:9], 12, v[8:9]
	v_lshl_add_u64 v[8:9], v[2:3], 0, v[8:9]
	global_load_dword v117, v[8:9], off nt
	v_add3_u32 v10, v6, s5, 12
	v_ashrrev_i32_e32 v11, 31, v10
	v_lshlrev_b64 v[10:11], 12, v[10:11]
	v_lshl_add_u64 v[10:11], v[2:3], 0, v[10:11]
	global_load_dword v118, v[10:11], off nt
	v_add3_u32 v8, v6, s5, 14
	v_ashrrev_i32_e32 v9, 31, v8
	v_lshlrev_b64 v[8:9], 12, v[8:9]
	v_lshl_add_u64 v[8:9], v[2:3], 0, v[8:9]
	global_load_dword v119, v[8:9], off nt
	s_add_i32 s5, s5, 16
	v_add_u32_e32 v10, s5, v6
	v_ashrrev_i32_e32 v11, 31, v10
	v_lshlrev_b64 v[10:11], 12, v[10:11]
	v_lshl_add_u64 v[10:11], v[2:3], 0, v[10:11]
	global_load_dword v120, v[10:11], off nt
	v_add3_u32 v8, v6, s5, 2
	v_ashrrev_i32_e32 v9, 31, v8
	v_lshlrev_b64 v[8:9], 12, v[8:9]
	v_lshl_add_u64 v[8:9], v[2:3], 0, v[8:9]
	global_load_dword v121, v[8:9], off nt
	v_add3_u32 v10, v6, s5, 4
	v_ashrrev_i32_e32 v11, 31, v10
	v_lshlrev_b64 v[10:11], 12, v[10:11]
	v_lshl_add_u64 v[10:11], v[2:3], 0, v[10:11]
	global_load_dword v122, v[10:11], off nt
	v_add3_u32 v8, v6, s5, 6
	v_ashrrev_i32_e32 v9, 31, v8
	v_lshlrev_b64 v[8:9], 12, v[8:9]
	v_lshl_add_u64 v[8:9], v[2:3], 0, v[8:9]
	global_load_dword v123, v[8:9], off nt
	v_add3_u32 v10, v6, s5, 8
	v_ashrrev_i32_e32 v11, 31, v10
	v_lshlrev_b64 v[10:11], 12, v[10:11]
	v_lshl_add_u64 v[10:11], v[2:3], 0, v[10:11]
	global_load_dword v124, v[10:11], off nt
	v_add3_u32 v8, v6, s5, 10
	v_ashrrev_i32_e32 v9, 31, v8
	v_lshlrev_b64 v[8:9], 12, v[8:9]
	v_lshl_add_u64 v[8:9], v[2:3], 0, v[8:9]
	global_load_dword v125, v[8:9], off nt
	v_add3_u32 v10, v6, s5, 12
	v_ashrrev_i32_e32 v11, 31, v10
	v_lshlrev_b64 v[10:11], 12, v[10:11]
	v_lshl_add_u64 v[10:11], v[2:3], 0, v[10:11]
	global_load_dword v126, v[10:11], off nt
	v_add3_u32 v8, v6, s5, 14
	v_ashrrev_i32_e32 v9, 31, v8
	v_lshlrev_b64 v[8:9], 12, v[8:9]
	v_lshl_add_u64 v[8:9], v[2:3], 0, v[8:9]
	global_load_dword v127, v[8:9], off nt
	s_add_i32 s5, s5, 16
	v_add_u32_e32 v10, s5, v6
	v_ashrrev_i32_e32 v11, 31, v10
	v_lshlrev_b64 v[10:11], 12, v[10:11]
	v_lshl_add_u64 v[10:11], v[2:3], 0, v[10:11]
	global_load_dword v128, v[10:11], off nt
	v_add3_u32 v8, v6, s5, 2
	v_ashrrev_i32_e32 v9, 31, v8
	v_lshlrev_b64 v[8:9], 12, v[8:9]
	v_lshl_add_u64 v[8:9], v[2:3], 0, v[8:9]
	global_load_dword v129, v[8:9], off nt
	v_add3_u32 v10, v6, s5, 4
	v_ashrrev_i32_e32 v11, 31, v10
	v_lshlrev_b64 v[10:11], 12, v[10:11]
	v_lshl_add_u64 v[10:11], v[2:3], 0, v[10:11]
	global_load_dword v130, v[10:11], off nt
	v_add3_u32 v8, v6, s5, 6
	v_ashrrev_i32_e32 v9, 31, v8
	v_lshlrev_b64 v[8:9], 12, v[8:9]
	v_lshl_add_u64 v[8:9], v[2:3], 0, v[8:9]
	global_load_dword v131, v[8:9], off nt
	v_add3_u32 v10, v6, s5, 8
	v_ashrrev_i32_e32 v11, 31, v10
	v_lshlrev_b64 v[10:11], 12, v[10:11]
	v_lshl_add_u64 v[10:11], v[2:3], 0, v[10:11]
	global_load_dword v132, v[10:11], off nt
	v_add3_u32 v8, v6, s5, 10
	v_ashrrev_i32_e32 v9, 31, v8
	v_lshlrev_b64 v[8:9], 12, v[8:9]
	v_lshl_add_u64 v[8:9], v[2:3], 0, v[8:9]
	global_load_dword v133, v[8:9], off nt
	v_add3_u32 v10, v6, s5, 12
	v_ashrrev_i32_e32 v11, 31, v10
	v_lshlrev_b64 v[10:11], 12, v[10:11]
	v_lshl_add_u64 v[10:11], v[2:3], 0, v[10:11]
	global_load_dword v134, v[10:11], off nt
	v_add3_u32 v8, v6, s5, 14
	v_ashrrev_i32_e32 v9, 31, v8
	v_lshlrev_b64 v[8:9], 12, v[8:9]
	v_lshl_add_u64 v[8:9], v[2:3], 0, v[8:9]
	global_load_dword v135, v[8:9], off nt
	s_add_i32 s5, s5, 16
	s_or_b64 exec, exec, s[6:7]
	s_waitcnt vmcnt(31)
; DI void cvt_item(const float* W, int ldw, int nvalid, int srccol0, bf16_t* WT, int K, int dstrow0, int k0, LAS float* scr, int lane) {
;     const int n = srccol0 + (lane & 31);
; #pragma unroll 8
;     for (int i = 0; i < 32; ++i) { const int kk = 2 * i + (lane >> 5); scr[kk * 33 + (lane & 31)] = (n < nvalid) ? __builtin_nontemporal_load(W + (size_t)(k0 + kk) * ldw + n) : 0.f; }
;     asm volatile("s_waitcnt lgkmcnt(0)" ::: "memory");
	ds_write_b32 v7, v104
	s_waitcnt vmcnt(30)
	ds_write_b32 v7, v105 offset:264
	s_waitcnt vmcnt(29)
	ds_write_b32 v7, v106 offset:528
	s_waitcnt vmcnt(28)
	ds_write_b32 v7, v107 offset:792
	s_waitcnt vmcnt(27)
	ds_write_b32 v7, v108 offset:1056
	s_waitcnt vmcnt(26)
	ds_write_b32 v7, v109 offset:1320
	s_waitcnt vmcnt(25)
	ds_write_b32 v7, v110 offset:1584
	s_waitcnt vmcnt(24)
	ds_write_b32 v7, v111 offset:1848
	s_waitcnt vmcnt(23)
	ds_write_b32 v7, v112 offset:2112
	s_waitcnt vmcnt(22)
	ds_write_b32 v7, v113 offset:2376
	s_waitcnt vmcnt(21)
	ds_write_b32 v7, v114 offset:2640
	s_waitcnt vmcnt(20)
	ds_write_b32 v7, v115 offset:2904
	s_waitcnt vmcnt(19)
	ds_write_b32 v7, v116 offset:3168
	s_waitcnt vmcnt(18)
	ds_write_b32 v7, v117 offset:3432
	s_waitcnt vmcnt(17)
	ds_write_b32 v7, v118 offset:3696
	s_waitcnt vmcnt(16)
	ds_write_b32 v7, v119 offset:3960
	s_waitcnt vmcnt(15)
	ds_write_b32 v7, v120 offset:4224
	s_waitcnt vmcnt(14)
	ds_write_b32 v7, v121 offset:4488
	s_waitcnt vmcnt(13)
	ds_write_b32 v7, v122 offset:4752
	s_waitcnt vmcnt(12)
	ds_write_b32 v7, v123 offset:5016
	s_waitcnt vmcnt(11)
	ds_write_b32 v7, v124 offset:5280
	s_waitcnt vmcnt(10)
	ds_write_b32 v7, v125 offset:5544
	s_waitcnt vmcnt(9)
	ds_write_b32 v7, v126 offset:5808
	s_waitcnt vmcnt(8)
	ds_write_b32 v7, v127 offset:6072
	s_waitcnt vmcnt(7)
	ds_write_b32 v7, v128 offset:6336
	s_waitcnt vmcnt(6)
	ds_write_b32 v7, v129 offset:6600
	s_waitcnt vmcnt(5)
	ds_write_b32 v7, v130 offset:6864
	s_waitcnt vmcnt(4)
	ds_write_b32 v7, v131 offset:7128
	s_waitcnt vmcnt(3)
	ds_write_b32 v7, v132 offset:7392
	s_waitcnt vmcnt(2)
	ds_write_b32 v7, v133 offset:7656
	s_waitcnt vmcnt(1)
	ds_write_b32 v7, v134 offset:7920
	s_waitcnt vmcnt(0)
	ds_write_b32 v7, v135 offset:8184
	s_branch .LBB0_1539

; DI void cvt_item(const float* W, int ldw, int nvalid, int srccol0, bf16_t* WT, int K, int dstrow0, int k0, LAS float* scr, int lane) {
;     const int n = srccol0 + (lane & 31);
; #pragma unroll 8
;     for (int i = 0; i < 32; ++i) { const int kk = 2 * i + (lane >> 5); scr[kk * 33 + (lane & 31)] = (n < nvalid) ? __builtin_nontemporal_load(W + (size_t)(k0 + kk) * ldw + n) : 0.f; }
;     asm volatile("s_waitcnt lgkmcnt(0)" ::: "memory");
.LBB0_1566:
	v_mov_b32_e32 v104, 0
	v_mov_b32_e32 v105, 0
	v_mov_b32_e32 v106, 0
	v_mov_b32_e32 v107, 0
	v_mov_b32_e32 v108, 0
	v_mov_b32_e32 v109, 0
	v_mov_b32_e32 v110, 0
	v_mov_b32_e32 v111, 0
	v_mov_b32_e32 v112, 0
	v_mov_b32_e32 v113, 0
	v_mov_b32_e32 v114, 0
	v_mov_b32_e32 v115, 0
	v_mov_b32_e32 v116, 0
	v_mov_b32_e32 v117, 0
	v_mov_b32_e32 v118, 0
	v_mov_b32_e32 v119, 0
	v_mov_b32_e32 v120, 0
	v_mov_b32_e32 v121, 0
	v_mov_b32_e32 v122, 0
	v_mov_b32_e32 v123, 0
	v_mov_b32_e32 v124, 0
	v_mov_b32_e32 v125, 0
	v_mov_b32_e32 v126, 0
	v_mov_b32_e32 v127, 0
	v_mov_b32_e32 v128, 0
	v_mov_b32_e32 v129, 0
	v_mov_b32_e32 v130, 0
	v_mov_b32_e32 v131, 0
	v_mov_b32_e32 v132, 0
	v_mov_b32_e32 v133, 0
	v_mov_b32_e32 v134, 0
	v_mov_b32_e32 v135, 0
	s_and_saveexec_b64 s[12:13], vcc
	v_add_u32_e32 v12, s11, v8
	v_ashrrev_i32_e32 v13, 31, v12
	v_lshlrev_b64 v[12:13], 10, v[12:13]
	v_lshl_add_u64 v[12:13], v[4:5], 0, v[12:13]
	global_load_dword v104, v[12:13], off nt
	v_add3_u32 v10, v8, s11, 2
	v_ashrrev_i32_e32 v11, 31, v10
	v_lshlrev_b64 v[10:11], 10, v[10:11]
	v_lshl_add_u64 v[10:11], v[4:5], 0, v[10:11]
	global_load_dword v105, v[10:11], off nt
	v_add3_u32 v12, v8, s11, 4
	v_ashrrev_i32_e32 v13, 31, v12
	v_lshlrev_b64 v[12:13], 10, v[12:13]
	v_lshl_add_u64 v[12:13], v[4:5], 0, v[12:13]
	global_load_dword v106, v[12:13], off nt
	v_add3_u32 v10, v8, s11, 6
	v_ashrrev_i32_e32 v11, 31, v10
	v_lshlrev_b64 v[10:11], 10, v[10:11]
	v_lshl_add_u64 v[10:11], v[4:5], 0, v[10:11]
	global_load_dword v107, v[10:11], off nt
	v_add3_u32 v12, v8, s11, 8
	v_ashrrev_i32_e32 v13, 31, v12
	v_lshlrev_b64 v[12:13], 10, v[12:13]
	v_lshl_add_u64 v[12:13], v[4:5], 0, v[12:13]
	global_load_dword v108, v[12:13], off nt
	v_add3_u32 v10, v8, s11, 10
	v_ashrrev_i32_e32 v11, 31, v10
	v_lshlrev_b64 v[10:11], 10, v[10:11]
	v_lshl_add_u64 v[10:11], v[4:5], 0, v[10:11]
	global_load_dword v109, v[10:11], off nt
	v_add3_u32 v12, v8, s11, 12
	v_ashrrev_i32_e32 v13, 31, v12
	v_lshlrev_b64 v[12:13], 10, v[12:13]
	v_lshl_add_u64 v[12:13], v[4:5], 0, v[12:13]
	global_load_dword v110, v[12:13], off nt
	v_add3_u32 v10, v8, s11, 14
	v_ashrrev_i32_e32 v11, 31, v10
	v_lshlrev_b64 v[10:11], 10, v[10:11]
	v_lshl_add_u64 v[10:11], v[4:5], 0, v[10:11]
	global_load_dword v111, v[10:11], off nt
	s_add_i32 s11, s11, 16
	v_add_u32_e32 v12, s11, v8
	v_ashrrev_i32_e32 v13, 31, v12
	v_lshlrev_b64 v[12:13], 10, v[12:13]
	v_lshl_add_u64 v[12:13], v[4:5], 0, v[12:13]
	global_load_dword v112, v[12:13], off nt
	v_add3_u32 v10, v8, s11, 2
	v_ashrrev_i32_e32 v11, 31, v10
	v_lshlrev_b64 v[10:11], 10, v[10:11]
	v_lshl_add_u64 v[10:11], v[4:5], 0, v[10:11]
	global_load_dword v113, v[10:11], off nt
	v_add3_u32 v12, v8, s11, 4
	v_ashrrev_i32_e32 v13, 31, v12
	v_lshlrev_b64 v[12:13], 10, v[12:13]
	v_lshl_add_u64 v[12:13], v[4:5], 0, v[12:13]
	global_load_dword v114, v[12:13], off nt
	v_add3_u32 v10, v8, s11, 6
	v_ashrrev_i32_e32 v11, 31, v10
	v_lshlrev_b64 v[10:11], 10, v[10:11]
	v_lshl_add_u64 v[10:11], v[4:5], 0, v[10:11]
	global_load_dword v115, v[10:11], off nt
	v_add3_u32 v12, v8, s11, 8
	v_ashrrev_i32_e32 v13, 31, v12
	v_lshlrev_b64 v[12:13], 10, v[12:13]
	v_lshl_add_u64 v[12:13], v[4:5], 0, v[12:13]
	global_load_dword v116, v[12:13], off nt
	v_add3_u32 v10, v8, s11, 10
	v_ashrrev_i32_e32 v11, 31, v10
	v_lshlrev_b64 v[10:11], 10, v[10:11]
	v_lshl_add_u64 v[10:11], v[4:5], 0, v[10:11]
	global_load_dword v117, v[10:11], off nt
	v_add3_u32 v12, v8, s11, 12
	v_ashrrev_i32_e32 v13, 31, v12
	v_lshlrev_b64 v[12:13], 10, v[12:13]
	v_lshl_add_u64 v[12:13], v[4:5], 0, v[12:13]
	global_load_dword v118, v[12:13], off nt
	v_add3_u32 v10, v8, s11, 14
	v_ashrrev_i32_e32 v11, 31, v10
	v_lshlrev_b64 v[10:11], 10, v[10:11]
	v_lshl_add_u64 v[10:11], v[4:5], 0, v[10:11]
	global_load_dword v119, v[10:11], off nt
	s_add_i32 s11, s11, 16
	v_add_u32_e32 v12, s11, v8
	v_ashrrev_i32_e32 v13, 31, v12
	v_lshlrev_b64 v[12:13], 10, v[12:13]
	v_lshl_add_u64 v[12:13], v[4:5], 0, v[12:13]
	global_load_dword v120, v[12:13], off nt
	v_add3_u32 v10, v8, s11, 2
	v_ashrrev_i32_e32 v11, 31, v10
	v_lshlrev_b64 v[10:11], 10, v[10:11]
	v_lshl_add_u64 v[10:11], v[4:5], 0, v[10:11]
	global_load_dword v121, v[10:11], off nt
	v_add3_u32 v12, v8, s11, 4
	v_ashrrev_i32_e32 v13, 31, v12
	v_lshlrev_b64 v[12:13], 10, v[12:13]
	v_lshl_add_u64 v[12:13], v[4:5], 0, v[12:13]
	global_load_dword v122, v[12:13], off nt
	v_add3_u32 v10, v8, s11, 6
	v_ashrrev_i32_e32 v11, 31, v10
	v_lshlrev_b64 v[10:11], 10, v[10:11]
	v_lshl_add_u64 v[10:11], v[4:5], 0, v[10:11]
	global_load_dword v123, v[10:11], off nt
	v_add3_u32 v12, v8, s11, 8
	v_ashrrev_i32_e32 v13, 31, v12
	v_lshlrev_b64 v[12:13], 10, v[12:13]
	v_lshl_add_u64 v[12:13], v[4:5], 0, v[12:13]
	global_load_dword v124, v[12:13], off nt
	v_add3_u32 v10, v8, s11, 10
	v_ashrrev_i32_e32 v11, 31, v10
	v_lshlrev_b64 v[10:11], 10, v[10:11]
	v_lshl_add_u64 v[10:11], v[4:5], 0, v[10:11]
	global_load_dword v125, v[10:11], off nt
	v_add3_u32 v12, v8, s11, 12
	v_ashrrev_i32_e32 v13, 31, v12
	v_lshlrev_b64 v[12:13], 10, v[12:13]
	v_lshl_add_u64 v[12:13], v[4:5], 0, v[12:13]
	global_load_dword v126, v[12:13], off nt
	v_add3_u32 v10, v8, s11, 14
	v_ashrrev_i32_e32 v11, 31, v10
	v_lshlrev_b64 v[10:11], 10, v[10:11]
	v_lshl_add_u64 v[10:11], v[4:5], 0, v[10:11]
	global_load_dword v127, v[10:11], off nt
	s_add_i32 s11, s11, 16
	v_add_u32_e32 v12, s11, v8
	v_ashrrev_i32_e32 v13, 31, v12
	v_lshlrev_b64 v[12:13], 10, v[12:13]
	v_lshl_add_u64 v[12:13], v[4:5], 0, v[12:13]
	global_load_dword v128, v[12:13], off nt
	v_add3_u32 v10, v8, s11, 2
	v_ashrrev_i32_e32 v11, 31, v10
	v_lshlrev_b64 v[10:11], 10, v[10:11]
	v_lshl_add_u64 v[10:11], v[4:5], 0, v[10:11]
	global_load_dword v129, v[10:11], off nt
	v_add3_u32 v12, v8, s11, 4
	v_ashrrev_i32_e32 v13, 31, v12
	v_lshlrev_b64 v[12:13], 10, v[12:13]
	v_lshl_add_u64 v[12:13], v[4:5], 0, v[12:13]
	global_load_dword v130, v[12:13], off nt
	v_add3_u32 v10, v8, s11, 6
	v_ashrrev_i32_e32 v11, 31, v10
	v_lshlrev_b64 v[10:11], 10, v[10:11]
	v_lshl_add_u64 v[10:11], v[4:5], 0, v[10:11]
	global_load_dword v131, v[10:11], off nt
	v_add3_u32 v12, v8, s11, 8
	v_ashrrev_i32_e32 v13, 31, v12
	v_lshlrev_b64 v[12:13], 10, v[12:13]
	v_lshl_add_u64 v[12:13], v[4:5], 0, v[12:13]
	global_load_dword v132, v[12:13], off nt
	v_add3_u32 v10, v8, s11, 10
	v_ashrrev_i32_e32 v11, 31, v10
	v_lshlrev_b64 v[10:11], 10, v[10:11]
	v_lshl_add_u64 v[10:11], v[4:5], 0, v[10:11]
	global_load_dword v133, v[10:11], off nt
	v_add3_u32 v12, v8, s11, 12
	v_ashrrev_i32_e32 v13, 31, v12
	v_lshlrev_b64 v[12:13], 10, v[12:13]
	v_lshl_add_u64 v[12:13], v[4:5], 0, v[12:13]
	global_load_dword v134, v[12:13], off nt
	v_add3_u32 v10, v8, s11, 14
	v_ashrrev_i32_e32 v11, 31, v10
	v_lshlrev_b64 v[10:11], 10, v[10:11]
	v_lshl_add_u64 v[10:11], v[4:5], 0, v[10:11]
	global_load_dword v135, v[10:11], off nt
	s_add_i32 s11, s11, 16
	s_or_b64 exec, exec, s[12:13]
	s_waitcnt vmcnt(31)
; DI void cvt_item(const float* W, int ldw, int nvalid, int srccol0, bf16_t* WT, int K, int dstrow0, int k0, LAS float* scr, int lane) {
;     const int n = srccol0 + (lane & 31);
; #pragma unroll 8
;     for (int i = 0; i < 32; ++i) { const int kk = 2 * i + (lane >> 5); scr[kk * 33 + (lane & 31)] = (n < nvalid) ? __builtin_nontemporal_load(W + (size_t)(k0 + kk) * ldw + n) : 0.f; }
;     asm volatile("s_waitcnt lgkmcnt(0)" ::: "memory");
	ds_write_b32 v9, v104
	s_waitcnt vmcnt(30)
	ds_write_b32 v9, v105 offset:264
	s_waitcnt vmcnt(29)
	ds_write_b32 v9, v106 offset:528
	s_waitcnt vmcnt(28)
	ds_write_b32 v9, v107 offset:792
	s_waitcnt vmcnt(27)
	ds_write_b32 v9, v108 offset:1056
	s_waitcnt vmcnt(26)
	ds_write_b32 v9, v109 offset:1320
	s_waitcnt vmcnt(25)
	ds_write_b32 v9, v110 offset:1584
	s_waitcnt vmcnt(24)
	ds_write_b32 v9, v111 offset:1848
	s_waitcnt vmcnt(23)
	ds_write_b32 v9, v112 offset:2112
	s_waitcnt vmcnt(22)
	ds_write_b32 v9, v113 offset:2376
	s_waitcnt vmcnt(21)
	ds_write_b32 v9, v114 offset:2640
	s_waitcnt vmcnt(20)
	ds_write_b32 v9, v115 offset:2904
	s_waitcnt vmcnt(19)
	ds_write_b32 v9, v116 offset:3168
	s_waitcnt vmcnt(18)
	ds_write_b32 v9, v117 offset:3432
	s_waitcnt vmcnt(17)
	ds_write_b32 v9, v118 offset:3696
	s_waitcnt vmcnt(16)
	ds_write_b32 v9, v119 offset:3960
	s_waitcnt vmcnt(15)
	ds_write_b32 v9, v120 offset:4224
	s_waitcnt vmcnt(14)
	ds_write_b32 v9, v121 offset:4488
	s_waitcnt vmcnt(13)
	ds_write_b32 v9, v122 offset:4752
	s_waitcnt vmcnt(12)
	ds_write_b32 v9, v123 offset:5016
	s_waitcnt vmcnt(11)
	ds_write_b32 v9, v124 offset:5280
	s_waitcnt vmcnt(10)
	ds_write_b32 v9, v125 offset:5544
	s_waitcnt vmcnt(9)
	ds_write_b32 v9, v126 offset:5808
	s_waitcnt vmcnt(8)
	ds_write_b32 v9, v127 offset:6072
	s_waitcnt vmcnt(7)
	ds_write_b32 v9, v128 offset:6336
	s_waitcnt vmcnt(6)
	ds_write_b32 v9, v129 offset:6600
	s_waitcnt vmcnt(5)
	ds_write_b32 v9, v130 offset:6864
	s_waitcnt vmcnt(4)
	ds_write_b32 v9, v131 offset:7128
	s_waitcnt vmcnt(3)
	ds_write_b32 v9, v132 offset:7392
	s_waitcnt vmcnt(2)
	ds_write_b32 v9, v133 offset:7656
	s_waitcnt vmcnt(1)
	ds_write_b32 v9, v134 offset:7920
	s_waitcnt vmcnt(0)
	ds_write_b32 v9, v135 offset:8184
	s_branch .LBB0_1563
